# GEMM loops: LDS-DMA loads use saddr form (SGPR base + 32-bit VGPR offset), 64-bit VALU address adds removed from load segments
# speedup vs baseline: 1.0544x; 1.0544x over previous
.LBB0_171:
	ds_read_b128 v[152:155], v135
	ds_read_b128 v[156:159], v135 offset:1024
	ds_read_b128 v[160:163], v135 offset:2048
	ds_read_b128 v[164:167], v135 offset:3072
	ds_read_b128 v[168:171], v141
	ds_read_b128 v[172:175], v141 offset:1024
	ds_read_b128 v[176:179], v141 offset:2048
	ds_read_b128 v[180:183], v141 offset:3072
	s_add_u32 s20, s16, s18
	s_addc_u32 s21, s17, s19
	s_add_u32 s20, s20, 0x8a00100
	s_addc_u32 s21, s21, 0
	s_add_u32 s59, s46, s18
	s_addc_u32 s60, s47, s19
	s_cmpk_eq_i32 s18, 0x700
	s_cselect_b32 s23, s7, s21
	s_cselect_b32 s22, s6, s20
	s_cselect_b32 s21, s5, s60
	s_cselect_b32 s20, s4, s59
	s_mov_b32 m0, s49
	v_lshl_add_u64 v[148:149], v[136:137], 0, s[18:19]
	ds_read_b128 v[184:187], v142
	ds_read_b128 v[188:191], v142 offset:1024
	ds_read_b128 v[192:195], v142 offset:2048
	ds_read_b128 v[196:199], v142 offset:3072
	ds_read_b128 v[200:203], v142 offset:4096
	ds_read_b128 v[204:207], v142 offset:5120
	ds_read_b128 v[208:211], v142 offset:6144
	ds_read_b128 v[216:219], v142 offset:7168
	global_load_lds_dwordx4 v[148:149], off
	v_lshl_add_u64 v[148:149], v[138:139], 0, s[18:19]
	s_mov_b32 m0, s50
	s_nop 0
	global_load_lds_dwordx4 v[148:149], off
	s_waitcnt vmcnt(8)
	s_waitcnt lgkmcnt(0)
	s_barrier
	s_setprio 1
	s_waitcnt lgkmcnt(0)
	v_mfma_f32_16x16x32_bf16 v[126:129], v[152:155], v[184:187], v[126:129]
	v_mfma_f32_16x16x32_bf16 v[122:125], v[160:163], v[184:187], v[122:125]
	v_mfma_f32_16x16x32_bf16 v[110:113], v[152:155], v[192:195], v[110:113]
	v_mfma_f32_16x16x32_bf16 v[106:109], v[160:163], v[192:195], v[106:109]
	v_mfma_f32_16x16x32_bf16 v[94:97], v[152:155], v[200:203], v[94:97]
	v_mfma_f32_16x16x32_bf16 v[90:93], v[160:163], v[200:203], v[90:93]
	v_mfma_f32_16x16x32_bf16 v[78:81], v[152:155], v[208:211], v[78:81]
	v_mfma_f32_16x16x32_bf16 v[74:77], v[160:163], v[208:211], v[74:77]
	v_mfma_f32_16x16x32_bf16 v[126:129], v[156:159], v[188:191], v[126:129]
	v_mfma_f32_16x16x32_bf16 v[122:125], v[164:167], v[188:191], v[122:125]
	v_mfma_f32_16x16x32_bf16 v[110:113], v[156:159], v[196:199], v[110:113]
	v_mfma_f32_16x16x32_bf16 v[106:109], v[164:167], v[196:199], v[106:109]
	v_mfma_f32_16x16x32_bf16 v[94:97], v[156:159], v[204:207], v[94:97]
	v_mfma_f32_16x16x32_bf16 v[90:93], v[164:167], v[204:207], v[90:93]
	v_mfma_f32_16x16x32_bf16 v[78:81], v[156:159], v[216:219], v[78:81]
	v_mfma_f32_16x16x32_bf16 v[74:77], v[164:167], v[216:219], v[74:77]
	s_setprio 0
	s_setprio 1
	v_mfma_f32_16x16x32_bf16 v[118:121], v[168:171], v[184:187], v[118:121]
	v_mfma_f32_16x16x32_bf16 v[114:117], v[176:179], v[184:187], v[114:117]
	v_mfma_f32_16x16x32_bf16 v[102:105], v[168:171], v[192:195], v[102:105]
	v_mfma_f32_16x16x32_bf16 v[98:101], v[176:179], v[192:195], v[98:101]
	v_mfma_f32_16x16x32_bf16 v[86:89], v[168:171], v[200:203], v[86:89]
	v_mfma_f32_16x16x32_bf16 v[82:85], v[176:179], v[200:203], v[82:85]
	v_mfma_f32_16x16x32_bf16 v[70:73], v[168:171], v[208:211], v[70:73]
	v_mfma_f32_16x16x32_bf16 v[66:69], v[176:179], v[208:211], v[66:69]
	v_mfma_f32_16x16x32_bf16 v[118:121], v[172:175], v[188:191], v[118:121]
	v_mfma_f32_16x16x32_bf16 v[114:117], v[180:183], v[188:191], v[114:117]
	v_mfma_f32_16x16x32_bf16 v[102:105], v[172:175], v[196:199], v[102:105]
	v_mfma_f32_16x16x32_bf16 v[98:101], v[180:183], v[196:199], v[98:101]
	v_mfma_f32_16x16x32_bf16 v[86:89], v[172:175], v[204:207], v[86:89]
	v_mfma_f32_16x16x32_bf16 v[82:85], v[180:183], v[204:207], v[82:85]
	v_mfma_f32_16x16x32_bf16 v[70:73], v[172:175], v[216:219], v[70:73]
	v_mfma_f32_16x16x32_bf16 v[66:69], v[180:183], v[216:219], v[66:69]
	s_setprio 0
	s_barrier
	s_add_u32 s98, s20, 0x80
	s_addc_u32 s99, s21, 0
	s_add_u32 s100, s22, 0x80
	s_addc_u32 s101, s23, 0
	s_mov_b32 m0, s51
	s_add_u32 s60, s20, 0x40000
	ds_read_b128 v[184:187], v142 offset:16384
	ds_read_b128 v[188:191], v142 offset:17408
	ds_read_b128 v[192:195], v142 offset:18432
	ds_read_b128 v[196:199], v142 offset:19456
	ds_read_b128 v[200:203], v142 offset:20480
	ds_read_b128 v[204:207], v142 offset:21504
	ds_read_b128 v[208:211], v142 offset:22528
	ds_read_b128 v[216:219], v142 offset:23552
	global_load_lds_dwordx4 v130, s[20:21]
	s_mov_b32 m0, s52
	s_addc_u32 s61, s21, 0
	global_load_lds_dwordx4 v132, s[20:21]
	s_mov_b32 m0, s53
	s_nop 0
	global_load_lds_dwordx4 v130, s[60:61]
	s_mov_b32 m0, s54
	s_nop 0
	global_load_lds_dwordx4 v132, s[60:61]
	s_mov_b32 m0, s26
	s_nop 0
	global_load_lds_dwordx4 v130, s[22:23]
	s_mov_b32 m0, s27
	s_nop 0
	global_load_lds_dwordx4 v132, s[22:23]
	s_waitcnt vmcnt(8)
	s_waitcnt lgkmcnt(0)
	s_barrier
	s_setprio 1
	s_waitcnt lgkmcnt(0)
	v_mfma_f32_16x16x32_bf16 v[62:65], v[152:155], v[184:187], v[62:65]
	v_mfma_f32_16x16x32_bf16 v[58:61], v[160:163], v[184:187], v[58:61]
	v_mfma_f32_16x16x32_bf16 v[46:49], v[152:155], v[192:195], v[46:49]
	v_mfma_f32_16x16x32_bf16 v[42:45], v[160:163], v[192:195], v[42:45]
	v_mfma_f32_16x16x32_bf16 v[30:33], v[152:155], v[200:203], v[30:33]
	v_mfma_f32_16x16x32_bf16 v[26:29], v[160:163], v[200:203], v[26:29]
	v_mfma_f32_16x16x32_bf16 v[14:17], v[152:155], v[208:211], v[14:17]
	v_mfma_f32_16x16x32_bf16 v[10:13], v[160:163], v[208:211], v[10:13]
	v_mfma_f32_16x16x32_bf16 v[62:65], v[156:159], v[188:191], v[62:65]
	v_mfma_f32_16x16x32_bf16 v[58:61], v[164:167], v[188:191], v[58:61]
	v_mfma_f32_16x16x32_bf16 v[46:49], v[156:159], v[196:199], v[46:49]
	v_mfma_f32_16x16x32_bf16 v[42:45], v[164:167], v[196:199], v[42:45]
	v_mfma_f32_16x16x32_bf16 v[30:33], v[156:159], v[204:207], v[30:33]
	v_mfma_f32_16x16x32_bf16 v[26:29], v[164:167], v[204:207], v[26:29]
	v_mfma_f32_16x16x32_bf16 v[14:17], v[156:159], v[216:219], v[14:17]
	v_mfma_f32_16x16x32_bf16 v[10:13], v[164:167], v[216:219], v[10:13]
	s_setprio 0
	s_setprio 1
	v_mfma_f32_16x16x32_bf16 v[54:57], v[168:171], v[184:187], v[54:57]
	v_mfma_f32_16x16x32_bf16 v[50:53], v[176:179], v[184:187], v[50:53]
	v_mfma_f32_16x16x32_bf16 v[38:41], v[168:171], v[192:195], v[38:41]
	v_mfma_f32_16x16x32_bf16 v[34:37], v[176:179], v[192:195], v[34:37]
	v_mfma_f32_16x16x32_bf16 v[22:25], v[168:171], v[200:203], v[22:25]
	v_mfma_f32_16x16x32_bf16 v[18:21], v[176:179], v[200:203], v[18:21]
	v_mfma_f32_16x16x32_bf16 v[6:9], v[168:171], v[208:211], v[6:9]
	v_mfma_f32_16x16x32_bf16 v[2:5], v[176:179], v[208:211], v[2:5]
	v_mfma_f32_16x16x32_bf16 v[54:57], v[172:175], v[188:191], v[54:57]
	v_mfma_f32_16x16x32_bf16 v[50:53], v[180:183], v[188:191], v[50:53]
	v_mfma_f32_16x16x32_bf16 v[38:41], v[172:175], v[196:199], v[38:41]
	v_mfma_f32_16x16x32_bf16 v[34:37], v[180:183], v[196:199], v[34:37]
	v_mfma_f32_16x16x32_bf16 v[22:25], v[172:175], v[204:207], v[22:25]
	v_mfma_f32_16x16x32_bf16 v[18:21], v[180:183], v[204:207], v[18:21]
	v_mfma_f32_16x16x32_bf16 v[6:9], v[172:175], v[216:219], v[6:9]
	v_mfma_f32_16x16x32_bf16 v[2:5], v[180:183], v[216:219], v[2:5]
	s_setprio 0
	s_barrier
	ds_read_b128 v[152:155], v143
	ds_read_b128 v[156:159], v143 offset:1024
	ds_read_b128 v[160:163], v143 offset:2048
	ds_read_b128 v[164:167], v143 offset:3072
	ds_read_b128 v[168:171], v144
	ds_read_b128 v[172:175], v144 offset:1024
	ds_read_b128 v[176:179], v144 offset:2048
	ds_read_b128 v[180:183], v144 offset:3072
	s_add_u32 s22, s22, 0x40000
	s_addc_u32 s23, s23, 0
	s_mov_b32 m0, s28
	ds_read_b128 v[184:187], v142 offset:32768
	ds_read_b128 v[188:191], v142 offset:33792
	ds_read_b128 v[192:195], v142 offset:34816
	ds_read_b128 v[196:199], v142 offset:35840
	ds_read_b128 v[200:203], v142 offset:36864
	ds_read_b128 v[204:207], v142 offset:37888
	ds_read_b128 v[208:211], v142 offset:38912
	ds_read_b128 v[216:219], v142 offset:39936
	global_load_lds_dwordx4 v130, s[22:23]
	s_mov_b32 m0, s29
	s_nop 0
	global_load_lds_dwordx4 v132, s[22:23]
	s_waitcnt vmcnt(8)
	s_waitcnt lgkmcnt(0)
	s_barrier
	s_setprio 1
	s_waitcnt lgkmcnt(0)
	v_mfma_f32_16x16x32_bf16 v[126:129], v[152:155], v[184:187], v[126:129]
	v_mfma_f32_16x16x32_bf16 v[122:125], v[160:163], v[184:187], v[122:125]
	v_mfma_f32_16x16x32_bf16 v[110:113], v[152:155], v[192:195], v[110:113]
	v_mfma_f32_16x16x32_bf16 v[106:109], v[160:163], v[192:195], v[106:109]
	v_mfma_f32_16x16x32_bf16 v[94:97], v[152:155], v[200:203], v[94:97]
	v_mfma_f32_16x16x32_bf16 v[90:93], v[160:163], v[200:203], v[90:93]
	v_mfma_f32_16x16x32_bf16 v[78:81], v[152:155], v[208:211], v[78:81]
	v_mfma_f32_16x16x32_bf16 v[74:77], v[160:163], v[208:211], v[74:77]
	v_mfma_f32_16x16x32_bf16 v[126:129], v[156:159], v[188:191], v[126:129]
	v_mfma_f32_16x16x32_bf16 v[122:125], v[164:167], v[188:191], v[122:125]
	v_mfma_f32_16x16x32_bf16 v[110:113], v[156:159], v[196:199], v[110:113]
	v_mfma_f32_16x16x32_bf16 v[106:109], v[164:167], v[196:199], v[106:109]
	v_mfma_f32_16x16x32_bf16 v[94:97], v[156:159], v[204:207], v[94:97]
	v_mfma_f32_16x16x32_bf16 v[90:93], v[164:167], v[204:207], v[90:93]
	v_mfma_f32_16x16x32_bf16 v[78:81], v[156:159], v[216:219], v[78:81]
	v_mfma_f32_16x16x32_bf16 v[74:77], v[164:167], v[216:219], v[74:77]
	s_setprio 0
	s_setprio 1
	v_mfma_f32_16x16x32_bf16 v[118:121], v[168:171], v[184:187], v[118:121]
	v_mfma_f32_16x16x32_bf16 v[114:117], v[176:179], v[184:187], v[114:117]
	v_mfma_f32_16x16x32_bf16 v[102:105], v[168:171], v[192:195], v[102:105]
	v_mfma_f32_16x16x32_bf16 v[98:101], v[176:179], v[192:195], v[98:101]
	v_mfma_f32_16x16x32_bf16 v[86:89], v[168:171], v[200:203], v[86:89]
	v_mfma_f32_16x16x32_bf16 v[82:85], v[176:179], v[200:203], v[82:85]
	v_mfma_f32_16x16x32_bf16 v[70:73], v[168:171], v[208:211], v[70:73]
	v_mfma_f32_16x16x32_bf16 v[66:69], v[176:179], v[208:211], v[66:69]
	v_mfma_f32_16x16x32_bf16 v[118:121], v[172:175], v[188:191], v[118:121]
	v_mfma_f32_16x16x32_bf16 v[114:117], v[180:183], v[188:191], v[114:117]
	v_mfma_f32_16x16x32_bf16 v[102:105], v[172:175], v[196:199], v[102:105]
	v_mfma_f32_16x16x32_bf16 v[98:101], v[180:183], v[196:199], v[98:101]
	v_mfma_f32_16x16x32_bf16 v[86:89], v[172:175], v[204:207], v[86:89]
	v_mfma_f32_16x16x32_bf16 v[82:85], v[180:183], v[204:207], v[82:85]
	v_mfma_f32_16x16x32_bf16 v[70:73], v[172:175], v[216:219], v[70:73]
	v_mfma_f32_16x16x32_bf16 v[66:69], v[180:183], v[216:219], v[66:69]
	s_setprio 0
	s_barrier
	s_mov_b32 m0, s55
	s_add_u32 s20, s20, 0x40080
	ds_read_b128 v[184:187], v142 offset:49152
	ds_read_b128 v[188:191], v142 offset:50176
	ds_read_b128 v[192:195], v142 offset:51200
	ds_read_b128 v[196:199], v142 offset:52224
	ds_read_b128 v[200:203], v142 offset:53248
	ds_read_b128 v[204:207], v142 offset:54272
	ds_read_b128 v[208:211], v142 offset:55296
	ds_read_b128 v[216:219], v142 offset:56320
	global_load_lds_dwordx4 v130, s[98:99]
	s_mov_b32 m0, s56
	s_addc_u32 s21, s21, 0
	global_load_lds_dwordx4 v132, s[98:99]
	s_mov_b32 m0, s57
	s_nop 0
	global_load_lds_dwordx4 v130, s[20:21]
	s_mov_b32 m0, s58
	s_nop 0
	global_load_lds_dwordx4 v132, s[20:21]
	s_mov_b32 m0, s30
	s_nop 0
	global_load_lds_dwordx4 v130, s[100:101]
	s_mov_b32 m0, s31
	s_nop 0
	global_load_lds_dwordx4 v132, s[100:101]
	s_waitcnt vmcnt(8)
	s_waitcnt lgkmcnt(0)
	s_barrier
	s_setprio 1
	s_waitcnt lgkmcnt(0)
	v_mfma_f32_16x16x32_bf16 v[62:65], v[152:155], v[184:187], v[62:65]
	v_mfma_f32_16x16x32_bf16 v[58:61], v[160:163], v[184:187], v[58:61]
	v_mfma_f32_16x16x32_bf16 v[46:49], v[152:155], v[192:195], v[46:49]
	v_mfma_f32_16x16x32_bf16 v[42:45], v[160:163], v[192:195], v[42:45]
	v_mfma_f32_16x16x32_bf16 v[30:33], v[152:155], v[200:203], v[30:33]
	v_mfma_f32_16x16x32_bf16 v[26:29], v[160:163], v[200:203], v[26:29]
	v_mfma_f32_16x16x32_bf16 v[14:17], v[152:155], v[208:211], v[14:17]
	v_mfma_f32_16x16x32_bf16 v[10:13], v[160:163], v[208:211], v[10:13]
	v_mfma_f32_16x16x32_bf16 v[62:65], v[156:159], v[188:191], v[62:65]
	v_mfma_f32_16x16x32_bf16 v[58:61], v[164:167], v[188:191], v[58:61]
	v_mfma_f32_16x16x32_bf16 v[46:49], v[156:159], v[196:199], v[46:49]
	v_mfma_f32_16x16x32_bf16 v[42:45], v[164:167], v[196:199], v[42:45]
	v_mfma_f32_16x16x32_bf16 v[30:33], v[156:159], v[204:207], v[30:33]
	v_mfma_f32_16x16x32_bf16 v[26:29], v[164:167], v[204:207], v[26:29]
	v_mfma_f32_16x16x32_bf16 v[14:17], v[156:159], v[216:219], v[14:17]
	v_mfma_f32_16x16x32_bf16 v[10:13], v[164:167], v[216:219], v[10:13]
	s_setprio 0
	s_setprio 1
	v_mfma_f32_16x16x32_bf16 v[54:57], v[168:171], v[184:187], v[54:57]
	v_mfma_f32_16x16x32_bf16 v[50:53], v[176:179], v[184:187], v[50:53]
	v_mfma_f32_16x16x32_bf16 v[38:41], v[168:171], v[192:195], v[38:41]
	v_mfma_f32_16x16x32_bf16 v[34:37], v[176:179], v[192:195], v[34:37]
	v_mfma_f32_16x16x32_bf16 v[22:25], v[168:171], v[200:203], v[22:25]
	v_mfma_f32_16x16x32_bf16 v[18:21], v[176:179], v[200:203], v[18:21]
	v_mfma_f32_16x16x32_bf16 v[6:9], v[168:171], v[208:211], v[6:9]
	v_mfma_f32_16x16x32_bf16 v[2:5], v[176:179], v[208:211], v[2:5]
	v_mfma_f32_16x16x32_bf16 v[54:57], v[172:175], v[188:191], v[54:57]
	v_mfma_f32_16x16x32_bf16 v[50:53], v[180:183], v[188:191], v[50:53]
	v_mfma_f32_16x16x32_bf16 v[38:41], v[172:175], v[196:199], v[38:41]
	v_mfma_f32_16x16x32_bf16 v[34:37], v[180:183], v[196:199], v[34:37]
	v_mfma_f32_16x16x32_bf16 v[22:25], v[172:175], v[204:207], v[22:25]
	v_mfma_f32_16x16x32_bf16 v[18:21], v[180:183], v[204:207], v[18:21]
	v_mfma_f32_16x16x32_bf16 v[6:9], v[172:175], v[216:219], v[6:9]
	v_mfma_f32_16x16x32_bf16 v[2:5], v[180:183], v[216:219], v[2:5]
	s_setprio 0
	s_barrier
	s_add_i32 s48, s48, 2
	s_add_u32 s18, s18, 0x100
	s_addc_u32 s19, s19, 0
	s_cmp_gt_u32 s48, 13
	s_cbranch_scc0 .LBB0_171
	s_cmpk_lt_u32 s3, 0x100
	s_cbranch_scc0 .LBB0_174
	s_barrier

.LBB0_231:
	ds_read_b128 v[142:145], v172
	ds_read_b128 v[146:149], v172 offset:1024
	ds_read_b128 v[150:153], v172 offset:2048
	ds_read_b128 v[154:157], v172 offset:3072
	ds_read_b128 v[158:161], v173
	ds_read_b128 v[176:179], v173 offset:1024
	ds_read_b128 v[180:183], v173 offset:2048
	ds_read_b128 v[184:187], v173 offset:3072
	s_add_u32 s46, s30, 0xfffc0080
	s_addc_u32 s47, s31, -1
	s_cmp_eq_u32 s66, 12
	s_cselect_b32 s49, s7, s47
	s_cselect_b32 s48, s25, s46
	s_cselect_b32 s47, s9, s65
	s_cselect_b32 s46, s63, s64
	s_add_i32 m0, s15, 0xc000
	ds_read_b128 v[188:191], v174
	ds_read_b128 v[192:195], v174 offset:1024
	ds_read_b128 v[196:199], v174 offset:2048
	ds_read_b128 v[200:203], v174 offset:3072
	ds_read_b128 v[204:207], v174 offset:4096
	ds_read_b128 v[208:211], v174 offset:5120
	ds_read_b128 v[216:219], v174 offset:6144
	ds_read_b128 v[220:223], v174 offset:7168
	global_load_lds_dwordx4 v136, s[30:31]
	s_add_i32 m0, s15, 0xe000
	s_nop 0
	global_load_lds_dwordx4 v138, s[30:31]
	s_waitcnt vmcnt(8)
	s_waitcnt lgkmcnt(0)
	s_barrier
	s_setprio 1
	s_waitcnt lgkmcnt(0)
	v_mfma_f32_16x16x32_bf16 v[124:127], v[142:145], v[188:191], v[124:127]
	v_mfma_f32_16x16x32_bf16 v[120:123], v[150:153], v[188:191], v[120:123]
	v_mfma_f32_16x16x32_bf16 v[108:111], v[142:145], v[196:199], v[108:111]
	v_mfma_f32_16x16x32_bf16 v[104:107], v[150:153], v[196:199], v[104:107]
	v_mfma_f32_16x16x32_bf16 v[92:95], v[142:145], v[204:207], v[92:95]
	v_mfma_f32_16x16x32_bf16 v[88:91], v[150:153], v[204:207], v[88:91]
	v_mfma_f32_16x16x32_bf16 v[76:79], v[142:145], v[216:219], v[76:79]
	v_mfma_f32_16x16x32_bf16 v[72:75], v[150:153], v[216:219], v[72:75]
	v_mfma_f32_16x16x32_bf16 v[124:127], v[146:149], v[192:195], v[124:127]
	v_mfma_f32_16x16x32_bf16 v[120:123], v[154:157], v[192:195], v[120:123]
	v_mfma_f32_16x16x32_bf16 v[108:111], v[146:149], v[200:203], v[108:111]
	v_mfma_f32_16x16x32_bf16 v[104:107], v[154:157], v[200:203], v[104:107]
	v_mfma_f32_16x16x32_bf16 v[92:95], v[146:149], v[208:211], v[92:95]
	v_mfma_f32_16x16x32_bf16 v[88:91], v[154:157], v[208:211], v[88:91]
	v_mfma_f32_16x16x32_bf16 v[76:79], v[146:149], v[220:223], v[76:79]
	v_mfma_f32_16x16x32_bf16 v[72:75], v[154:157], v[220:223], v[72:75]
	s_setprio 0
	s_setprio 1
	v_mfma_f32_16x16x32_bf16 v[116:119], v[158:161], v[188:191], v[116:119]
	v_mfma_f32_16x16x32_bf16 v[112:115], v[180:183], v[188:191], v[112:115]
	v_mfma_f32_16x16x32_bf16 v[100:103], v[158:161], v[196:199], v[100:103]
	v_mfma_f32_16x16x32_bf16 v[96:99], v[180:183], v[196:199], v[96:99]
	v_mfma_f32_16x16x32_bf16 v[84:87], v[158:161], v[204:207], v[84:87]
	v_mfma_f32_16x16x32_bf16 v[80:83], v[180:183], v[204:207], v[80:83]
	v_mfma_f32_16x16x32_bf16 v[68:71], v[158:161], v[216:219], v[68:71]
	v_mfma_f32_16x16x32_bf16 v[64:67], v[180:183], v[216:219], v[64:67]
	v_mfma_f32_16x16x32_bf16 v[116:119], v[176:179], v[192:195], v[116:119]
	v_mfma_f32_16x16x32_bf16 v[112:115], v[184:187], v[192:195], v[112:115]
	v_mfma_f32_16x16x32_bf16 v[100:103], v[176:179], v[200:203], v[100:103]
	v_mfma_f32_16x16x32_bf16 v[96:99], v[184:187], v[200:203], v[96:99]
	v_mfma_f32_16x16x32_bf16 v[84:87], v[176:179], v[208:211], v[84:87]
	v_mfma_f32_16x16x32_bf16 v[80:83], v[184:187], v[208:211], v[80:83]
	v_mfma_f32_16x16x32_bf16 v[68:71], v[176:179], v[220:223], v[68:71]
	v_mfma_f32_16x16x32_bf16 v[64:67], v[184:187], v[220:223], v[64:67]
	s_setprio 0
	s_barrier
	s_add_u32 s98, s46, 0x80
	s_addc_u32 s99, s47, 0
	s_add_u32 s100, s48, 0x80
	s_addc_u32 s101, s49, 0
	s_add_i32 s67, s12, s53
	s_mov_b32 m0, s67
	ds_read_b128 v[188:191], v174 offset:16384
	ds_read_b128 v[192:195], v174 offset:17408
	ds_read_b128 v[196:199], v174 offset:18432
	ds_read_b128 v[200:203], v174 offset:19456
	ds_read_b128 v[204:207], v174 offset:20480
	ds_read_b128 v[208:211], v174 offset:21504
	ds_read_b128 v[216:219], v174 offset:22528
	ds_read_b128 v[220:223], v174 offset:23552
	global_load_lds_dwordx4 v128, s[46:47]
	s_add_i32 m0, s67, 0x2000
	s_add_u32 s68, s46, 0x40000
	s_addc_u32 s69, s47, 0
	s_add_i32 s67, s62, s53
	global_load_lds_dwordx4 v130, s[46:47]
	s_mov_b32 m0, s67
	s_nop 0
	global_load_lds_dwordx4 v128, s[68:69]
	s_add_i32 m0, s67, 0x2000
	s_nop 0
	global_load_lds_dwordx4 v130, s[68:69]
	s_mov_b32 m0, s15
	s_nop 0
	global_load_lds_dwordx4 v128, s[48:49]
	s_mov_b32 m0, s54
	s_nop 0
	global_load_lds_dwordx4 v130, s[48:49]
	s_waitcnt vmcnt(8)
	s_waitcnt lgkmcnt(0)
	s_barrier
	s_setprio 1
	s_waitcnt lgkmcnt(0)
	v_mfma_f32_16x16x32_bf16 v[60:63], v[142:145], v[188:191], v[60:63]
	v_mfma_f32_16x16x32_bf16 v[56:59], v[150:153], v[188:191], v[56:59]
	v_mfma_f32_16x16x32_bf16 v[44:47], v[142:145], v[196:199], v[44:47]
	v_mfma_f32_16x16x32_bf16 v[40:43], v[150:153], v[196:199], v[40:43]
	v_mfma_f32_16x16x32_bf16 v[28:31], v[142:145], v[204:207], v[28:31]
	v_mfma_f32_16x16x32_bf16 v[24:27], v[150:153], v[204:207], v[24:27]
	v_mfma_f32_16x16x32_bf16 v[12:15], v[142:145], v[216:219], v[12:15]
	v_mfma_f32_16x16x32_bf16 v[8:11], v[150:153], v[216:219], v[8:11]
	v_mfma_f32_16x16x32_bf16 v[60:63], v[146:149], v[192:195], v[60:63]
	v_mfma_f32_16x16x32_bf16 v[56:59], v[154:157], v[192:195], v[56:59]
	v_mfma_f32_16x16x32_bf16 v[44:47], v[146:149], v[200:203], v[44:47]
	v_mfma_f32_16x16x32_bf16 v[40:43], v[154:157], v[200:203], v[40:43]
	v_mfma_f32_16x16x32_bf16 v[28:31], v[146:149], v[208:211], v[28:31]
	v_mfma_f32_16x16x32_bf16 v[24:27], v[154:157], v[208:211], v[24:27]
	v_mfma_f32_16x16x32_bf16 v[12:15], v[146:149], v[220:223], v[12:15]
	v_mfma_f32_16x16x32_bf16 v[8:11], v[154:157], v[220:223], v[8:11]
	s_setprio 0
	s_setprio 1
	v_mfma_f32_16x16x32_bf16 v[52:55], v[158:161], v[188:191], v[52:55]
	v_mfma_f32_16x16x32_bf16 v[48:51], v[180:183], v[188:191], v[48:51]
	v_mfma_f32_16x16x32_bf16 v[36:39], v[158:161], v[196:199], v[36:39]
	v_mfma_f32_16x16x32_bf16 v[32:35], v[180:183], v[196:199], v[32:35]
	v_mfma_f32_16x16x32_bf16 v[20:23], v[158:161], v[204:207], v[20:23]
	v_mfma_f32_16x16x32_bf16 v[16:19], v[180:183], v[204:207], v[16:19]
	v_mfma_f32_16x16x32_bf16 v[4:7], v[158:161], v[216:219], v[4:7]
	v_mfma_f32_16x16x32_bf16 v[0:3], v[180:183], v[216:219], v[0:3]
	v_mfma_f32_16x16x32_bf16 v[52:55], v[176:179], v[192:195], v[52:55]
	v_mfma_f32_16x16x32_bf16 v[48:51], v[184:187], v[192:195], v[48:51]
	v_mfma_f32_16x16x32_bf16 v[36:39], v[176:179], v[200:203], v[36:39]
	v_mfma_f32_16x16x32_bf16 v[32:35], v[184:187], v[200:203], v[32:35]
	v_mfma_f32_16x16x32_bf16 v[20:23], v[176:179], v[208:211], v[20:23]
	v_mfma_f32_16x16x32_bf16 v[16:19], v[184:187], v[208:211], v[16:19]
	v_mfma_f32_16x16x32_bf16 v[4:7], v[176:179], v[220:223], v[4:7]
	v_mfma_f32_16x16x32_bf16 v[0:3], v[184:187], v[220:223], v[0:3]
	s_setprio 0
	s_barrier
	s_add_i32 s67, 0, 0x18000
	v_add_u32_e32 v132, s67, v167
	s_add_i32 s68, 0, 0x1c000
	ds_read_b128 v[142:145], v132
	ds_read_b128 v[146:149], v132 offset:1024
	ds_read_b128 v[150:153], v132 offset:2048
	ds_read_b128 v[154:157], v132 offset:3072
	v_add_u32_e32 v132, s68, v167
	ds_read_b128 v[158:161], v132
	ds_read_b128 v[176:179], v132 offset:1024
	ds_read_b128 v[180:183], v132 offset:2048
	ds_read_b128 v[184:187], v132 offset:3072
	s_add_u32 s48, s48, 0x40000
	s_addc_u32 s49, s49, 0
	s_mov_b32 m0, s55
	ds_read_b128 v[188:191], v174 offset:32768
	ds_read_b128 v[192:195], v174 offset:33792
	ds_read_b128 v[196:199], v174 offset:34816
	ds_read_b128 v[200:203], v174 offset:35840
	ds_read_b128 v[204:207], v174 offset:36864
	ds_read_b128 v[208:211], v174 offset:37888
	ds_read_b128 v[216:219], v174 offset:38912
	ds_read_b128 v[220:223], v174 offset:39936
	global_load_lds_dwordx4 v128, s[48:49]
	s_mov_b32 m0, s56
	s_nop 0
	global_load_lds_dwordx4 v130, s[48:49]
	s_waitcnt vmcnt(8)
	s_waitcnt lgkmcnt(0)
	s_barrier
	s_setprio 1
	s_waitcnt lgkmcnt(0)
	v_mfma_f32_16x16x32_bf16 v[124:127], v[142:145], v[188:191], v[124:127]
	v_mfma_f32_16x16x32_bf16 v[120:123], v[150:153], v[188:191], v[120:123]
	v_mfma_f32_16x16x32_bf16 v[108:111], v[142:145], v[196:199], v[108:111]
	v_mfma_f32_16x16x32_bf16 v[104:107], v[150:153], v[196:199], v[104:107]
	v_mfma_f32_16x16x32_bf16 v[92:95], v[142:145], v[204:207], v[92:95]
	v_mfma_f32_16x16x32_bf16 v[88:91], v[150:153], v[204:207], v[88:91]
	v_mfma_f32_16x16x32_bf16 v[76:79], v[142:145], v[216:219], v[76:79]
	v_mfma_f32_16x16x32_bf16 v[72:75], v[150:153], v[216:219], v[72:75]
	v_mfma_f32_16x16x32_bf16 v[124:127], v[146:149], v[192:195], v[124:127]
	v_mfma_f32_16x16x32_bf16 v[120:123], v[154:157], v[192:195], v[120:123]
	v_mfma_f32_16x16x32_bf16 v[108:111], v[146:149], v[200:203], v[108:111]
	v_mfma_f32_16x16x32_bf16 v[104:107], v[154:157], v[200:203], v[104:107]
	v_mfma_f32_16x16x32_bf16 v[92:95], v[146:149], v[208:211], v[92:95]
	v_mfma_f32_16x16x32_bf16 v[88:91], v[154:157], v[208:211], v[88:91]
	v_mfma_f32_16x16x32_bf16 v[76:79], v[146:149], v[220:223], v[76:79]
	v_mfma_f32_16x16x32_bf16 v[72:75], v[154:157], v[220:223], v[72:75]
	s_setprio 0
	s_setprio 1
	v_mfma_f32_16x16x32_bf16 v[116:119], v[158:161], v[188:191], v[116:119]
	v_mfma_f32_16x16x32_bf16 v[112:115], v[180:183], v[188:191], v[112:115]
	v_mfma_f32_16x16x32_bf16 v[100:103], v[158:161], v[196:199], v[100:103]
	v_mfma_f32_16x16x32_bf16 v[96:99], v[180:183], v[196:199], v[96:99]
	v_mfma_f32_16x16x32_bf16 v[84:87], v[158:161], v[204:207], v[84:87]
	v_mfma_f32_16x16x32_bf16 v[80:83], v[180:183], v[204:207], v[80:83]
	v_mfma_f32_16x16x32_bf16 v[68:71], v[158:161], v[216:219], v[68:71]
	v_mfma_f32_16x16x32_bf16 v[64:67], v[180:183], v[216:219], v[64:67]
	v_mfma_f32_16x16x32_bf16 v[116:119], v[176:179], v[192:195], v[116:119]
	v_mfma_f32_16x16x32_bf16 v[112:115], v[184:187], v[192:195], v[112:115]
	v_mfma_f32_16x16x32_bf16 v[100:103], v[176:179], v[200:203], v[100:103]
	v_mfma_f32_16x16x32_bf16 v[96:99], v[184:187], v[200:203], v[96:99]
	v_mfma_f32_16x16x32_bf16 v[84:87], v[176:179], v[208:211], v[84:87]
	v_mfma_f32_16x16x32_bf16 v[80:83], v[184:187], v[208:211], v[80:83]
	v_mfma_f32_16x16x32_bf16 v[68:71], v[176:179], v[220:223], v[68:71]
	v_mfma_f32_16x16x32_bf16 v[64:67], v[184:187], v[220:223], v[64:67]
	s_setprio 0
	s_barrier
	s_add_i32 s48, s67, s53
	s_mov_b32 m0, s48
	ds_read_b128 v[188:191], v174 offset:49152
	ds_read_b128 v[192:195], v174 offset:50176
	ds_read_b128 v[196:199], v174 offset:51200
	ds_read_b128 v[200:203], v174 offset:52224
	ds_read_b128 v[204:207], v174 offset:53248
	ds_read_b128 v[208:211], v174 offset:54272
	ds_read_b128 v[216:219], v174 offset:55296
	ds_read_b128 v[220:223], v174 offset:56320
	global_load_lds_dwordx4 v128, s[98:99]
	s_add_i32 m0, s48, 0x2000
	s_add_u32 s46, s46, 0x40080
	s_addc_u32 s47, s47, 0
	s_add_i32 s48, s68, s53
	global_load_lds_dwordx4 v130, s[98:99]
	s_mov_b32 m0, s48
	s_nop 0
	global_load_lds_dwordx4 v128, s[46:47]
	s_add_i32 m0, s48, 0x2000
	s_nop 0
	global_load_lds_dwordx4 v130, s[46:47]
	s_mov_b32 m0, s60
	s_nop 0
	global_load_lds_dwordx4 v128, s[100:101]
	s_mov_b32 m0, s61
	s_nop 0
	global_load_lds_dwordx4 v130, s[100:101]
	s_waitcnt vmcnt(8)
	s_waitcnt lgkmcnt(0)
	s_barrier
	s_setprio 1
	s_waitcnt lgkmcnt(0)
	v_mfma_f32_16x16x32_bf16 v[60:63], v[142:145], v[188:191], v[60:63]
	v_mfma_f32_16x16x32_bf16 v[56:59], v[150:153], v[188:191], v[56:59]
	v_mfma_f32_16x16x32_bf16 v[44:47], v[142:145], v[196:199], v[44:47]
	v_mfma_f32_16x16x32_bf16 v[40:43], v[150:153], v[196:199], v[40:43]
	v_mfma_f32_16x16x32_bf16 v[28:31], v[142:145], v[204:207], v[28:31]
	v_mfma_f32_16x16x32_bf16 v[24:27], v[150:153], v[204:207], v[24:27]
	v_mfma_f32_16x16x32_bf16 v[12:15], v[142:145], v[216:219], v[12:15]
	v_mfma_f32_16x16x32_bf16 v[8:11], v[150:153], v[216:219], v[8:11]
	v_mfma_f32_16x16x32_bf16 v[60:63], v[146:149], v[192:195], v[60:63]
	v_mfma_f32_16x16x32_bf16 v[56:59], v[154:157], v[192:195], v[56:59]
	v_mfma_f32_16x16x32_bf16 v[44:47], v[146:149], v[200:203], v[44:47]
	v_mfma_f32_16x16x32_bf16 v[40:43], v[154:157], v[200:203], v[40:43]
	v_mfma_f32_16x16x32_bf16 v[28:31], v[146:149], v[208:211], v[28:31]
	v_mfma_f32_16x16x32_bf16 v[24:27], v[154:157], v[208:211], v[24:27]
	v_mfma_f32_16x16x32_bf16 v[12:15], v[146:149], v[220:223], v[12:15]
	v_mfma_f32_16x16x32_bf16 v[8:11], v[154:157], v[220:223], v[8:11]
	s_setprio 0
	s_setprio 1
	v_mfma_f32_16x16x32_bf16 v[52:55], v[158:161], v[188:191], v[52:55]
	v_mfma_f32_16x16x32_bf16 v[48:51], v[180:183], v[188:191], v[48:51]
	v_mfma_f32_16x16x32_bf16 v[36:39], v[158:161], v[196:199], v[36:39]
	v_mfma_f32_16x16x32_bf16 v[32:35], v[180:183], v[196:199], v[32:35]
	v_mfma_f32_16x16x32_bf16 v[20:23], v[158:161], v[204:207], v[20:23]
	v_mfma_f32_16x16x32_bf16 v[16:19], v[180:183], v[204:207], v[16:19]
	v_mfma_f32_16x16x32_bf16 v[4:7], v[158:161], v[216:219], v[4:7]
	v_mfma_f32_16x16x32_bf16 v[0:3], v[180:183], v[216:219], v[0:3]
	v_mfma_f32_16x16x32_bf16 v[52:55], v[176:179], v[192:195], v[52:55]
	v_mfma_f32_16x16x32_bf16 v[48:51], v[184:187], v[192:195], v[48:51]
	v_mfma_f32_16x16x32_bf16 v[36:39], v[176:179], v[200:203], v[36:39]
	v_mfma_f32_16x16x32_bf16 v[32:35], v[184:187], v[200:203], v[32:35]
	v_mfma_f32_16x16x32_bf16 v[20:23], v[176:179], v[208:211], v[20:23]
	v_mfma_f32_16x16x32_bf16 v[16:19], v[184:187], v[208:211], v[16:19]
	v_mfma_f32_16x16x32_bf16 v[4:7], v[176:179], v[220:223], v[4:7]
	v_mfma_f32_16x16x32_bf16 v[0:3], v[184:187], v[220:223], v[0:3]
	s_setprio 0
	s_barrier
	s_add_i32 s66, s66, 2
	s_add_u32 s30, s30, 0x100
	s_addc_u32 s31, s31, 0
	s_add_u32 s64, s64, 0x100
	s_addc_u32 s65, s65, 0
	s_cmp_gt_u32 s66, 13
	s_cbranch_scc0 .LBB0_231
	s_and_b64 vcc, exec, s[22:23]
	s_cbranch_vccz .LBB0_234
	s_barrier

.LBB0_312:
	s_add_u32 s52, s94, s14
	s_addc_u32 s53, s95, s15
	s_add_u32 s52, s52, 0x14d00100
	s_addc_u32 s53, s53, 0
	s_add_u32 s58, s96, s14
	s_addc_u32 s59, s97, s15
	s_add_i32 s63, 0, 0x10000
	s_cmpk_eq_i32 s14, 0x700
	s_cselect_b32 s55, s13, s53
	s_cselect_b32 s54, s12, s52
	v_add_u32_e32 v139, s63, v131
	s_cselect_b32 s53, s11, s59
	s_cselect_b32 s52, s10, s58
	s_add_i32 s77, 0, 0x14000
	ds_read_b128 v[140:143], v139
	ds_read_b128 v[156:159], v139 offset:1024
	ds_read_b128 v[160:163], v139 offset:2048
	ds_read_b128 v[164:167], v139 offset:3072
	v_add_u32_e32 v139, s77, v131
	ds_read_b128 v[186:189], v139
	ds_read_b128 v[190:193], v139 offset:1024
	ds_read_b128 v[194:197], v139 offset:2048
	ds_read_b128 v[198:201], v139 offset:3072
	v_lshl_add_u64 v[236:237], v[132:133], 0, s[14:15]
	s_add_i32 m0, s87, 0xc000
	ds_read_b128 v[202:205], v138
	ds_read_b128 v[206:209], v138 offset:1024
	ds_read_b128 v[210:213], v138 offset:2048
	ds_read_b128 v[216:219], v138 offset:3072
	ds_read_b128 v[220:223], v138 offset:4096
	ds_read_b128 v[224:227], v138 offset:5120
	ds_read_b128 v[228:231], v138 offset:6144
	ds_read_b128 v[232:235], v138 offset:7168
	global_load_lds_dwordx4 v[236:237], off
	v_lshl_add_u64 v[236:237], v[134:135], 0, s[14:15]
	s_add_i32 m0, s87, 0xe000
	s_nop 0
	global_load_lds_dwordx4 v[236:237], off
	s_waitcnt vmcnt(8)
	s_waitcnt lgkmcnt(0)
	s_barrier
	s_setprio 1
	s_waitcnt lgkmcnt(0)
	v_mfma_f32_16x16x32_bf16 v[124:127], v[140:143], v[202:205], v[124:127]
	v_mfma_f32_16x16x32_bf16 v[120:123], v[160:163], v[202:205], v[120:123]
	v_mfma_f32_16x16x32_bf16 v[108:111], v[140:143], v[210:213], v[108:111]
	v_mfma_f32_16x16x32_bf16 v[104:107], v[160:163], v[210:213], v[104:107]
	v_mfma_f32_16x16x32_bf16 v[92:95], v[140:143], v[220:223], v[92:95]
	v_mfma_f32_16x16x32_bf16 v[88:91], v[160:163], v[220:223], v[88:91]
	v_mfma_f32_16x16x32_bf16 v[76:79], v[140:143], v[228:231], v[76:79]
	v_mfma_f32_16x16x32_bf16 v[72:75], v[160:163], v[228:231], v[72:75]
	v_mfma_f32_16x16x32_bf16 v[124:127], v[156:159], v[206:209], v[124:127]
	v_mfma_f32_16x16x32_bf16 v[120:123], v[164:167], v[206:209], v[120:123]
	v_mfma_f32_16x16x32_bf16 v[108:111], v[156:159], v[216:219], v[108:111]
	v_mfma_f32_16x16x32_bf16 v[104:107], v[164:167], v[216:219], v[104:107]
	v_mfma_f32_16x16x32_bf16 v[92:95], v[156:159], v[224:227], v[92:95]
	v_mfma_f32_16x16x32_bf16 v[88:91], v[164:167], v[224:227], v[88:91]
	v_mfma_f32_16x16x32_bf16 v[76:79], v[156:159], v[232:235], v[76:79]
	v_mfma_f32_16x16x32_bf16 v[72:75], v[164:167], v[232:235], v[72:75]
	s_setprio 0
	s_setprio 1
	v_mfma_f32_16x16x32_bf16 v[116:119], v[186:189], v[202:205], v[116:119]
	v_mfma_f32_16x16x32_bf16 v[112:115], v[194:197], v[202:205], v[112:115]
	v_mfma_f32_16x16x32_bf16 v[100:103], v[186:189], v[210:213], v[100:103]
	v_mfma_f32_16x16x32_bf16 v[96:99], v[194:197], v[210:213], v[96:99]
	v_mfma_f32_16x16x32_bf16 v[84:87], v[186:189], v[220:223], v[84:87]
	v_mfma_f32_16x16x32_bf16 v[80:83], v[194:197], v[220:223], v[80:83]
	v_mfma_f32_16x16x32_bf16 v[68:71], v[186:189], v[228:231], v[68:71]
	v_mfma_f32_16x16x32_bf16 v[64:67], v[194:197], v[228:231], v[64:67]
	v_mfma_f32_16x16x32_bf16 v[116:119], v[190:193], v[206:209], v[116:119]
	v_mfma_f32_16x16x32_bf16 v[112:115], v[198:201], v[206:209], v[112:115]
	v_mfma_f32_16x16x32_bf16 v[100:103], v[190:193], v[216:219], v[100:103]
	v_mfma_f32_16x16x32_bf16 v[96:99], v[198:201], v[216:219], v[96:99]
	v_mfma_f32_16x16x32_bf16 v[84:87], v[190:193], v[224:227], v[84:87]
	v_mfma_f32_16x16x32_bf16 v[80:83], v[198:201], v[224:227], v[80:83]
	v_mfma_f32_16x16x32_bf16 v[68:71], v[190:193], v[232:235], v[68:71]
	v_mfma_f32_16x16x32_bf16 v[64:67], v[198:201], v[232:235], v[64:67]
	s_setprio 0
	s_barrier
	s_add_u32 s98, s52, 0x80
	s_addc_u32 s99, s53, 0
	s_add_u32 s100, s54, 0x80
	s_addc_u32 s101, s55, 0
	s_add_i32 s58, s63, s86
	s_mov_b32 m0, s58
	ds_read_b128 v[202:205], v138 offset:16384
	ds_read_b128 v[206:209], v138 offset:17408
	ds_read_b128 v[210:213], v138 offset:18432
	ds_read_b128 v[216:219], v138 offset:19456
	ds_read_b128 v[220:223], v138 offset:20480
	ds_read_b128 v[224:227], v138 offset:21504
	ds_read_b128 v[228:231], v138 offset:22528
	ds_read_b128 v[232:235], v138 offset:23552
	global_load_lds_dwordx4 v148, s[52:53]
	s_add_i32 m0, s58, 0x2000
	s_add_u32 s58, s52, 0x40000
	s_addc_u32 s59, s53, 0
	s_add_i32 s63, s77, s86
	global_load_lds_dwordx4 v128, s[52:53]
	s_mov_b32 m0, s63
	s_nop 0
	global_load_lds_dwordx4 v148, s[58:59]
	s_add_i32 m0, s63, 0x2000
	s_nop 0
	global_load_lds_dwordx4 v128, s[58:59]
	s_mov_b32 m0, s87
	s_nop 0
	global_load_lds_dwordx4 v148, s[54:55]
	s_mov_b32 m0, s88
	s_nop 0
	global_load_lds_dwordx4 v128, s[54:55]
	s_waitcnt vmcnt(8)
	s_waitcnt lgkmcnt(0)
	s_barrier
	s_setprio 1
	s_waitcnt lgkmcnt(0)
	v_mfma_f32_16x16x32_bf16 v[60:63], v[140:143], v[202:205], v[60:63]
	v_mfma_f32_16x16x32_bf16 v[56:59], v[160:163], v[202:205], v[56:59]
	v_mfma_f32_16x16x32_bf16 v[44:47], v[140:143], v[210:213], v[44:47]
	v_mfma_f32_16x16x32_bf16 v[40:43], v[160:163], v[210:213], v[40:43]
	v_mfma_f32_16x16x32_bf16 v[28:31], v[140:143], v[220:223], v[28:31]
	v_mfma_f32_16x16x32_bf16 v[24:27], v[160:163], v[220:223], v[24:27]
	v_mfma_f32_16x16x32_bf16 v[12:15], v[140:143], v[228:231], v[12:15]
	v_mfma_f32_16x16x32_bf16 v[8:11], v[160:163], v[228:231], v[8:11]
	v_mfma_f32_16x16x32_bf16 v[60:63], v[156:159], v[206:209], v[60:63]
	v_mfma_f32_16x16x32_bf16 v[56:59], v[164:167], v[206:209], v[56:59]
	v_mfma_f32_16x16x32_bf16 v[44:47], v[156:159], v[216:219], v[44:47]
	v_mfma_f32_16x16x32_bf16 v[40:43], v[164:167], v[216:219], v[40:43]
	v_mfma_f32_16x16x32_bf16 v[28:31], v[156:159], v[224:227], v[28:31]
	v_mfma_f32_16x16x32_bf16 v[24:27], v[164:167], v[224:227], v[24:27]
	v_mfma_f32_16x16x32_bf16 v[12:15], v[156:159], v[232:235], v[12:15]
	v_mfma_f32_16x16x32_bf16 v[8:11], v[164:167], v[232:235], v[8:11]
	s_setprio 0
	s_setprio 1
	v_mfma_f32_16x16x32_bf16 v[52:55], v[186:189], v[202:205], v[52:55]
	v_mfma_f32_16x16x32_bf16 v[48:51], v[194:197], v[202:205], v[48:51]
	v_mfma_f32_16x16x32_bf16 v[36:39], v[186:189], v[210:213], v[36:39]
	v_mfma_f32_16x16x32_bf16 v[32:35], v[194:197], v[210:213], v[32:35]
	v_mfma_f32_16x16x32_bf16 v[20:23], v[186:189], v[220:223], v[20:23]
	v_mfma_f32_16x16x32_bf16 v[16:19], v[194:197], v[220:223], v[16:19]
	v_mfma_f32_16x16x32_bf16 v[4:7], v[186:189], v[228:231], v[4:7]
	v_mfma_f32_16x16x32_bf16 v[0:3], v[194:197], v[228:231], v[0:3]
	v_mfma_f32_16x16x32_bf16 v[52:55], v[190:193], v[206:209], v[52:55]
	v_mfma_f32_16x16x32_bf16 v[48:51], v[198:201], v[206:209], v[48:51]
	v_mfma_f32_16x16x32_bf16 v[36:39], v[190:193], v[216:219], v[36:39]
	v_mfma_f32_16x16x32_bf16 v[32:35], v[198:201], v[216:219], v[32:35]
	v_mfma_f32_16x16x32_bf16 v[20:23], v[190:193], v[224:227], v[20:23]
	v_mfma_f32_16x16x32_bf16 v[16:19], v[198:201], v[224:227], v[16:19]
	v_mfma_f32_16x16x32_bf16 v[4:7], v[190:193], v[232:235], v[4:7]
	v_mfma_f32_16x16x32_bf16 v[0:3], v[198:201], v[232:235], v[0:3]
	s_setprio 0
	s_barrier
	s_add_i32 s58, 0, 0x18000
	v_add_u32_e32 v139, s58, v131
	s_add_i32 s59, 0, 0x1c000
	ds_read_b128 v[140:143], v139
	ds_read_b128 v[156:159], v139 offset:1024
	ds_read_b128 v[160:163], v139 offset:2048
	ds_read_b128 v[164:167], v139 offset:3072
	v_add_u32_e32 v139, s59, v131
	ds_read_b128 v[186:189], v139
	ds_read_b128 v[190:193], v139 offset:1024
	ds_read_b128 v[194:197], v139 offset:2048
	ds_read_b128 v[198:201], v139 offset:3072
	s_add_u32 s54, s54, 0x40000
	s_addc_u32 s55, s55, 0
	s_mov_b32 m0, s89
	ds_read_b128 v[202:205], v138 offset:32768
	ds_read_b128 v[206:209], v138 offset:33792
	ds_read_b128 v[210:213], v138 offset:34816
	ds_read_b128 v[216:219], v138 offset:35840
	ds_read_b128 v[220:223], v138 offset:36864
	ds_read_b128 v[224:227], v138 offset:37888
	ds_read_b128 v[228:231], v138 offset:38912
	ds_read_b128 v[232:235], v138 offset:39936
	global_load_lds_dwordx4 v148, s[54:55]
	s_mov_b32 m0, s90
	s_nop 0
	global_load_lds_dwordx4 v128, s[54:55]
	s_waitcnt vmcnt(8)
	s_waitcnt lgkmcnt(0)
	s_barrier
	s_setprio 1
	s_waitcnt lgkmcnt(0)
	v_mfma_f32_16x16x32_bf16 v[124:127], v[140:143], v[202:205], v[124:127]
	v_mfma_f32_16x16x32_bf16 v[120:123], v[160:163], v[202:205], v[120:123]
	v_mfma_f32_16x16x32_bf16 v[108:111], v[140:143], v[210:213], v[108:111]
	v_mfma_f32_16x16x32_bf16 v[104:107], v[160:163], v[210:213], v[104:107]
	v_mfma_f32_16x16x32_bf16 v[92:95], v[140:143], v[220:223], v[92:95]
	v_mfma_f32_16x16x32_bf16 v[88:91], v[160:163], v[220:223], v[88:91]
	v_mfma_f32_16x16x32_bf16 v[76:79], v[140:143], v[228:231], v[76:79]
	v_mfma_f32_16x16x32_bf16 v[72:75], v[160:163], v[228:231], v[72:75]
	v_mfma_f32_16x16x32_bf16 v[124:127], v[156:159], v[206:209], v[124:127]
	v_mfma_f32_16x16x32_bf16 v[120:123], v[164:167], v[206:209], v[120:123]
	v_mfma_f32_16x16x32_bf16 v[108:111], v[156:159], v[216:219], v[108:111]
	v_mfma_f32_16x16x32_bf16 v[104:107], v[164:167], v[216:219], v[104:107]
	v_mfma_f32_16x16x32_bf16 v[92:95], v[156:159], v[224:227], v[92:95]
	v_mfma_f32_16x16x32_bf16 v[88:91], v[164:167], v[224:227], v[88:91]
	v_mfma_f32_16x16x32_bf16 v[76:79], v[156:159], v[232:235], v[76:79]
	v_mfma_f32_16x16x32_bf16 v[72:75], v[164:167], v[232:235], v[72:75]
	s_setprio 0
	s_setprio 1
	v_mfma_f32_16x16x32_bf16 v[116:119], v[186:189], v[202:205], v[116:119]
	v_mfma_f32_16x16x32_bf16 v[112:115], v[194:197], v[202:205], v[112:115]
	v_mfma_f32_16x16x32_bf16 v[100:103], v[186:189], v[210:213], v[100:103]
	v_mfma_f32_16x16x32_bf16 v[96:99], v[194:197], v[210:213], v[96:99]
	v_mfma_f32_16x16x32_bf16 v[84:87], v[186:189], v[220:223], v[84:87]
	v_mfma_f32_16x16x32_bf16 v[80:83], v[194:197], v[220:223], v[80:83]
	v_mfma_f32_16x16x32_bf16 v[68:71], v[186:189], v[228:231], v[68:71]
	v_mfma_f32_16x16x32_bf16 v[64:67], v[194:197], v[228:231], v[64:67]
	v_mfma_f32_16x16x32_bf16 v[116:119], v[190:193], v[206:209], v[116:119]
	v_mfma_f32_16x16x32_bf16 v[112:115], v[198:201], v[206:209], v[112:115]
	v_mfma_f32_16x16x32_bf16 v[100:103], v[190:193], v[216:219], v[100:103]
	v_mfma_f32_16x16x32_bf16 v[96:99], v[198:201], v[216:219], v[96:99]
	v_mfma_f32_16x16x32_bf16 v[84:87], v[190:193], v[224:227], v[84:87]
	v_mfma_f32_16x16x32_bf16 v[80:83], v[198:201], v[224:227], v[80:83]
	v_mfma_f32_16x16x32_bf16 v[68:71], v[190:193], v[232:235], v[68:71]
	v_mfma_f32_16x16x32_bf16 v[64:67], v[198:201], v[232:235], v[64:67]
	s_setprio 0
	s_barrier
	s_add_i32 s54, s58, s86
	s_mov_b32 m0, s54
	ds_read_b128 v[202:205], v138 offset:49152
	ds_read_b128 v[206:209], v138 offset:50176
	ds_read_b128 v[210:213], v138 offset:51200
	ds_read_b128 v[216:219], v138 offset:52224
	ds_read_b128 v[220:223], v138 offset:53248
	ds_read_b128 v[224:227], v138 offset:54272
	ds_read_b128 v[228:231], v138 offset:55296
	ds_read_b128 v[232:235], v138 offset:56320
	global_load_lds_dwordx4 v148, s[98:99]
	s_add_i32 m0, s54, 0x2000
	s_add_u32 s52, s52, 0x40080
	s_addc_u32 s53, s53, 0
	s_add_i32 s54, s59, s86
	global_load_lds_dwordx4 v128, s[98:99]
	s_mov_b32 m0, s54
	s_nop 0
	global_load_lds_dwordx4 v148, s[52:53]
	s_add_i32 m0, s54, 0x2000
	s_nop 0
	global_load_lds_dwordx4 v128, s[52:53]
	s_mov_b32 m0, s92
	s_nop 0
	global_load_lds_dwordx4 v148, s[100:101]
	s_mov_b32 m0, s93
	s_nop 0
	global_load_lds_dwordx4 v128, s[100:101]
	s_waitcnt vmcnt(8)
	s_waitcnt lgkmcnt(0)
	s_barrier
	s_setprio 1
	s_waitcnt lgkmcnt(0)
	v_mfma_f32_16x16x32_bf16 v[60:63], v[140:143], v[202:205], v[60:63]
	v_mfma_f32_16x16x32_bf16 v[56:59], v[160:163], v[202:205], v[56:59]
	v_mfma_f32_16x16x32_bf16 v[44:47], v[140:143], v[210:213], v[44:47]
	v_mfma_f32_16x16x32_bf16 v[40:43], v[160:163], v[210:213], v[40:43]
	v_mfma_f32_16x16x32_bf16 v[28:31], v[140:143], v[220:223], v[28:31]
	v_mfma_f32_16x16x32_bf16 v[24:27], v[160:163], v[220:223], v[24:27]
	v_mfma_f32_16x16x32_bf16 v[12:15], v[140:143], v[228:231], v[12:15]
	v_mfma_f32_16x16x32_bf16 v[8:11], v[160:163], v[228:231], v[8:11]
	v_mfma_f32_16x16x32_bf16 v[60:63], v[156:159], v[206:209], v[60:63]
	v_mfma_f32_16x16x32_bf16 v[56:59], v[164:167], v[206:209], v[56:59]
	v_mfma_f32_16x16x32_bf16 v[44:47], v[156:159], v[216:219], v[44:47]
	v_mfma_f32_16x16x32_bf16 v[40:43], v[164:167], v[216:219], v[40:43]
	v_mfma_f32_16x16x32_bf16 v[28:31], v[156:159], v[224:227], v[28:31]
	v_mfma_f32_16x16x32_bf16 v[24:27], v[164:167], v[224:227], v[24:27]
	v_mfma_f32_16x16x32_bf16 v[12:15], v[156:159], v[232:235], v[12:15]
	v_mfma_f32_16x16x32_bf16 v[8:11], v[164:167], v[232:235], v[8:11]
	s_setprio 0
	s_setprio 1
	v_mfma_f32_16x16x32_bf16 v[52:55], v[186:189], v[202:205], v[52:55]
	v_mfma_f32_16x16x32_bf16 v[48:51], v[194:197], v[202:205], v[48:51]
	v_mfma_f32_16x16x32_bf16 v[36:39], v[186:189], v[210:213], v[36:39]
	v_mfma_f32_16x16x32_bf16 v[32:35], v[194:197], v[210:213], v[32:35]
	v_mfma_f32_16x16x32_bf16 v[20:23], v[186:189], v[220:223], v[20:23]
	v_mfma_f32_16x16x32_bf16 v[16:19], v[194:197], v[220:223], v[16:19]
	v_mfma_f32_16x16x32_bf16 v[4:7], v[186:189], v[228:231], v[4:7]
	v_mfma_f32_16x16x32_bf16 v[0:3], v[194:197], v[228:231], v[0:3]
	v_mfma_f32_16x16x32_bf16 v[52:55], v[190:193], v[206:209], v[52:55]
	v_mfma_f32_16x16x32_bf16 v[48:51], v[198:201], v[206:209], v[48:51]
	v_mfma_f32_16x16x32_bf16 v[36:39], v[190:193], v[216:219], v[36:39]
	v_mfma_f32_16x16x32_bf16 v[32:35], v[198:201], v[216:219], v[32:35]
	v_mfma_f32_16x16x32_bf16 v[20:23], v[190:193], v[224:227], v[20:23]
	v_mfma_f32_16x16x32_bf16 v[16:19], v[198:201], v[224:227], v[16:19]
	v_mfma_f32_16x16x32_bf16 v[4:7], v[190:193], v[232:235], v[4:7]
	v_mfma_f32_16x16x32_bf16 v[0:3], v[198:201], v[232:235], v[0:3]
	s_setprio 0
	s_barrier
	s_add_i32 s72, s72, 2
	s_add_u32 s14, s14, 0x100
	s_addc_u32 s15, s15, 0
	s_cmp_gt_u32 s72, 13
	s_cbranch_scc0 .LBB0_312
	s_cmpk_lt_u32 s83, 0x100
	s_cbranch_scc0 .LBB0_315
	s_barrier

.LBB0_365:
	s_add_u32 s54, s96, s52
	s_addc_u32 s55, s97, s53
	s_add_u32 s54, s54, 0x2f400100
	s_addc_u32 s55, s55, 0
	s_add_u32 s58, vcc_lo, s52
	s_addc_u32 s59, vcc_hi, s53
	s_add_i32 s77, 0, 0x10000
	s_cmpk_eq_i32 s52, 0x700
	s_cselect_b32 s57, s15, s55
	s_cselect_b32 s56, s14, s54
	v_add_u32_e32 v141, s77, v139
	s_cselect_b32 s55, s11, s59
	s_cselect_b32 s54, s10, s58
	s_add_i32 s63, 0, 0x14000
	ds_read_b128 v[156:159], v141
	ds_read_b128 v[160:163], v141 offset:1024
	ds_read_b128 v[164:167], v141 offset:2048
	ds_read_b128 v[188:191], v141 offset:3072
	v_add_u32_e32 v141, s63, v139
	ds_read_b128 v[192:195], v141
	ds_read_b128 v[196:199], v141 offset:1024
	ds_read_b128 v[200:203], v141 offset:2048
	ds_read_b128 v[204:207], v141 offset:3072
	v_lshl_add_u64 v[142:143], v[134:135], 0, s[52:53]
	s_add_i32 m0, s90, 0xc000
	ds_read_b128 v[208:211], v140
	ds_read_b128 v[216:219], v140 offset:1024
	ds_read_b128 v[220:223], v140 offset:2048
	ds_read_b128 v[224:227], v140 offset:3072
	ds_read_b128 v[228:231], v140 offset:4096
	ds_read_b128 v[232:235], v140 offset:5120
	ds_read_b128 v[236:239], v140 offset:6144
	ds_read_b128 v[240:243], v140 offset:7168
	global_load_lds_dwordx4 v[142:143], off
	v_lshl_add_u64 v[142:143], v[136:137], 0, s[52:53]
	s_add_i32 m0, s90, 0xe000
	s_nop 0
	global_load_lds_dwordx4 v[142:143], off
	s_waitcnt vmcnt(8)
	s_waitcnt lgkmcnt(0)
	s_barrier
	s_setprio 1
	s_waitcnt lgkmcnt(0)
	v_mfma_f32_16x16x32_bf16 v[124:127], v[156:159], v[208:211], v[124:127]
	v_mfma_f32_16x16x32_bf16 v[120:123], v[164:167], v[208:211], v[120:123]
	v_mfma_f32_16x16x32_bf16 v[108:111], v[156:159], v[220:223], v[108:111]
	v_mfma_f32_16x16x32_bf16 v[104:107], v[164:167], v[220:223], v[104:107]
	v_mfma_f32_16x16x32_bf16 v[92:95], v[156:159], v[228:231], v[92:95]
	v_mfma_f32_16x16x32_bf16 v[88:91], v[164:167], v[228:231], v[88:91]
	v_mfma_f32_16x16x32_bf16 v[76:79], v[156:159], v[236:239], v[76:79]
	v_mfma_f32_16x16x32_bf16 v[72:75], v[164:167], v[236:239], v[72:75]
	v_mfma_f32_16x16x32_bf16 v[124:127], v[160:163], v[216:219], v[124:127]
	v_mfma_f32_16x16x32_bf16 v[120:123], v[188:191], v[216:219], v[120:123]
	v_mfma_f32_16x16x32_bf16 v[108:111], v[160:163], v[224:227], v[108:111]
	v_mfma_f32_16x16x32_bf16 v[104:107], v[188:191], v[224:227], v[104:107]
	v_mfma_f32_16x16x32_bf16 v[92:95], v[160:163], v[232:235], v[92:95]
	v_mfma_f32_16x16x32_bf16 v[88:91], v[188:191], v[232:235], v[88:91]
	v_mfma_f32_16x16x32_bf16 v[76:79], v[160:163], v[240:243], v[76:79]
	v_mfma_f32_16x16x32_bf16 v[72:75], v[188:191], v[240:243], v[72:75]
	s_setprio 0
	s_setprio 1
	v_mfma_f32_16x16x32_bf16 v[116:119], v[192:195], v[208:211], v[116:119]
	v_mfma_f32_16x16x32_bf16 v[112:115], v[200:203], v[208:211], v[112:115]
	v_mfma_f32_16x16x32_bf16 v[100:103], v[192:195], v[220:223], v[100:103]
	v_mfma_f32_16x16x32_bf16 v[96:99], v[200:203], v[220:223], v[96:99]
	v_mfma_f32_16x16x32_bf16 v[84:87], v[192:195], v[228:231], v[84:87]
	v_mfma_f32_16x16x32_bf16 v[80:83], v[200:203], v[228:231], v[80:83]
	v_mfma_f32_16x16x32_bf16 v[68:71], v[192:195], v[236:239], v[68:71]
	v_mfma_f32_16x16x32_bf16 v[64:67], v[200:203], v[236:239], v[64:67]
	v_mfma_f32_16x16x32_bf16 v[116:119], v[196:199], v[216:219], v[116:119]
	v_mfma_f32_16x16x32_bf16 v[112:115], v[204:207], v[216:219], v[112:115]
	v_mfma_f32_16x16x32_bf16 v[100:103], v[196:199], v[224:227], v[100:103]
	v_mfma_f32_16x16x32_bf16 v[96:99], v[204:207], v[224:227], v[96:99]
	v_mfma_f32_16x16x32_bf16 v[84:87], v[196:199], v[232:235], v[84:87]
	v_mfma_f32_16x16x32_bf16 v[80:83], v[204:207], v[232:235], v[80:83]
	v_mfma_f32_16x16x32_bf16 v[68:71], v[196:199], v[240:243], v[68:71]
	v_mfma_f32_16x16x32_bf16 v[64:67], v[204:207], v[240:243], v[64:67]
	s_setprio 0
	s_barrier
	s_add_i32 s58, s77, s89
	v_lshl_add_u64 v[142:143], s[54:55], 0, v[148:149]
	s_mov_b32 m0, s58
	ds_read_b128 v[208:211], v140 offset:16384
	ds_read_b128 v[216:219], v140 offset:17408
	ds_read_b128 v[220:223], v140 offset:18432
	ds_read_b128 v[224:227], v140 offset:19456
	ds_read_b128 v[228:231], v140 offset:20480
	ds_read_b128 v[232:235], v140 offset:21504
	ds_read_b128 v[236:239], v140 offset:22528
	ds_read_b128 v[240:243], v140 offset:23552
	global_load_lds_dwordx4 v148, s[54:55]
	s_add_i32 m0, s58, 0x2000
	s_add_u32 s58, s54, 0x40000
	v_lshl_add_u64 v[212:213], s[54:55], 0, v[132:133]
	s_addc_u32 s59, s55, 0
	s_add_i32 s63, s63, s89
	global_load_lds_dwordx4 v132, s[54:55]
	s_mov_b32 m0, s63
	v_lshl_add_u64 v[246:247], s[56:57], 0, v[130:131]
	global_load_lds_dwordx4 v148, s[58:59]
	s_add_i32 m0, s63, 0x2000
	s_nop 0
	global_load_lds_dwordx4 v132, s[58:59]
	v_lshl_add_u64 v[244:245], s[56:57], 0, v[128:129]
	s_mov_b32 m0, s90
	s_nop 0
	global_load_lds_dwordx4 v128, s[56:57]
	s_mov_b32 m0, s91
	s_nop 0
	global_load_lds_dwordx4 v130, s[56:57]
	s_waitcnt vmcnt(8)
	s_waitcnt lgkmcnt(0)
	s_barrier
	s_setprio 1
	s_waitcnt lgkmcnt(0)
	v_mfma_f32_16x16x32_bf16 v[60:63], v[156:159], v[208:211], v[60:63]
	v_mfma_f32_16x16x32_bf16 v[56:59], v[164:167], v[208:211], v[56:59]
	v_mfma_f32_16x16x32_bf16 v[44:47], v[156:159], v[220:223], v[44:47]
	v_mfma_f32_16x16x32_bf16 v[40:43], v[164:167], v[220:223], v[40:43]
	v_mfma_f32_16x16x32_bf16 v[28:31], v[156:159], v[228:231], v[28:31]
	v_mfma_f32_16x16x32_bf16 v[24:27], v[164:167], v[228:231], v[24:27]
	v_mfma_f32_16x16x32_bf16 v[12:15], v[156:159], v[236:239], v[12:15]
	v_mfma_f32_16x16x32_bf16 v[8:11], v[164:167], v[236:239], v[8:11]
	v_mfma_f32_16x16x32_bf16 v[60:63], v[160:163], v[216:219], v[60:63]
	v_mfma_f32_16x16x32_bf16 v[56:59], v[188:191], v[216:219], v[56:59]
	v_mfma_f32_16x16x32_bf16 v[44:47], v[160:163], v[224:227], v[44:47]
	v_mfma_f32_16x16x32_bf16 v[40:43], v[188:191], v[224:227], v[40:43]
	v_mfma_f32_16x16x32_bf16 v[28:31], v[160:163], v[232:235], v[28:31]
	v_mfma_f32_16x16x32_bf16 v[24:27], v[188:191], v[232:235], v[24:27]
	v_mfma_f32_16x16x32_bf16 v[12:15], v[160:163], v[240:243], v[12:15]
	v_mfma_f32_16x16x32_bf16 v[8:11], v[188:191], v[240:243], v[8:11]
	s_setprio 0
	s_setprio 1
	v_mfma_f32_16x16x32_bf16 v[52:55], v[192:195], v[208:211], v[52:55]
	v_mfma_f32_16x16x32_bf16 v[48:51], v[200:203], v[208:211], v[48:51]
	v_mfma_f32_16x16x32_bf16 v[36:39], v[192:195], v[220:223], v[36:39]
	v_mfma_f32_16x16x32_bf16 v[32:35], v[200:203], v[220:223], v[32:35]
	v_mfma_f32_16x16x32_bf16 v[20:23], v[192:195], v[228:231], v[20:23]
	v_mfma_f32_16x16x32_bf16 v[16:19], v[200:203], v[228:231], v[16:19]
	v_mfma_f32_16x16x32_bf16 v[4:7], v[192:195], v[236:239], v[4:7]
	v_mfma_f32_16x16x32_bf16 v[0:3], v[200:203], v[236:239], v[0:3]
	v_mfma_f32_16x16x32_bf16 v[52:55], v[196:199], v[216:219], v[52:55]
	v_mfma_f32_16x16x32_bf16 v[48:51], v[204:207], v[216:219], v[48:51]
	v_mfma_f32_16x16x32_bf16 v[36:39], v[196:199], v[224:227], v[36:39]
	v_mfma_f32_16x16x32_bf16 v[32:35], v[204:207], v[224:227], v[32:35]
	v_mfma_f32_16x16x32_bf16 v[20:23], v[196:199], v[232:235], v[20:23]
	v_mfma_f32_16x16x32_bf16 v[16:19], v[204:207], v[232:235], v[16:19]
	v_mfma_f32_16x16x32_bf16 v[4:7], v[196:199], v[240:243], v[4:7]
	v_mfma_f32_16x16x32_bf16 v[0:3], v[204:207], v[240:243], v[0:3]
	s_setprio 0
	s_barrier
	s_add_i32 s58, 0, 0x18000
	v_add_u32_e32 v141, s58, v139
	s_add_i32 s59, 0, 0x1c000
	ds_read_b128 v[156:159], v141
	ds_read_b128 v[160:163], v141 offset:1024
	ds_read_b128 v[164:167], v141 offset:2048
	ds_read_b128 v[188:191], v141 offset:3072
	v_add_u32_e32 v141, s59, v139
	ds_read_b128 v[192:195], v141
	ds_read_b128 v[196:199], v141 offset:1024
	ds_read_b128 v[200:203], v141 offset:2048
	ds_read_b128 v[204:207], v141 offset:3072
	s_add_u32 s56, s56, 0x40000
	s_addc_u32 s57, s57, 0
	s_mov_b32 m0, s92
	ds_read_b128 v[208:211], v140 offset:32768
	ds_read_b128 v[216:219], v140 offset:33792
	ds_read_b128 v[220:223], v140 offset:34816
	ds_read_b128 v[224:227], v140 offset:35840
	ds_read_b128 v[228:231], v140 offset:36864
	ds_read_b128 v[232:235], v140 offset:37888
	ds_read_b128 v[236:239], v140 offset:38912
	ds_read_b128 v[240:243], v140 offset:39936
	global_load_lds_dwordx4 v128, s[56:57]
	s_mov_b32 m0, s93
	s_nop 0
	global_load_lds_dwordx4 v130, s[56:57]
	s_waitcnt vmcnt(8)
	s_waitcnt lgkmcnt(0)
	s_barrier
	s_setprio 1
	s_waitcnt lgkmcnt(0)
	v_mfma_f32_16x16x32_bf16 v[124:127], v[156:159], v[208:211], v[124:127]
	v_mfma_f32_16x16x32_bf16 v[120:123], v[164:167], v[208:211], v[120:123]
	v_mfma_f32_16x16x32_bf16 v[108:111], v[156:159], v[220:223], v[108:111]
	v_mfma_f32_16x16x32_bf16 v[104:107], v[164:167], v[220:223], v[104:107]
	v_mfma_f32_16x16x32_bf16 v[92:95], v[156:159], v[228:231], v[92:95]
	v_mfma_f32_16x16x32_bf16 v[88:91], v[164:167], v[228:231], v[88:91]
	v_mfma_f32_16x16x32_bf16 v[76:79], v[156:159], v[236:239], v[76:79]
	v_mfma_f32_16x16x32_bf16 v[72:75], v[164:167], v[236:239], v[72:75]
	v_mfma_f32_16x16x32_bf16 v[124:127], v[160:163], v[216:219], v[124:127]
	v_mfma_f32_16x16x32_bf16 v[120:123], v[188:191], v[216:219], v[120:123]
	v_mfma_f32_16x16x32_bf16 v[108:111], v[160:163], v[224:227], v[108:111]
	v_mfma_f32_16x16x32_bf16 v[104:107], v[188:191], v[224:227], v[104:107]
	v_mfma_f32_16x16x32_bf16 v[92:95], v[160:163], v[232:235], v[92:95]
	v_mfma_f32_16x16x32_bf16 v[88:91], v[188:191], v[232:235], v[88:91]
	v_mfma_f32_16x16x32_bf16 v[76:79], v[160:163], v[240:243], v[76:79]
	v_mfma_f32_16x16x32_bf16 v[72:75], v[188:191], v[240:243], v[72:75]
	s_setprio 0
	s_setprio 1
	v_mfma_f32_16x16x32_bf16 v[116:119], v[192:195], v[208:211], v[116:119]
	v_mfma_f32_16x16x32_bf16 v[112:115], v[200:203], v[208:211], v[112:115]
	v_mfma_f32_16x16x32_bf16 v[100:103], v[192:195], v[220:223], v[100:103]
	v_mfma_f32_16x16x32_bf16 v[96:99], v[200:203], v[220:223], v[96:99]
	v_mfma_f32_16x16x32_bf16 v[84:87], v[192:195], v[228:231], v[84:87]
	v_mfma_f32_16x16x32_bf16 v[80:83], v[200:203], v[228:231], v[80:83]
	v_mfma_f32_16x16x32_bf16 v[68:71], v[192:195], v[236:239], v[68:71]
	v_mfma_f32_16x16x32_bf16 v[64:67], v[200:203], v[236:239], v[64:67]
	v_mfma_f32_16x16x32_bf16 v[116:119], v[196:199], v[216:219], v[116:119]
	v_mfma_f32_16x16x32_bf16 v[112:115], v[204:207], v[216:219], v[112:115]
	v_mfma_f32_16x16x32_bf16 v[100:103], v[196:199], v[224:227], v[100:103]
	v_mfma_f32_16x16x32_bf16 v[96:99], v[204:207], v[224:227], v[96:99]
	v_mfma_f32_16x16x32_bf16 v[84:87], v[196:199], v[232:235], v[84:87]
	v_mfma_f32_16x16x32_bf16 v[80:83], v[204:207], v[232:235], v[80:83]
	v_mfma_f32_16x16x32_bf16 v[68:71], v[196:199], v[240:243], v[68:71]
	v_mfma_f32_16x16x32_bf16 v[64:67], v[204:207], v[240:243], v[64:67]
	s_setprio 0
	s_barrier
	s_add_i32 s56, s58, s89
	v_lshl_add_u64 v[142:143], v[142:143], 0, s[26:27]
	s_mov_b32 m0, s56
	ds_read_b128 v[208:211], v140 offset:49152
	ds_read_b128 v[216:219], v140 offset:50176
	ds_read_b128 v[220:223], v140 offset:51200
	ds_read_b128 v[224:227], v140 offset:52224
	ds_read_b128 v[228:231], v140 offset:53248
	ds_read_b128 v[232:235], v140 offset:54272
	ds_read_b128 v[236:239], v140 offset:55296
	ds_read_b128 v[240:243], v140 offset:56320
	global_load_lds_dwordx4 v[142:143], off
	s_add_i32 m0, s56, 0x2000
	s_add_u32 s54, s54, 0x40080
	v_lshl_add_u64 v[142:143], v[212:213], 0, s[26:27]
	s_addc_u32 s55, s55, 0
	s_add_i32 s56, s59, s89
	global_load_lds_dwordx4 v[142:143], off
	s_mov_b32 m0, s56
	s_nop 0
	global_load_lds_dwordx4 v148, s[54:55]
	s_add_i32 m0, s56, 0x2000
	s_nop 0
	global_load_lds_dwordx4 v132, s[54:55]
	v_lshl_add_u64 v[142:143], v[244:245], 0, s[26:27]
	s_mov_b32 m0, s94
	s_nop 0
	global_load_lds_dwordx4 v[142:143], off
	v_lshl_add_u64 v[142:143], v[246:247], 0, s[26:27]
	s_mov_b32 m0, s95
	s_nop 0
	global_load_lds_dwordx4 v[142:143], off
	s_waitcnt vmcnt(8)
	s_waitcnt lgkmcnt(0)
	s_barrier
	s_setprio 1
	s_waitcnt lgkmcnt(0)
	v_mfma_f32_16x16x32_bf16 v[60:63], v[156:159], v[208:211], v[60:63]
	v_mfma_f32_16x16x32_bf16 v[56:59], v[164:167], v[208:211], v[56:59]
	v_mfma_f32_16x16x32_bf16 v[44:47], v[156:159], v[220:223], v[44:47]
	v_mfma_f32_16x16x32_bf16 v[40:43], v[164:167], v[220:223], v[40:43]
	v_mfma_f32_16x16x32_bf16 v[28:31], v[156:159], v[228:231], v[28:31]
	v_mfma_f32_16x16x32_bf16 v[24:27], v[164:167], v[228:231], v[24:27]
	v_mfma_f32_16x16x32_bf16 v[12:15], v[156:159], v[236:239], v[12:15]
	v_mfma_f32_16x16x32_bf16 v[8:11], v[164:167], v[236:239], v[8:11]
	v_mfma_f32_16x16x32_bf16 v[60:63], v[160:163], v[216:219], v[60:63]
	v_mfma_f32_16x16x32_bf16 v[56:59], v[188:191], v[216:219], v[56:59]
	v_mfma_f32_16x16x32_bf16 v[44:47], v[160:163], v[224:227], v[44:47]
	v_mfma_f32_16x16x32_bf16 v[40:43], v[188:191], v[224:227], v[40:43]
	v_mfma_f32_16x16x32_bf16 v[28:31], v[160:163], v[232:235], v[28:31]
	v_mfma_f32_16x16x32_bf16 v[24:27], v[188:191], v[232:235], v[24:27]
	v_mfma_f32_16x16x32_bf16 v[12:15], v[160:163], v[240:243], v[12:15]
	v_mfma_f32_16x16x32_bf16 v[8:11], v[188:191], v[240:243], v[8:11]
	s_setprio 0
	s_setprio 1
	v_mfma_f32_16x16x32_bf16 v[52:55], v[192:195], v[208:211], v[52:55]
	v_mfma_f32_16x16x32_bf16 v[48:51], v[200:203], v[208:211], v[48:51]
	v_mfma_f32_16x16x32_bf16 v[36:39], v[192:195], v[220:223], v[36:39]
	v_mfma_f32_16x16x32_bf16 v[32:35], v[200:203], v[220:223], v[32:35]
	v_mfma_f32_16x16x32_bf16 v[20:23], v[192:195], v[228:231], v[20:23]
	v_mfma_f32_16x16x32_bf16 v[16:19], v[200:203], v[228:231], v[16:19]
	v_mfma_f32_16x16x32_bf16 v[4:7], v[192:195], v[236:239], v[4:7]
	v_mfma_f32_16x16x32_bf16 v[0:3], v[200:203], v[236:239], v[0:3]
	v_mfma_f32_16x16x32_bf16 v[52:55], v[196:199], v[216:219], v[52:55]
	v_mfma_f32_16x16x32_bf16 v[48:51], v[204:207], v[216:219], v[48:51]
	v_mfma_f32_16x16x32_bf16 v[36:39], v[196:199], v[224:227], v[36:39]
	v_mfma_f32_16x16x32_bf16 v[32:35], v[204:207], v[224:227], v[32:35]
	v_mfma_f32_16x16x32_bf16 v[20:23], v[196:199], v[232:235], v[20:23]
	v_mfma_f32_16x16x32_bf16 v[16:19], v[204:207], v[232:235], v[16:19]
	v_mfma_f32_16x16x32_bf16 v[4:7], v[196:199], v[240:243], v[4:7]
	v_mfma_f32_16x16x32_bf16 v[0:3], v[204:207], v[240:243], v[0:3]
	s_setprio 0
	s_barrier
	s_add_i32 s72, s72, 2
	s_add_u32 s52, s52, 0x100
	s_addc_u32 s53, s53, 0
	s_cmp_gt_u32 s72, 13
	s_cbranch_scc0 .LBB0_365
	s_cmpk_lt_u32 s88, 0x100
	s_cbranch_scc0 .LBB0_368
	s_barrier

.LBB0_439:
	ds_read_b128 v[128:131], v181
	ds_read_b128 v[132:135], v181 offset:1024
	ds_read_b128 v[136:139], v181 offset:2048
	ds_read_b128 v[140:143], v181 offset:3072
	ds_read_b128 v[160:163], v182
	ds_read_b128 v[164:167], v182 offset:1024
	ds_read_b128 v[168:171], v182 offset:2048
	ds_read_b128 v[172:175], v182 offset:3072
	s_add_u32 s52, s30, 0xfffc0080
	s_addc_u32 s53, s31, -1
	s_cmp_eq_u32 s76, 12
	s_cselect_b32 s55, s23, s53
	s_cselect_b32 s54, s29, s52
	s_cselect_b32 s53, s21, s74
	s_cselect_b32 s52, s71, s73
	s_add_i32 m0, s59, 0xc000
	ds_read_b128 v[184:187], v183
	ds_read_b128 v[188:191], v183 offset:1024
	ds_read_b128 v[192:195], v183 offset:2048
	ds_read_b128 v[196:199], v183 offset:3072
	ds_read_b128 v[200:203], v183 offset:4096
	ds_read_b128 v[204:207], v183 offset:5120
	ds_read_b128 v[208:211], v183 offset:6144
	ds_read_b128 v[216:219], v183 offset:7168
	global_load_lds_dwordx4 v152, s[30:31]
	s_add_i32 m0, s59, 0xe000
	s_nop 0
	global_load_lds_dwordx4 v154, s[30:31]
	s_waitcnt vmcnt(8)
	s_waitcnt lgkmcnt(0)
	s_barrier
	s_setprio 1
	s_waitcnt lgkmcnt(0)
	v_mfma_f32_16x16x32_bf16 v[124:127], v[128:131], v[184:187], v[124:127]
	v_mfma_f32_16x16x32_bf16 v[120:123], v[136:139], v[184:187], v[120:123]
	v_mfma_f32_16x16x32_bf16 v[108:111], v[128:131], v[192:195], v[108:111]
	v_mfma_f32_16x16x32_bf16 v[104:107], v[136:139], v[192:195], v[104:107]
	v_mfma_f32_16x16x32_bf16 v[92:95], v[128:131], v[200:203], v[92:95]
	v_mfma_f32_16x16x32_bf16 v[88:91], v[136:139], v[200:203], v[88:91]
	v_mfma_f32_16x16x32_bf16 v[76:79], v[128:131], v[208:211], v[76:79]
	v_mfma_f32_16x16x32_bf16 v[72:75], v[136:139], v[208:211], v[72:75]
	v_mfma_f32_16x16x32_bf16 v[124:127], v[132:135], v[188:191], v[124:127]
	v_mfma_f32_16x16x32_bf16 v[120:123], v[140:143], v[188:191], v[120:123]
	v_mfma_f32_16x16x32_bf16 v[108:111], v[132:135], v[196:199], v[108:111]
	v_mfma_f32_16x16x32_bf16 v[104:107], v[140:143], v[196:199], v[104:107]
	v_mfma_f32_16x16x32_bf16 v[92:95], v[132:135], v[204:207], v[92:95]
	v_mfma_f32_16x16x32_bf16 v[88:91], v[140:143], v[204:207], v[88:91]
	v_mfma_f32_16x16x32_bf16 v[76:79], v[132:135], v[216:219], v[76:79]
	v_mfma_f32_16x16x32_bf16 v[72:75], v[140:143], v[216:219], v[72:75]
	s_setprio 0
	s_setprio 1
	v_mfma_f32_16x16x32_bf16 v[116:119], v[160:163], v[184:187], v[116:119]
	v_mfma_f32_16x16x32_bf16 v[112:115], v[168:171], v[184:187], v[112:115]
	v_mfma_f32_16x16x32_bf16 v[100:103], v[160:163], v[192:195], v[100:103]
	v_mfma_f32_16x16x32_bf16 v[96:99], v[168:171], v[192:195], v[96:99]
	v_mfma_f32_16x16x32_bf16 v[84:87], v[160:163], v[200:203], v[84:87]
	v_mfma_f32_16x16x32_bf16 v[80:83], v[168:171], v[200:203], v[80:83]
	v_mfma_f32_16x16x32_bf16 v[68:71], v[160:163], v[208:211], v[68:71]
	v_mfma_f32_16x16x32_bf16 v[64:67], v[168:171], v[208:211], v[64:67]
	v_mfma_f32_16x16x32_bf16 v[116:119], v[164:167], v[188:191], v[116:119]
	v_mfma_f32_16x16x32_bf16 v[112:115], v[172:175], v[188:191], v[112:115]
	v_mfma_f32_16x16x32_bf16 v[100:103], v[164:167], v[196:199], v[100:103]
	v_mfma_f32_16x16x32_bf16 v[96:99], v[172:175], v[196:199], v[96:99]
	v_mfma_f32_16x16x32_bf16 v[84:87], v[164:167], v[204:207], v[84:87]
	v_mfma_f32_16x16x32_bf16 v[80:83], v[172:175], v[204:207], v[80:83]
	v_mfma_f32_16x16x32_bf16 v[68:71], v[164:167], v[216:219], v[68:71]
	v_mfma_f32_16x16x32_bf16 v[64:67], v[172:175], v[216:219], v[64:67]
	s_setprio 0
	s_barrier
	s_add_u32 s98, s52, 0x80
	s_addc_u32 s99, s53, 0
	s_add_u32 s100, s54, 0x80
	s_addc_u32 s101, s55, 0
	s_add_i32 s72, s68, s58
	s_mov_b32 m0, s72
	ds_read_b128 v[184:187], v183 offset:16384
	ds_read_b128 v[188:191], v183 offset:17408
	ds_read_b128 v[192:195], v183 offset:18432
	ds_read_b128 v[196:199], v183 offset:19456
	ds_read_b128 v[200:203], v183 offset:20480
	ds_read_b128 v[204:207], v183 offset:21504
	ds_read_b128 v[208:211], v183 offset:22528
	ds_read_b128 v[216:219], v183 offset:23552
	global_load_lds_dwordx4 v146, s[52:53]
	s_add_i32 m0, s72, 0x2000
	s_add_u32 s78, s52, 0x40000
	s_addc_u32 s79, s53, 0
	s_add_i32 s72, s69, s58
	global_load_lds_dwordx4 v150, s[52:53]
	s_mov_b32 m0, s72
	s_nop 0
	global_load_lds_dwordx4 v146, s[78:79]
	s_add_i32 m0, s72, 0x2000
	s_nop 0
	global_load_lds_dwordx4 v150, s[78:79]
	s_mov_b32 m0, s59
	s_nop 0
	global_load_lds_dwordx4 v144, s[54:55]
	s_mov_b32 m0, s60
	s_nop 0
	global_load_lds_dwordx4 v148, s[54:55]
	s_waitcnt vmcnt(8)
	s_waitcnt lgkmcnt(0)
	s_barrier
	s_setprio 1
	s_waitcnt lgkmcnt(0)
	v_mfma_f32_16x16x32_bf16 v[60:63], v[128:131], v[184:187], v[60:63]
	v_mfma_f32_16x16x32_bf16 v[56:59], v[136:139], v[184:187], v[56:59]
	v_mfma_f32_16x16x32_bf16 v[44:47], v[128:131], v[192:195], v[44:47]
	v_mfma_f32_16x16x32_bf16 v[40:43], v[136:139], v[192:195], v[40:43]
	v_mfma_f32_16x16x32_bf16 v[28:31], v[128:131], v[200:203], v[28:31]
	v_mfma_f32_16x16x32_bf16 v[24:27], v[136:139], v[200:203], v[24:27]
	v_mfma_f32_16x16x32_bf16 v[12:15], v[128:131], v[208:211], v[12:15]
	v_mfma_f32_16x16x32_bf16 v[8:11], v[136:139], v[208:211], v[8:11]
	v_mfma_f32_16x16x32_bf16 v[60:63], v[132:135], v[188:191], v[60:63]
	v_mfma_f32_16x16x32_bf16 v[56:59], v[140:143], v[188:191], v[56:59]
	v_mfma_f32_16x16x32_bf16 v[44:47], v[132:135], v[196:199], v[44:47]
	v_mfma_f32_16x16x32_bf16 v[40:43], v[140:143], v[196:199], v[40:43]
	v_mfma_f32_16x16x32_bf16 v[28:31], v[132:135], v[204:207], v[28:31]
	v_mfma_f32_16x16x32_bf16 v[24:27], v[140:143], v[204:207], v[24:27]
	v_mfma_f32_16x16x32_bf16 v[12:15], v[132:135], v[216:219], v[12:15]
	v_mfma_f32_16x16x32_bf16 v[8:11], v[140:143], v[216:219], v[8:11]
	s_setprio 0
	s_setprio 1
	v_mfma_f32_16x16x32_bf16 v[52:55], v[160:163], v[184:187], v[52:55]
	v_mfma_f32_16x16x32_bf16 v[48:51], v[168:171], v[184:187], v[48:51]
	v_mfma_f32_16x16x32_bf16 v[36:39], v[160:163], v[192:195], v[36:39]
	v_mfma_f32_16x16x32_bf16 v[32:35], v[168:171], v[192:195], v[32:35]
	v_mfma_f32_16x16x32_bf16 v[20:23], v[160:163], v[200:203], v[20:23]
	v_mfma_f32_16x16x32_bf16 v[16:19], v[168:171], v[200:203], v[16:19]
	v_mfma_f32_16x16x32_bf16 v[4:7], v[160:163], v[208:211], v[4:7]
	v_mfma_f32_16x16x32_bf16 v[0:3], v[168:171], v[208:211], v[0:3]
	v_mfma_f32_16x16x32_bf16 v[52:55], v[164:167], v[188:191], v[52:55]
	v_mfma_f32_16x16x32_bf16 v[48:51], v[172:175], v[188:191], v[48:51]
	v_mfma_f32_16x16x32_bf16 v[36:39], v[164:167], v[196:199], v[36:39]
	v_mfma_f32_16x16x32_bf16 v[32:35], v[172:175], v[196:199], v[32:35]
	v_mfma_f32_16x16x32_bf16 v[20:23], v[164:167], v[204:207], v[20:23]
	v_mfma_f32_16x16x32_bf16 v[16:19], v[172:175], v[204:207], v[16:19]
	v_mfma_f32_16x16x32_bf16 v[4:7], v[164:167], v[216:219], v[4:7]
	v_mfma_f32_16x16x32_bf16 v[0:3], v[172:175], v[216:219], v[0:3]
	s_setprio 0
	s_barrier
	s_add_i32 s72, 0, 0x18000
	s_add_i32 s77, 0, 0x1c000
	v_add_u32_e32 v140, s72, v179
	v_add_u32_e32 v172, s77, v179
	ds_read_b128 v[128:131], v140
	ds_read_b128 v[132:135], v140 offset:1024
	ds_read_b128 v[136:139], v140 offset:2048
	ds_read_b128 v[140:143], v140 offset:3072
	ds_read_b128 v[160:163], v172
	ds_read_b128 v[164:167], v172 offset:1024
	ds_read_b128 v[168:171], v172 offset:2048
	ds_read_b128 v[172:175], v172 offset:3072
	s_add_u32 s54, s54, 0x40000
	s_addc_u32 s55, s55, 0
	s_mov_b32 m0, s61
	ds_read_b128 v[184:187], v183 offset:32768
	ds_read_b128 v[188:191], v183 offset:33792
	ds_read_b128 v[192:195], v183 offset:34816
	ds_read_b128 v[196:199], v183 offset:35840
	ds_read_b128 v[200:203], v183 offset:36864
	ds_read_b128 v[204:207], v183 offset:37888
	ds_read_b128 v[208:211], v183 offset:38912
	ds_read_b128 v[216:219], v183 offset:39936
	global_load_lds_dwordx4 v144, s[54:55]
	s_mov_b32 m0, s62
	s_nop 0
	global_load_lds_dwordx4 v148, s[54:55]
	s_waitcnt vmcnt(8)
	s_waitcnt lgkmcnt(0)
	s_barrier
	s_setprio 1
	s_waitcnt lgkmcnt(0)
	v_mfma_f32_16x16x32_bf16 v[124:127], v[128:131], v[184:187], v[124:127]
	v_mfma_f32_16x16x32_bf16 v[120:123], v[136:139], v[184:187], v[120:123]
	v_mfma_f32_16x16x32_bf16 v[108:111], v[128:131], v[192:195], v[108:111]
	v_mfma_f32_16x16x32_bf16 v[104:107], v[136:139], v[192:195], v[104:107]
	v_mfma_f32_16x16x32_bf16 v[92:95], v[128:131], v[200:203], v[92:95]
	v_mfma_f32_16x16x32_bf16 v[88:91], v[136:139], v[200:203], v[88:91]
	v_mfma_f32_16x16x32_bf16 v[76:79], v[128:131], v[208:211], v[76:79]
	v_mfma_f32_16x16x32_bf16 v[72:75], v[136:139], v[208:211], v[72:75]
	v_mfma_f32_16x16x32_bf16 v[124:127], v[132:135], v[188:191], v[124:127]
	v_mfma_f32_16x16x32_bf16 v[120:123], v[140:143], v[188:191], v[120:123]
	v_mfma_f32_16x16x32_bf16 v[108:111], v[132:135], v[196:199], v[108:111]
	v_mfma_f32_16x16x32_bf16 v[104:107], v[140:143], v[196:199], v[104:107]
	v_mfma_f32_16x16x32_bf16 v[92:95], v[132:135], v[204:207], v[92:95]
	v_mfma_f32_16x16x32_bf16 v[88:91], v[140:143], v[204:207], v[88:91]
	v_mfma_f32_16x16x32_bf16 v[76:79], v[132:135], v[216:219], v[76:79]
	v_mfma_f32_16x16x32_bf16 v[72:75], v[140:143], v[216:219], v[72:75]
	s_setprio 0
	s_setprio 1
	v_mfma_f32_16x16x32_bf16 v[116:119], v[160:163], v[184:187], v[116:119]
	v_mfma_f32_16x16x32_bf16 v[112:115], v[168:171], v[184:187], v[112:115]
	v_mfma_f32_16x16x32_bf16 v[100:103], v[160:163], v[192:195], v[100:103]
	v_mfma_f32_16x16x32_bf16 v[96:99], v[168:171], v[192:195], v[96:99]
	v_mfma_f32_16x16x32_bf16 v[84:87], v[160:163], v[200:203], v[84:87]
	v_mfma_f32_16x16x32_bf16 v[80:83], v[168:171], v[200:203], v[80:83]
	v_mfma_f32_16x16x32_bf16 v[68:71], v[160:163], v[208:211], v[68:71]
	v_mfma_f32_16x16x32_bf16 v[64:67], v[168:171], v[208:211], v[64:67]
	v_mfma_f32_16x16x32_bf16 v[116:119], v[164:167], v[188:191], v[116:119]
	v_mfma_f32_16x16x32_bf16 v[112:115], v[172:175], v[188:191], v[112:115]
	v_mfma_f32_16x16x32_bf16 v[100:103], v[164:167], v[196:199], v[100:103]
	v_mfma_f32_16x16x32_bf16 v[96:99], v[172:175], v[196:199], v[96:99]
	v_mfma_f32_16x16x32_bf16 v[84:87], v[164:167], v[204:207], v[84:87]
	v_mfma_f32_16x16x32_bf16 v[80:83], v[172:175], v[204:207], v[80:83]
	v_mfma_f32_16x16x32_bf16 v[68:71], v[164:167], v[216:219], v[68:71]
	v_mfma_f32_16x16x32_bf16 v[64:67], v[172:175], v[216:219], v[64:67]
	s_setprio 0
	s_barrier
	s_add_i32 s54, s72, s58
	s_mov_b32 m0, s54
	ds_read_b128 v[184:187], v183 offset:49152
	ds_read_b128 v[188:191], v183 offset:50176
	ds_read_b128 v[192:195], v183 offset:51200
	ds_read_b128 v[196:199], v183 offset:52224
	ds_read_b128 v[200:203], v183 offset:53248
	ds_read_b128 v[204:207], v183 offset:54272
	ds_read_b128 v[208:211], v183 offset:55296
	ds_read_b128 v[216:219], v183 offset:56320
	global_load_lds_dwordx4 v146, s[98:99]
	s_add_i32 m0, s54, 0x2000
	s_add_u32 s52, s52, 0x40080
	s_addc_u32 s53, s53, 0
	s_add_i32 s54, s77, s58
	global_load_lds_dwordx4 v150, s[98:99]
	s_mov_b32 m0, s54
	s_nop 0
	global_load_lds_dwordx4 v146, s[52:53]
	s_add_i32 m0, s54, 0x2000
	s_nop 0
	global_load_lds_dwordx4 v150, s[52:53]
	s_mov_b32 m0, s66
	s_nop 0
	global_load_lds_dwordx4 v144, s[100:101]
	s_mov_b32 m0, s67
	s_nop 0
	global_load_lds_dwordx4 v148, s[100:101]
	s_waitcnt vmcnt(8)
	s_waitcnt lgkmcnt(0)
	s_barrier
	s_setprio 1
	s_waitcnt lgkmcnt(0)
	v_mfma_f32_16x16x32_bf16 v[60:63], v[128:131], v[184:187], v[60:63]
	v_mfma_f32_16x16x32_bf16 v[56:59], v[136:139], v[184:187], v[56:59]
	v_mfma_f32_16x16x32_bf16 v[44:47], v[128:131], v[192:195], v[44:47]
	v_mfma_f32_16x16x32_bf16 v[40:43], v[136:139], v[192:195], v[40:43]
	v_mfma_f32_16x16x32_bf16 v[28:31], v[128:131], v[200:203], v[28:31]
	v_mfma_f32_16x16x32_bf16 v[24:27], v[136:139], v[200:203], v[24:27]
	v_mfma_f32_16x16x32_bf16 v[12:15], v[128:131], v[208:211], v[12:15]
	v_mfma_f32_16x16x32_bf16 v[8:11], v[136:139], v[208:211], v[8:11]
	v_mfma_f32_16x16x32_bf16 v[60:63], v[132:135], v[188:191], v[60:63]
	v_mfma_f32_16x16x32_bf16 v[56:59], v[140:143], v[188:191], v[56:59]
	v_mfma_f32_16x16x32_bf16 v[44:47], v[132:135], v[196:199], v[44:47]
	v_mfma_f32_16x16x32_bf16 v[40:43], v[140:143], v[196:199], v[40:43]
	v_mfma_f32_16x16x32_bf16 v[28:31], v[132:135], v[204:207], v[28:31]
	v_mfma_f32_16x16x32_bf16 v[24:27], v[140:143], v[204:207], v[24:27]
	v_mfma_f32_16x16x32_bf16 v[12:15], v[132:135], v[216:219], v[12:15]
	v_mfma_f32_16x16x32_bf16 v[8:11], v[140:143], v[216:219], v[8:11]
	s_setprio 0
	s_setprio 1
	v_mfma_f32_16x16x32_bf16 v[52:55], v[160:163], v[184:187], v[52:55]
	v_mfma_f32_16x16x32_bf16 v[48:51], v[168:171], v[184:187], v[48:51]
	v_mfma_f32_16x16x32_bf16 v[36:39], v[160:163], v[192:195], v[36:39]
	v_mfma_f32_16x16x32_bf16 v[32:35], v[168:171], v[192:195], v[32:35]
	v_mfma_f32_16x16x32_bf16 v[20:23], v[160:163], v[200:203], v[20:23]
	v_mfma_f32_16x16x32_bf16 v[16:19], v[168:171], v[200:203], v[16:19]
	v_mfma_f32_16x16x32_bf16 v[4:7], v[160:163], v[208:211], v[4:7]
	v_mfma_f32_16x16x32_bf16 v[0:3], v[168:171], v[208:211], v[0:3]
	v_mfma_f32_16x16x32_bf16 v[52:55], v[164:167], v[188:191], v[52:55]
	v_mfma_f32_16x16x32_bf16 v[48:51], v[172:175], v[188:191], v[48:51]
	v_mfma_f32_16x16x32_bf16 v[36:39], v[164:167], v[196:199], v[36:39]
	v_mfma_f32_16x16x32_bf16 v[32:35], v[172:175], v[196:199], v[32:35]
	v_mfma_f32_16x16x32_bf16 v[20:23], v[164:167], v[204:207], v[20:23]
	v_mfma_f32_16x16x32_bf16 v[16:19], v[172:175], v[204:207], v[16:19]
	v_mfma_f32_16x16x32_bf16 v[4:7], v[164:167], v[216:219], v[4:7]
	v_mfma_f32_16x16x32_bf16 v[0:3], v[172:175], v[216:219], v[0:3]
	s_setprio 0
	s_barrier
	s_add_i32 s76, s76, 2
	s_add_u32 s30, s30, 0x100
	s_addc_u32 s31, s31, 0
	s_add_u32 s73, s73, 0x100
	s_addc_u32 s74, s74, 0
	s_cmp_gt_u32 s76, 13
	s_cbranch_scc0 .LBB0_439
	s_and_b64 vcc, exec, s[14:15]
	s_cbranch_vccz .LBB0_442
	s_barrier

.LBB0_488:
	ds_read_b128 v[146:149], v220
	ds_read_b128 v[150:153], v220 offset:1024
	ds_read_b128 v[154:157], v220 offset:2048
	ds_read_b128 v[158:161], v220 offset:3072
	ds_read_b128 v[162:165], v221
	ds_read_b128 v[166:169], v221 offset:1024
	ds_read_b128 v[170:173], v221 offset:2048
	ds_read_b128 v[174:177], v221 offset:3072
	s_add_u32 s68, s66, 0xfffc0080
	s_addc_u32 s69, s67, -1
	s_cmp_eq_u32 s97, 12
	s_cselect_b32 s71, s57, s69
	s_cselect_b32 s70, s63, s68
	s_cselect_b32 s69, s55, s96
	s_cselect_b32 s68, s65, s95
	s_add_i32 m0, s77, 0xc000
	ds_read_b128 v[178:181], v222
	ds_read_b128 v[182:185], v222 offset:1024
	ds_read_b128 v[186:189], v222 offset:2048
	ds_read_b128 v[190:193], v222 offset:3072
	ds_read_b128 v[194:197], v222 offset:4096
	ds_read_b128 v[198:201], v222 offset:5120
	ds_read_b128 v[202:205], v222 offset:6144
	ds_read_b128 v[206:209], v222 offset:7168
	global_load_lds_dwordx4 v138, s[66:67]
	s_add_i32 m0, s77, 0xe000
	s_nop 0
	global_load_lds_dwordx4 v140, s[66:67]
	s_waitcnt vmcnt(8)
	s_waitcnt lgkmcnt(0)
	s_barrier
	s_setprio 1
	s_waitcnt lgkmcnt(0)
	v_mfma_f32_16x16x32_bf16 v[124:127], v[146:149], v[178:181], v[124:127]
	v_mfma_f32_16x16x32_bf16 v[60:63], v[154:157], v[178:181], v[60:63]
	v_mfma_f32_16x16x32_bf16 v[116:119], v[146:149], v[186:189], v[116:119]
	v_mfma_f32_16x16x32_bf16 v[52:55], v[154:157], v[186:189], v[52:55]
	v_mfma_f32_16x16x32_bf16 v[112:115], v[146:149], v[194:197], v[112:115]
	v_mfma_f32_16x16x32_bf16 v[48:51], v[154:157], v[194:197], v[48:51]
	v_mfma_f32_16x16x32_bf16 v[108:111], v[146:149], v[202:205], v[108:111]
	v_mfma_f32_16x16x32_bf16 v[40:43], v[154:157], v[202:205], v[40:43]
	v_mfma_f32_16x16x32_bf16 v[124:127], v[150:153], v[182:185], v[124:127]
	v_mfma_f32_16x16x32_bf16 v[60:63], v[158:161], v[182:185], v[60:63]
	v_mfma_f32_16x16x32_bf16 v[116:119], v[150:153], v[190:193], v[116:119]
	v_mfma_f32_16x16x32_bf16 v[52:55], v[158:161], v[190:193], v[52:55]
	v_mfma_f32_16x16x32_bf16 v[112:115], v[150:153], v[198:201], v[112:115]
	v_mfma_f32_16x16x32_bf16 v[48:51], v[158:161], v[198:201], v[48:51]
	v_mfma_f32_16x16x32_bf16 v[108:111], v[150:153], v[206:209], v[108:111]
	v_mfma_f32_16x16x32_bf16 v[40:43], v[158:161], v[206:209], v[40:43]
	s_setprio 0
	s_setprio 1
	v_mfma_f32_16x16x32_bf16 v[120:123], v[162:165], v[178:181], v[120:123]
	v_mfma_f32_16x16x32_bf16 v[56:59], v[170:173], v[178:181], v[56:59]
	v_mfma_f32_16x16x32_bf16 v[104:107], v[162:165], v[186:189], v[104:107]
	v_mfma_f32_16x16x32_bf16 v[44:47], v[170:173], v[186:189], v[44:47]
	v_mfma_f32_16x16x32_bf16 v[100:103], v[162:165], v[194:197], v[100:103]
	v_mfma_f32_16x16x32_bf16 v[36:39], v[170:173], v[194:197], v[36:39]
	v_mfma_f32_16x16x32_bf16 v[96:99], v[162:165], v[202:205], v[96:99]
	v_mfma_f32_16x16x32_bf16 v[32:35], v[170:173], v[202:205], v[32:35]
	v_mfma_f32_16x16x32_bf16 v[120:123], v[166:169], v[182:185], v[120:123]
	v_mfma_f32_16x16x32_bf16 v[56:59], v[174:177], v[182:185], v[56:59]
	v_mfma_f32_16x16x32_bf16 v[104:107], v[166:169], v[190:193], v[104:107]
	v_mfma_f32_16x16x32_bf16 v[44:47], v[174:177], v[190:193], v[44:47]
	v_mfma_f32_16x16x32_bf16 v[100:103], v[166:169], v[198:201], v[100:103]
	v_mfma_f32_16x16x32_bf16 v[36:39], v[174:177], v[198:201], v[36:39]
	v_mfma_f32_16x16x32_bf16 v[96:99], v[166:169], v[206:209], v[96:99]
	v_mfma_f32_16x16x32_bf16 v[32:35], v[174:177], v[206:209], v[32:35]
	s_setprio 0
	s_barrier
	s_add_u32 s98, s68, 0x80
	s_addc_u32 s99, s69, 0
	s_add_u32 s100, s70, 0x80
	s_addc_u32 s101, s71, 0
	s_add_i32 s72, s91, s76
	s_mov_b32 m0, s72
	ds_read_b128 v[178:181], v222 offset:16384
	ds_read_b128 v[182:185], v222 offset:17408
	ds_read_b128 v[186:189], v222 offset:18432
	ds_read_b128 v[190:193], v222 offset:19456
	ds_read_b128 v[194:197], v222 offset:20480
	ds_read_b128 v[198:201], v222 offset:21504
	ds_read_b128 v[202:205], v222 offset:22528
	ds_read_b128 v[206:209], v222 offset:23552
	global_load_lds_dwordx4 v128, s[68:69]
	s_add_i32 m0, s72, 0x2000
	s_add_u32 vcc_lo, s68, 0x40000
	s_addc_u32 vcc_hi, s69, 0
	s_add_i32 s72, s92, s76
	global_load_lds_dwordx4 v130, s[68:69]
	s_mov_b32 m0, s72
	s_nop 0
	global_load_lds_dwordx4 v128, vcc
	s_add_i32 m0, s72, 0x2000
	s_nop 0
	global_load_lds_dwordx4 v130, vcc
	s_mov_b32 m0, s77
	s_nop 0
	global_load_lds_dwordx4 v128, s[70:71]
	s_mov_b32 m0, s78
	s_nop 0
	global_load_lds_dwordx4 v130, s[70:71]
	s_waitcnt vmcnt(8)
	s_waitcnt lgkmcnt(0)
	s_barrier
	s_setprio 1
	s_waitcnt lgkmcnt(0)
	v_mfma_f32_16x16x32_bf16 v[92:95], v[146:149], v[178:181], v[92:95]
	v_mfma_f32_16x16x32_bf16 v[28:31], v[154:157], v[178:181], v[28:31]
	v_mfma_f32_16x16x32_bf16 v[84:87], v[146:149], v[186:189], v[84:87]
	v_mfma_f32_16x16x32_bf16 v[20:23], v[154:157], v[186:189], v[20:23]
	v_mfma_f32_16x16x32_bf16 v[80:83], v[146:149], v[194:197], v[80:83]
	v_mfma_f32_16x16x32_bf16 v[16:19], v[154:157], v[194:197], v[16:19]
	v_mfma_f32_16x16x32_bf16 v[76:79], v[146:149], v[202:205], v[76:79]
	v_mfma_f32_16x16x32_bf16 v[8:11], v[154:157], v[202:205], v[8:11]
	v_mfma_f32_16x16x32_bf16 v[92:95], v[150:153], v[182:185], v[92:95]
	v_mfma_f32_16x16x32_bf16 v[28:31], v[158:161], v[182:185], v[28:31]
	v_mfma_f32_16x16x32_bf16 v[84:87], v[150:153], v[190:193], v[84:87]
	v_mfma_f32_16x16x32_bf16 v[20:23], v[158:161], v[190:193], v[20:23]
	v_mfma_f32_16x16x32_bf16 v[80:83], v[150:153], v[198:201], v[80:83]
	v_mfma_f32_16x16x32_bf16 v[16:19], v[158:161], v[198:201], v[16:19]
	v_mfma_f32_16x16x32_bf16 v[76:79], v[150:153], v[206:209], v[76:79]
	v_mfma_f32_16x16x32_bf16 v[8:11], v[158:161], v[206:209], v[8:11]
	s_setprio 0
	s_setprio 1
	v_mfma_f32_16x16x32_bf16 v[88:91], v[162:165], v[178:181], v[88:91]
	v_mfma_f32_16x16x32_bf16 v[24:27], v[170:173], v[178:181], v[24:27]
	v_mfma_f32_16x16x32_bf16 v[72:75], v[162:165], v[186:189], v[72:75]
	v_mfma_f32_16x16x32_bf16 v[12:15], v[170:173], v[186:189], v[12:15]
	v_mfma_f32_16x16x32_bf16 v[68:71], v[162:165], v[194:197], v[68:71]
	v_mfma_f32_16x16x32_bf16 v[4:7], v[170:173], v[194:197], v[4:7]
	v_mfma_f32_16x16x32_bf16 v[64:67], v[162:165], v[202:205], v[64:67]
	v_mfma_f32_16x16x32_bf16 v[0:3], v[170:173], v[202:205], v[0:3]
	v_mfma_f32_16x16x32_bf16 v[88:91], v[166:169], v[182:185], v[88:91]
	v_mfma_f32_16x16x32_bf16 v[24:27], v[174:177], v[182:185], v[24:27]
	v_mfma_f32_16x16x32_bf16 v[72:75], v[166:169], v[190:193], v[72:75]
	v_mfma_f32_16x16x32_bf16 v[12:15], v[174:177], v[190:193], v[12:15]
	v_mfma_f32_16x16x32_bf16 v[68:71], v[166:169], v[198:201], v[68:71]
	v_mfma_f32_16x16x32_bf16 v[4:7], v[174:177], v[198:201], v[4:7]
	v_mfma_f32_16x16x32_bf16 v[64:67], v[166:169], v[206:209], v[64:67]
	v_mfma_f32_16x16x32_bf16 v[0:3], v[174:177], v[206:209], v[0:3]
	s_setprio 0
	s_barrier
	s_add_i32 s72, 0, 0x18000
	s_add_i32 vcc_lo, 0, 0x1c000
	v_add_u32_e32 v158, s72, v216
	v_add_u32_e32 v174, vcc_lo, v216
	ds_read_b128 v[146:149], v158
	ds_read_b128 v[150:153], v158 offset:1024
	ds_read_b128 v[154:157], v158 offset:2048
	ds_read_b128 v[158:161], v158 offset:3072
	ds_read_b128 v[162:165], v174
	ds_read_b128 v[166:169], v174 offset:1024
	ds_read_b128 v[170:173], v174 offset:2048
	ds_read_b128 v[174:177], v174 offset:3072
	s_add_u32 s70, s70, 0x40000
	s_addc_u32 s71, s71, 0
	s_mov_b32 m0, s79
	ds_read_b128 v[178:181], v222 offset:32768
	ds_read_b128 v[182:185], v222 offset:33792
	ds_read_b128 v[186:189], v222 offset:34816
	ds_read_b128 v[190:193], v222 offset:35840
	ds_read_b128 v[194:197], v222 offset:36864
	ds_read_b128 v[198:201], v222 offset:37888
	ds_read_b128 v[202:205], v222 offset:38912
	ds_read_b128 v[206:209], v222 offset:39936
	global_load_lds_dwordx4 v128, s[70:71]
	s_mov_b32 m0, s80
	s_nop 0
	global_load_lds_dwordx4 v130, s[70:71]
	s_waitcnt vmcnt(8)
	s_waitcnt lgkmcnt(0)
	s_barrier
	s_setprio 1
	s_waitcnt lgkmcnt(0)
	v_mfma_f32_16x16x32_bf16 v[124:127], v[146:149], v[178:181], v[124:127]
	v_mfma_f32_16x16x32_bf16 v[60:63], v[154:157], v[178:181], v[60:63]
	v_mfma_f32_16x16x32_bf16 v[116:119], v[146:149], v[186:189], v[116:119]
	v_mfma_f32_16x16x32_bf16 v[52:55], v[154:157], v[186:189], v[52:55]
	v_mfma_f32_16x16x32_bf16 v[112:115], v[146:149], v[194:197], v[112:115]
	v_mfma_f32_16x16x32_bf16 v[48:51], v[154:157], v[194:197], v[48:51]
	v_mfma_f32_16x16x32_bf16 v[108:111], v[146:149], v[202:205], v[108:111]
	v_mfma_f32_16x16x32_bf16 v[40:43], v[154:157], v[202:205], v[40:43]
	v_mfma_f32_16x16x32_bf16 v[124:127], v[150:153], v[182:185], v[124:127]
	v_mfma_f32_16x16x32_bf16 v[60:63], v[158:161], v[182:185], v[60:63]
	v_mfma_f32_16x16x32_bf16 v[116:119], v[150:153], v[190:193], v[116:119]
	v_mfma_f32_16x16x32_bf16 v[52:55], v[158:161], v[190:193], v[52:55]
	v_mfma_f32_16x16x32_bf16 v[112:115], v[150:153], v[198:201], v[112:115]
	v_mfma_f32_16x16x32_bf16 v[48:51], v[158:161], v[198:201], v[48:51]
	v_mfma_f32_16x16x32_bf16 v[108:111], v[150:153], v[206:209], v[108:111]
	v_mfma_f32_16x16x32_bf16 v[40:43], v[158:161], v[206:209], v[40:43]
	s_setprio 0
	s_setprio 1
	v_mfma_f32_16x16x32_bf16 v[120:123], v[162:165], v[178:181], v[120:123]
	v_mfma_f32_16x16x32_bf16 v[56:59], v[170:173], v[178:181], v[56:59]
	v_mfma_f32_16x16x32_bf16 v[104:107], v[162:165], v[186:189], v[104:107]
	v_mfma_f32_16x16x32_bf16 v[44:47], v[170:173], v[186:189], v[44:47]
	v_mfma_f32_16x16x32_bf16 v[100:103], v[162:165], v[194:197], v[100:103]
	v_mfma_f32_16x16x32_bf16 v[36:39], v[170:173], v[194:197], v[36:39]
	v_mfma_f32_16x16x32_bf16 v[96:99], v[162:165], v[202:205], v[96:99]
	v_mfma_f32_16x16x32_bf16 v[32:35], v[170:173], v[202:205], v[32:35]
	v_mfma_f32_16x16x32_bf16 v[120:123], v[166:169], v[182:185], v[120:123]
	v_mfma_f32_16x16x32_bf16 v[56:59], v[174:177], v[182:185], v[56:59]
	v_mfma_f32_16x16x32_bf16 v[104:107], v[166:169], v[190:193], v[104:107]
	v_mfma_f32_16x16x32_bf16 v[44:47], v[174:177], v[190:193], v[44:47]
	v_mfma_f32_16x16x32_bf16 v[100:103], v[166:169], v[198:201], v[100:103]
	v_mfma_f32_16x16x32_bf16 v[36:39], v[174:177], v[198:201], v[36:39]
	v_mfma_f32_16x16x32_bf16 v[96:99], v[166:169], v[206:209], v[96:99]
	v_mfma_f32_16x16x32_bf16 v[32:35], v[174:177], v[206:209], v[32:35]
	s_setprio 0
	s_barrier
	s_add_i32 s70, s72, s76
	s_mov_b32 m0, s70
	ds_read_b128 v[178:181], v222 offset:49152
	ds_read_b128 v[182:185], v222 offset:50176
	ds_read_b128 v[186:189], v222 offset:51200
	ds_read_b128 v[190:193], v222 offset:52224
	ds_read_b128 v[194:197], v222 offset:53248
	ds_read_b128 v[198:201], v222 offset:54272
	ds_read_b128 v[202:205], v222 offset:55296
	ds_read_b128 v[206:209], v222 offset:56320
	global_load_lds_dwordx4 v128, s[98:99]
	s_add_i32 m0, s70, 0x2000
	s_add_u32 s68, s68, 0x40080
	s_addc_u32 s69, s69, 0
	s_add_i32 s70, vcc_lo, s76
	global_load_lds_dwordx4 v130, s[98:99]
	s_mov_b32 m0, s70
	s_nop 0
	global_load_lds_dwordx4 v128, s[68:69]
	s_add_i32 m0, s70, 0x2000
	s_nop 0
	global_load_lds_dwordx4 v130, s[68:69]
	s_mov_b32 m0, s88
	s_nop 0
	global_load_lds_dwordx4 v128, s[100:101]
	s_mov_b32 m0, s89
	s_nop 0
	global_load_lds_dwordx4 v130, s[100:101]
	s_waitcnt vmcnt(8)
	s_waitcnt lgkmcnt(0)
	s_barrier
	s_setprio 1
	s_waitcnt lgkmcnt(0)
	v_mfma_f32_16x16x32_bf16 v[92:95], v[146:149], v[178:181], v[92:95]
	v_mfma_f32_16x16x32_bf16 v[28:31], v[154:157], v[178:181], v[28:31]
	v_mfma_f32_16x16x32_bf16 v[84:87], v[146:149], v[186:189], v[84:87]
	v_mfma_f32_16x16x32_bf16 v[20:23], v[154:157], v[186:189], v[20:23]
	v_mfma_f32_16x16x32_bf16 v[80:83], v[146:149], v[194:197], v[80:83]
	v_mfma_f32_16x16x32_bf16 v[16:19], v[154:157], v[194:197], v[16:19]
	v_mfma_f32_16x16x32_bf16 v[76:79], v[146:149], v[202:205], v[76:79]
	v_mfma_f32_16x16x32_bf16 v[8:11], v[154:157], v[202:205], v[8:11]
	v_mfma_f32_16x16x32_bf16 v[92:95], v[150:153], v[182:185], v[92:95]
	v_mfma_f32_16x16x32_bf16 v[28:31], v[158:161], v[182:185], v[28:31]
	v_mfma_f32_16x16x32_bf16 v[84:87], v[150:153], v[190:193], v[84:87]
	v_mfma_f32_16x16x32_bf16 v[20:23], v[158:161], v[190:193], v[20:23]
	v_mfma_f32_16x16x32_bf16 v[80:83], v[150:153], v[198:201], v[80:83]
	v_mfma_f32_16x16x32_bf16 v[16:19], v[158:161], v[198:201], v[16:19]
	v_mfma_f32_16x16x32_bf16 v[76:79], v[150:153], v[206:209], v[76:79]
	v_mfma_f32_16x16x32_bf16 v[8:11], v[158:161], v[206:209], v[8:11]
	s_setprio 0
	s_setprio 1
	v_mfma_f32_16x16x32_bf16 v[88:91], v[162:165], v[178:181], v[88:91]
	v_mfma_f32_16x16x32_bf16 v[24:27], v[170:173], v[178:181], v[24:27]
	v_mfma_f32_16x16x32_bf16 v[72:75], v[162:165], v[186:189], v[72:75]
	v_mfma_f32_16x16x32_bf16 v[12:15], v[170:173], v[186:189], v[12:15]
	v_mfma_f32_16x16x32_bf16 v[68:71], v[162:165], v[194:197], v[68:71]
	v_mfma_f32_16x16x32_bf16 v[4:7], v[170:173], v[194:197], v[4:7]
	v_mfma_f32_16x16x32_bf16 v[64:67], v[162:165], v[202:205], v[64:67]
	v_mfma_f32_16x16x32_bf16 v[0:3], v[170:173], v[202:205], v[0:3]
	v_mfma_f32_16x16x32_bf16 v[88:91], v[166:169], v[182:185], v[88:91]
	v_mfma_f32_16x16x32_bf16 v[24:27], v[174:177], v[182:185], v[24:27]
	v_mfma_f32_16x16x32_bf16 v[72:75], v[166:169], v[190:193], v[72:75]
	v_mfma_f32_16x16x32_bf16 v[12:15], v[174:177], v[190:193], v[12:15]
	v_mfma_f32_16x16x32_bf16 v[68:71], v[166:169], v[198:201], v[68:71]
	v_mfma_f32_16x16x32_bf16 v[4:7], v[174:177], v[198:201], v[4:7]
	v_mfma_f32_16x16x32_bf16 v[64:67], v[166:169], v[206:209], v[64:67]
	v_mfma_f32_16x16x32_bf16 v[0:3], v[174:177], v[206:209], v[0:3]
	s_setprio 0
	s_barrier
	s_add_i32 s97, s97, 2
	s_add_u32 s66, s66, 0x100
	s_addc_u32 s67, s67, 0
	s_add_u32 s95, s95, 0x100
	s_addc_u32 s96, s96, 0
	s_cmp_gt_u32 s97, 13
	s_cbranch_scc0 .LBB0_488
	s_and_b64 vcc, exec, s[22:23]
	s_cbranch_vccz .LBB0_491
	s_barrier

.LBB0_567:
	ds_read_b128 v[144:147], v138
	ds_read_b128 v[148:151], v138 offset:1024
	ds_read_b128 v[152:155], v138 offset:2048
	ds_read_b128 v[160:163], v138 offset:3072
	ds_read_b128 v[164:167], v139
	ds_read_b128 v[168:171], v139 offset:1024
	ds_read_b128 v[172:175], v139 offset:2048
	ds_read_b128 v[176:179], v139 offset:3072
	s_or_b32 s26, s30, 1
	s_lshl_b64 s[90:91], s[26:27], 7
	s_add_i32 s26, s30, 2
	s_lshl_b64 s[52:53], s[26:27], 7
	s_cmp_lg_u32 s30, s78
	s_cselect_b32 s30, s52, 0
	s_cselect_b32 s31, s53, 0
	s_add_u32 s52, s24, s30
	s_addc_u32 s53, s25, s31
	s_add_u32 s30, s22, s30
	s_addc_u32 s31, s23, s31
	s_add_u32 s90, s24, s90
	s_addc_u32 s91, s25, s91
	s_add_u32 s90, s90, 0xb0000
	s_addc_u32 s91, s91, 0
	s_mov_b32 m0, s79
	ds_read_b128 v[180:183], v140
	ds_read_b128 v[184:187], v140 offset:1024
	ds_read_b128 v[188:191], v140 offset:2048
	ds_read_b128 v[192:195], v140 offset:3072
	ds_read_b128 v[196:199], v140 offset:4096
	ds_read_b128 v[200:203], v140 offset:5120
	ds_read_b128 v[204:207], v140 offset:6144
	ds_read_b128 v[208:211], v140 offset:7168
	global_load_lds_dwordx4 v128, s[90:91]
	s_mov_b32 m0, s72
	s_nop 0
	global_load_lds_dwordx4 v132, s[90:91]
	s_waitcnt vmcnt(8)
	s_waitcnt lgkmcnt(0)
	s_barrier
	s_setprio 1
	s_waitcnt lgkmcnt(0)
	v_mfma_f32_16x16x32_bf16 v[124:127], v[144:147], v[180:183], v[124:127]
	v_mfma_f32_16x16x32_bf16 v[120:123], v[152:155], v[180:183], v[120:123]
	v_mfma_f32_16x16x32_bf16 v[116:119], v[144:147], v[188:191], v[116:119]
	v_mfma_f32_16x16x32_bf16 v[112:115], v[152:155], v[188:191], v[112:115]
	v_mfma_f32_16x16x32_bf16 v[108:111], v[144:147], v[196:199], v[108:111]
	v_mfma_f32_16x16x32_bf16 v[104:107], v[152:155], v[196:199], v[104:107]
	v_mfma_f32_16x16x32_bf16 v[100:103], v[144:147], v[204:207], v[100:103]
	v_mfma_f32_16x16x32_bf16 v[96:99], v[152:155], v[204:207], v[96:99]
	v_mfma_f32_16x16x32_bf16 v[124:127], v[148:151], v[184:187], v[124:127]
	v_mfma_f32_16x16x32_bf16 v[120:123], v[160:163], v[184:187], v[120:123]
	v_mfma_f32_16x16x32_bf16 v[116:119], v[148:151], v[192:195], v[116:119]
	v_mfma_f32_16x16x32_bf16 v[112:115], v[160:163], v[192:195], v[112:115]
	v_mfma_f32_16x16x32_bf16 v[108:111], v[148:151], v[200:203], v[108:111]
	v_mfma_f32_16x16x32_bf16 v[104:107], v[160:163], v[200:203], v[104:107]
	v_mfma_f32_16x16x32_bf16 v[100:103], v[148:151], v[208:211], v[100:103]
	v_mfma_f32_16x16x32_bf16 v[96:99], v[160:163], v[208:211], v[96:99]
	s_setprio 0
	s_setprio 1
	v_mfma_f32_16x16x32_bf16 v[92:95], v[164:167], v[180:183], v[92:95]
	v_mfma_f32_16x16x32_bf16 v[88:91], v[172:175], v[180:183], v[88:91]
	v_mfma_f32_16x16x32_bf16 v[84:87], v[164:167], v[188:191], v[84:87]
	v_mfma_f32_16x16x32_bf16 v[80:83], v[172:175], v[188:191], v[80:83]
	v_mfma_f32_16x16x32_bf16 v[76:79], v[164:167], v[196:199], v[76:79]
	v_mfma_f32_16x16x32_bf16 v[72:75], v[172:175], v[196:199], v[72:75]
	v_mfma_f32_16x16x32_bf16 v[68:71], v[164:167], v[204:207], v[68:71]
	v_mfma_f32_16x16x32_bf16 v[64:67], v[172:175], v[204:207], v[64:67]
	v_mfma_f32_16x16x32_bf16 v[92:95], v[168:171], v[184:187], v[92:95]
	v_mfma_f32_16x16x32_bf16 v[88:91], v[176:179], v[184:187], v[88:91]
	v_mfma_f32_16x16x32_bf16 v[84:87], v[168:171], v[192:195], v[84:87]
	v_mfma_f32_16x16x32_bf16 v[80:83], v[176:179], v[192:195], v[80:83]
	v_mfma_f32_16x16x32_bf16 v[76:79], v[168:171], v[200:203], v[76:79]
	v_mfma_f32_16x16x32_bf16 v[72:75], v[176:179], v[200:203], v[72:75]
	v_mfma_f32_16x16x32_bf16 v[68:71], v[168:171], v[208:211], v[68:71]
	v_mfma_f32_16x16x32_bf16 v[64:67], v[176:179], v[208:211], v[64:67]
	s_setprio 0
	s_barrier
	s_add_u32 s98, s30, 0x80
	s_addc_u32 s99, s31, 0
	s_add_u32 s100, s52, 0x80
	s_addc_u32 s101, s53, 0
	s_mov_b32 m0, s80
	s_add_u32 s90, s30, 0xb0000
	ds_read_b128 v[180:183], v140 offset:16384
	ds_read_b128 v[184:187], v140 offset:17408
	ds_read_b128 v[188:191], v140 offset:18432
	ds_read_b128 v[192:195], v140 offset:19456
	ds_read_b128 v[196:199], v140 offset:20480
	ds_read_b128 v[200:203], v140 offset:21504
	ds_read_b128 v[204:207], v140 offset:22528
	ds_read_b128 v[208:211], v140 offset:23552
	global_load_lds_dwordx4 v130, s[30:31]
	s_mov_b32 m0, s81
	s_addc_u32 s91, s31, 0
	global_load_lds_dwordx4 v134, s[30:31]
	s_mov_b32 m0, s82
	s_nop 0
	global_load_lds_dwordx4 v130, s[90:91]
	s_mov_b32 m0, s83
	s_nop 0
	global_load_lds_dwordx4 v134, s[90:91]
	s_mov_b32 m0, s68
	s_nop 0
	global_load_lds_dwordx4 v128, s[52:53]
	s_mov_b32 m0, s69
	s_nop 0
	global_load_lds_dwordx4 v132, s[52:53]
	s_waitcnt vmcnt(8)
	s_waitcnt lgkmcnt(0)
	s_barrier
	s_setprio 1
	s_waitcnt lgkmcnt(0)
	v_mfma_f32_16x16x32_bf16 v[60:63], v[144:147], v[180:183], v[60:63]
	v_mfma_f32_16x16x32_bf16 v[56:59], v[152:155], v[180:183], v[56:59]
	v_mfma_f32_16x16x32_bf16 v[52:55], v[144:147], v[188:191], v[52:55]
	v_mfma_f32_16x16x32_bf16 v[48:51], v[152:155], v[188:191], v[48:51]
	v_mfma_f32_16x16x32_bf16 v[44:47], v[144:147], v[196:199], v[44:47]
	v_mfma_f32_16x16x32_bf16 v[40:43], v[152:155], v[196:199], v[40:43]
	v_mfma_f32_16x16x32_bf16 v[36:39], v[144:147], v[204:207], v[36:39]
	v_mfma_f32_16x16x32_bf16 v[32:35], v[152:155], v[204:207], v[32:35]
	v_mfma_f32_16x16x32_bf16 v[60:63], v[148:151], v[184:187], v[60:63]
	v_mfma_f32_16x16x32_bf16 v[56:59], v[160:163], v[184:187], v[56:59]
	v_mfma_f32_16x16x32_bf16 v[52:55], v[148:151], v[192:195], v[52:55]
	v_mfma_f32_16x16x32_bf16 v[48:51], v[160:163], v[192:195], v[48:51]
	v_mfma_f32_16x16x32_bf16 v[44:47], v[148:151], v[200:203], v[44:47]
	v_mfma_f32_16x16x32_bf16 v[40:43], v[160:163], v[200:203], v[40:43]
	v_mfma_f32_16x16x32_bf16 v[36:39], v[148:151], v[208:211], v[36:39]
	v_mfma_f32_16x16x32_bf16 v[32:35], v[160:163], v[208:211], v[32:35]
	s_setprio 0
	s_setprio 1
	v_mfma_f32_16x16x32_bf16 v[28:31], v[164:167], v[180:183], v[28:31]
	v_mfma_f32_16x16x32_bf16 v[24:27], v[172:175], v[180:183], v[24:27]
	v_mfma_f32_16x16x32_bf16 v[20:23], v[164:167], v[188:191], v[20:23]
	v_mfma_f32_16x16x32_bf16 v[16:19], v[172:175], v[188:191], v[16:19]
	v_mfma_f32_16x16x32_bf16 v[12:15], v[164:167], v[196:199], v[12:15]
	v_mfma_f32_16x16x32_bf16 v[8:11], v[172:175], v[196:199], v[8:11]
	v_mfma_f32_16x16x32_bf16 v[4:7], v[164:167], v[204:207], v[4:7]
	v_mfma_f32_16x16x32_bf16 v[0:3], v[172:175], v[204:207], v[0:3]
	v_mfma_f32_16x16x32_bf16 v[28:31], v[168:171], v[184:187], v[28:31]
	v_mfma_f32_16x16x32_bf16 v[24:27], v[176:179], v[184:187], v[24:27]
	v_mfma_f32_16x16x32_bf16 v[20:23], v[168:171], v[192:195], v[20:23]
	v_mfma_f32_16x16x32_bf16 v[16:19], v[176:179], v[192:195], v[16:19]
	v_mfma_f32_16x16x32_bf16 v[12:15], v[168:171], v[200:203], v[12:15]
	v_mfma_f32_16x16x32_bf16 v[8:11], v[176:179], v[200:203], v[8:11]
	v_mfma_f32_16x16x32_bf16 v[4:7], v[168:171], v[208:211], v[4:7]
	v_mfma_f32_16x16x32_bf16 v[0:3], v[176:179], v[208:211], v[0:3]
	s_setprio 0
	s_barrier
	ds_read_b128 v[144:147], v141
	ds_read_b128 v[148:151], v141 offset:1024
	ds_read_b128 v[152:155], v141 offset:2048
	ds_read_b128 v[160:163], v141 offset:3072
	ds_read_b128 v[164:167], v142
	ds_read_b128 v[168:171], v142 offset:1024
	ds_read_b128 v[172:175], v142 offset:2048
	ds_read_b128 v[176:179], v142 offset:3072
	s_add_u32 s52, s52, 0xb0000
	s_addc_u32 s53, s53, 0
	s_mov_b32 m0, s70
	ds_read_b128 v[180:183], v140 offset:32768
	ds_read_b128 v[184:187], v140 offset:33792
	ds_read_b128 v[188:191], v140 offset:34816
	ds_read_b128 v[192:195], v140 offset:35840
	ds_read_b128 v[196:199], v140 offset:36864
	ds_read_b128 v[200:203], v140 offset:37888
	ds_read_b128 v[204:207], v140 offset:38912
	ds_read_b128 v[208:211], v140 offset:39936
	global_load_lds_dwordx4 v128, s[52:53]
	s_mov_b32 m0, s71
	s_nop 0
	global_load_lds_dwordx4 v132, s[52:53]
	s_waitcnt vmcnt(8)
	s_waitcnt lgkmcnt(0)
	s_barrier
	s_setprio 1
	s_waitcnt lgkmcnt(0)
	v_mfma_f32_16x16x32_bf16 v[124:127], v[144:147], v[180:183], v[124:127]
	v_mfma_f32_16x16x32_bf16 v[120:123], v[152:155], v[180:183], v[120:123]
	v_mfma_f32_16x16x32_bf16 v[116:119], v[144:147], v[188:191], v[116:119]
	v_mfma_f32_16x16x32_bf16 v[112:115], v[152:155], v[188:191], v[112:115]
	v_mfma_f32_16x16x32_bf16 v[108:111], v[144:147], v[196:199], v[108:111]
	v_mfma_f32_16x16x32_bf16 v[104:107], v[152:155], v[196:199], v[104:107]
	v_mfma_f32_16x16x32_bf16 v[100:103], v[144:147], v[204:207], v[100:103]
	v_mfma_f32_16x16x32_bf16 v[96:99], v[152:155], v[204:207], v[96:99]
	v_mfma_f32_16x16x32_bf16 v[124:127], v[148:151], v[184:187], v[124:127]
	v_mfma_f32_16x16x32_bf16 v[120:123], v[160:163], v[184:187], v[120:123]
	v_mfma_f32_16x16x32_bf16 v[116:119], v[148:151], v[192:195], v[116:119]
	v_mfma_f32_16x16x32_bf16 v[112:115], v[160:163], v[192:195], v[112:115]
	v_mfma_f32_16x16x32_bf16 v[108:111], v[148:151], v[200:203], v[108:111]
	v_mfma_f32_16x16x32_bf16 v[104:107], v[160:163], v[200:203], v[104:107]
	v_mfma_f32_16x16x32_bf16 v[100:103], v[148:151], v[208:211], v[100:103]
	v_mfma_f32_16x16x32_bf16 v[96:99], v[160:163], v[208:211], v[96:99]
	s_setprio 0
	s_setprio 1
	v_mfma_f32_16x16x32_bf16 v[92:95], v[164:167], v[180:183], v[92:95]
	v_mfma_f32_16x16x32_bf16 v[88:91], v[172:175], v[180:183], v[88:91]
	v_mfma_f32_16x16x32_bf16 v[84:87], v[164:167], v[188:191], v[84:87]
	v_mfma_f32_16x16x32_bf16 v[80:83], v[172:175], v[188:191], v[80:83]
	v_mfma_f32_16x16x32_bf16 v[76:79], v[164:167], v[196:199], v[76:79]
	v_mfma_f32_16x16x32_bf16 v[72:75], v[172:175], v[196:199], v[72:75]
	v_mfma_f32_16x16x32_bf16 v[68:71], v[164:167], v[204:207], v[68:71]
	v_mfma_f32_16x16x32_bf16 v[64:67], v[172:175], v[204:207], v[64:67]
	v_mfma_f32_16x16x32_bf16 v[92:95], v[168:171], v[184:187], v[92:95]
	v_mfma_f32_16x16x32_bf16 v[88:91], v[176:179], v[184:187], v[88:91]
	v_mfma_f32_16x16x32_bf16 v[84:87], v[168:171], v[192:195], v[84:87]
	v_mfma_f32_16x16x32_bf16 v[80:83], v[176:179], v[192:195], v[80:83]
	v_mfma_f32_16x16x32_bf16 v[76:79], v[168:171], v[200:203], v[76:79]
	v_mfma_f32_16x16x32_bf16 v[72:75], v[176:179], v[200:203], v[72:75]
	v_mfma_f32_16x16x32_bf16 v[68:71], v[168:171], v[208:211], v[68:71]
	v_mfma_f32_16x16x32_bf16 v[64:67], v[176:179], v[208:211], v[64:67]
	s_setprio 0
	s_barrier
	s_mov_b32 m0, s86
	s_add_u32 s30, s30, 0xb0080
	ds_read_b128 v[180:183], v140 offset:49152
	ds_read_b128 v[184:187], v140 offset:50176
	ds_read_b128 v[188:191], v140 offset:51200
	ds_read_b128 v[192:195], v140 offset:52224
	ds_read_b128 v[196:199], v140 offset:53248
	ds_read_b128 v[200:203], v140 offset:54272
	ds_read_b128 v[204:207], v140 offset:55296
	ds_read_b128 v[208:211], v140 offset:56320
	global_load_lds_dwordx4 v130, s[98:99]
	s_mov_b32 m0, s87
	s_addc_u32 s31, s31, 0
	global_load_lds_dwordx4 v134, s[98:99]
	s_mov_b32 m0, s88
	s_nop 0
	global_load_lds_dwordx4 v130, s[30:31]
	s_mov_b32 m0, s89
	s_nop 0
	global_load_lds_dwordx4 v134, s[30:31]
	s_mov_b32 m0, s76
	s_nop 0
	global_load_lds_dwordx4 v128, s[100:101]
	s_mov_b32 m0, s77
	s_nop 0
	global_load_lds_dwordx4 v132, s[100:101]
	s_waitcnt vmcnt(8)
	s_waitcnt lgkmcnt(0)
	s_barrier
	s_setprio 1
	s_waitcnt lgkmcnt(0)
	v_mfma_f32_16x16x32_bf16 v[60:63], v[144:147], v[180:183], v[60:63]
	v_mfma_f32_16x16x32_bf16 v[56:59], v[152:155], v[180:183], v[56:59]
	v_mfma_f32_16x16x32_bf16 v[52:55], v[144:147], v[188:191], v[52:55]
	v_mfma_f32_16x16x32_bf16 v[48:51], v[152:155], v[188:191], v[48:51]
	v_mfma_f32_16x16x32_bf16 v[44:47], v[144:147], v[196:199], v[44:47]
	v_mfma_f32_16x16x32_bf16 v[40:43], v[152:155], v[196:199], v[40:43]
	v_mfma_f32_16x16x32_bf16 v[36:39], v[144:147], v[204:207], v[36:39]
	v_mfma_f32_16x16x32_bf16 v[32:35], v[152:155], v[204:207], v[32:35]
	v_mfma_f32_16x16x32_bf16 v[60:63], v[148:151], v[184:187], v[60:63]
	v_mfma_f32_16x16x32_bf16 v[56:59], v[160:163], v[184:187], v[56:59]
	v_mfma_f32_16x16x32_bf16 v[52:55], v[148:151], v[192:195], v[52:55]
	v_mfma_f32_16x16x32_bf16 v[48:51], v[160:163], v[192:195], v[48:51]
	v_mfma_f32_16x16x32_bf16 v[44:47], v[148:151], v[200:203], v[44:47]
	v_mfma_f32_16x16x32_bf16 v[40:43], v[160:163], v[200:203], v[40:43]
	v_mfma_f32_16x16x32_bf16 v[36:39], v[148:151], v[208:211], v[36:39]
	v_mfma_f32_16x16x32_bf16 v[32:35], v[160:163], v[208:211], v[32:35]
	s_setprio 0
	s_setprio 1
	v_mfma_f32_16x16x32_bf16 v[28:31], v[164:167], v[180:183], v[28:31]
	v_mfma_f32_16x16x32_bf16 v[24:27], v[172:175], v[180:183], v[24:27]
	v_mfma_f32_16x16x32_bf16 v[20:23], v[164:167], v[188:191], v[20:23]
	v_mfma_f32_16x16x32_bf16 v[16:19], v[172:175], v[188:191], v[16:19]
	v_mfma_f32_16x16x32_bf16 v[12:15], v[164:167], v[196:199], v[12:15]
	v_mfma_f32_16x16x32_bf16 v[8:11], v[172:175], v[196:199], v[8:11]
	v_mfma_f32_16x16x32_bf16 v[4:7], v[164:167], v[204:207], v[4:7]
	v_mfma_f32_16x16x32_bf16 v[0:3], v[172:175], v[204:207], v[0:3]
	v_mfma_f32_16x16x32_bf16 v[28:31], v[168:171], v[184:187], v[28:31]
	v_mfma_f32_16x16x32_bf16 v[24:27], v[176:179], v[184:187], v[24:27]
	v_mfma_f32_16x16x32_bf16 v[20:23], v[168:171], v[192:195], v[20:23]
	v_mfma_f32_16x16x32_bf16 v[16:19], v[176:179], v[192:195], v[16:19]
	v_mfma_f32_16x16x32_bf16 v[12:15], v[168:171], v[200:203], v[12:15]
	v_mfma_f32_16x16x32_bf16 v[8:11], v[176:179], v[200:203], v[8:11]
	v_mfma_f32_16x16x32_bf16 v[4:7], v[168:171], v[208:211], v[4:7]
	v_mfma_f32_16x16x32_bf16 v[0:3], v[176:179], v[208:211], v[0:3]
	s_setprio 0
	s_barrier
	s_cmp_ge_u32 s26, s74
	s_mov_b32 s30, s26
	s_cbranch_scc0 .LBB0_567
	s_cmpk_lt_u32 s67, 0x100
	s_cbranch_scc0 .LBB0_570
	s_barrier

.LBB0_581:
	ds_read_b128 v[148:151], v143
	ds_read_b128 v[152:155], v143 offset:1024
	ds_read_b128 v[162:165], v143 offset:2048
	ds_read_b128 v[166:169], v143 offset:3072
	ds_read_b128 v[170:173], v144
	ds_read_b128 v[174:177], v144 offset:1024
	ds_read_b128 v[178:181], v144 offset:2048
	ds_read_b128 v[182:185], v144 offset:3072
	s_add_u32 s30, s28, 0x100
	s_addc_u32 s31, s29, 0
	s_cmp_lg_u32 s67, 6
	s_cselect_b32 s52, s30, 0
	s_cselect_b32 s53, s31, 0
	s_add_u32 s54, s24, s52
	s_addc_u32 s55, s25, s53
	s_add_u32 s52, s22, s52
	s_addc_u32 s53, s23, s53
	s_mov_b32 m0, s68
	v_lshl_add_u64 v[156:157], v[136:137], 0, s[28:29]
	ds_read_b128 v[186:189], v145
	ds_read_b128 v[190:193], v145 offset:1024
	ds_read_b128 v[194:197], v145 offset:2048
	ds_read_b128 v[198:201], v145 offset:3072
	ds_read_b128 v[202:205], v145 offset:4096
	ds_read_b128 v[206:209], v145 offset:5120
	ds_read_b128 v[210:213], v145 offset:6144
	ds_read_b128 v[216:219], v145 offset:7168
	global_load_lds_dwordx4 v[156:157], off
	v_lshl_add_u64 v[156:157], v[138:139], 0, s[28:29]
	s_mov_b32 m0, s69
	s_nop 0
	global_load_lds_dwordx4 v[156:157], off
	s_waitcnt vmcnt(8)
	s_waitcnt lgkmcnt(0)
	s_barrier
	s_setprio 1
	s_waitcnt lgkmcnt(0)
	v_mfma_f32_16x16x32_bf16 v[124:127], v[148:151], v[186:189], v[124:127]
	v_mfma_f32_16x16x32_bf16 v[120:123], v[162:165], v[186:189], v[120:123]
	v_mfma_f32_16x16x32_bf16 v[108:111], v[148:151], v[194:197], v[108:111]
	v_mfma_f32_16x16x32_bf16 v[104:107], v[162:165], v[194:197], v[104:107]
	v_mfma_f32_16x16x32_bf16 v[92:95], v[148:151], v[202:205], v[92:95]
	v_mfma_f32_16x16x32_bf16 v[88:91], v[162:165], v[202:205], v[88:91]
	v_mfma_f32_16x16x32_bf16 v[76:79], v[148:151], v[210:213], v[76:79]
	v_mfma_f32_16x16x32_bf16 v[72:75], v[162:165], v[210:213], v[72:75]
	v_mfma_f32_16x16x32_bf16 v[124:127], v[152:155], v[190:193], v[124:127]
	v_mfma_f32_16x16x32_bf16 v[120:123], v[166:169], v[190:193], v[120:123]
	v_mfma_f32_16x16x32_bf16 v[108:111], v[152:155], v[198:201], v[108:111]
	v_mfma_f32_16x16x32_bf16 v[104:107], v[166:169], v[198:201], v[104:107]
	v_mfma_f32_16x16x32_bf16 v[92:95], v[152:155], v[206:209], v[92:95]
	v_mfma_f32_16x16x32_bf16 v[88:91], v[166:169], v[206:209], v[88:91]
	v_mfma_f32_16x16x32_bf16 v[76:79], v[152:155], v[216:219], v[76:79]
	v_mfma_f32_16x16x32_bf16 v[72:75], v[166:169], v[216:219], v[72:75]
	s_setprio 0
	s_setprio 1
	v_mfma_f32_16x16x32_bf16 v[116:119], v[170:173], v[186:189], v[116:119]
	v_mfma_f32_16x16x32_bf16 v[112:115], v[178:181], v[186:189], v[112:115]
	v_mfma_f32_16x16x32_bf16 v[100:103], v[170:173], v[194:197], v[100:103]
	v_mfma_f32_16x16x32_bf16 v[96:99], v[178:181], v[194:197], v[96:99]
	v_mfma_f32_16x16x32_bf16 v[84:87], v[170:173], v[202:205], v[84:87]
	v_mfma_f32_16x16x32_bf16 v[80:83], v[178:181], v[202:205], v[80:83]
	v_mfma_f32_16x16x32_bf16 v[68:71], v[170:173], v[210:213], v[68:71]
	v_mfma_f32_16x16x32_bf16 v[64:67], v[178:181], v[210:213], v[64:67]
	v_mfma_f32_16x16x32_bf16 v[116:119], v[174:177], v[190:193], v[116:119]
	v_mfma_f32_16x16x32_bf16 v[112:115], v[182:185], v[190:193], v[112:115]
	v_mfma_f32_16x16x32_bf16 v[100:103], v[174:177], v[198:201], v[100:103]
	v_mfma_f32_16x16x32_bf16 v[96:99], v[182:185], v[198:201], v[96:99]
	v_mfma_f32_16x16x32_bf16 v[84:87], v[174:177], v[206:209], v[84:87]
	v_mfma_f32_16x16x32_bf16 v[80:83], v[182:185], v[206:209], v[80:83]
	v_mfma_f32_16x16x32_bf16 v[68:71], v[174:177], v[216:219], v[68:71]
	v_mfma_f32_16x16x32_bf16 v[64:67], v[182:185], v[216:219], v[64:67]
	s_setprio 0
	s_barrier
	s_add_u32 s98, s52, 0x80
	s_addc_u32 s99, s53, 0
	s_add_u32 s100, s54, 0x80
	s_addc_u32 s101, s55, 0
	s_mov_b32 m0, s70
	s_add_u32 s28, s52, 0xb0000
	ds_read_b128 v[186:189], v145 offset:16384
	ds_read_b128 v[190:193], v145 offset:17408
	ds_read_b128 v[194:197], v145 offset:18432
	ds_read_b128 v[198:201], v145 offset:19456
	ds_read_b128 v[202:205], v145 offset:20480
	ds_read_b128 v[206:209], v145 offset:21504
	ds_read_b128 v[210:213], v145 offset:22528
	ds_read_b128 v[216:219], v145 offset:23552
	global_load_lds_dwordx4 v130, s[52:53]
	s_mov_b32 m0, s71
	s_addc_u32 s29, s53, 0
	global_load_lds_dwordx4 v134, s[52:53]
	s_mov_b32 m0, s72
	s_nop 0
	global_load_lds_dwordx4 v130, s[28:29]
	s_mov_b32 m0, s73
	s_nop 0
	global_load_lds_dwordx4 v134, s[28:29]
	s_mov_b32 m0, s63
	s_nop 0
	global_load_lds_dwordx4 v128, s[54:55]
	s_mov_b32 m0, s60
	s_nop 0
	global_load_lds_dwordx4 v132, s[54:55]
	s_waitcnt vmcnt(8)
	s_waitcnt lgkmcnt(0)
	s_barrier
	s_setprio 1
	s_waitcnt lgkmcnt(0)
	v_mfma_f32_16x16x32_bf16 v[60:63], v[148:151], v[186:189], v[60:63]
	v_mfma_f32_16x16x32_bf16 v[56:59], v[162:165], v[186:189], v[56:59]
	v_mfma_f32_16x16x32_bf16 v[44:47], v[148:151], v[194:197], v[44:47]
	v_mfma_f32_16x16x32_bf16 v[40:43], v[162:165], v[194:197], v[40:43]
	v_mfma_f32_16x16x32_bf16 v[28:31], v[148:151], v[202:205], v[28:31]
	v_mfma_f32_16x16x32_bf16 v[24:27], v[162:165], v[202:205], v[24:27]
	v_mfma_f32_16x16x32_bf16 v[12:15], v[148:151], v[210:213], v[12:15]
	v_mfma_f32_16x16x32_bf16 v[8:11], v[162:165], v[210:213], v[8:11]
	v_mfma_f32_16x16x32_bf16 v[60:63], v[152:155], v[190:193], v[60:63]
	v_mfma_f32_16x16x32_bf16 v[56:59], v[166:169], v[190:193], v[56:59]
	v_mfma_f32_16x16x32_bf16 v[44:47], v[152:155], v[198:201], v[44:47]
	v_mfma_f32_16x16x32_bf16 v[40:43], v[166:169], v[198:201], v[40:43]
	v_mfma_f32_16x16x32_bf16 v[28:31], v[152:155], v[206:209], v[28:31]
	v_mfma_f32_16x16x32_bf16 v[24:27], v[166:169], v[206:209], v[24:27]
	v_mfma_f32_16x16x32_bf16 v[12:15], v[152:155], v[216:219], v[12:15]
	v_mfma_f32_16x16x32_bf16 v[8:11], v[166:169], v[216:219], v[8:11]
	s_setprio 0
	s_setprio 1
	v_mfma_f32_16x16x32_bf16 v[52:55], v[170:173], v[186:189], v[52:55]
	v_mfma_f32_16x16x32_bf16 v[48:51], v[178:181], v[186:189], v[48:51]
	v_mfma_f32_16x16x32_bf16 v[36:39], v[170:173], v[194:197], v[36:39]
	v_mfma_f32_16x16x32_bf16 v[32:35], v[178:181], v[194:197], v[32:35]
	v_mfma_f32_16x16x32_bf16 v[20:23], v[170:173], v[202:205], v[20:23]
	v_mfma_f32_16x16x32_bf16 v[16:19], v[178:181], v[202:205], v[16:19]
	v_mfma_f32_16x16x32_bf16 v[4:7], v[170:173], v[210:213], v[4:7]
	v_mfma_f32_16x16x32_bf16 v[0:3], v[178:181], v[210:213], v[0:3]
	v_mfma_f32_16x16x32_bf16 v[52:55], v[174:177], v[190:193], v[52:55]
	v_mfma_f32_16x16x32_bf16 v[48:51], v[182:185], v[190:193], v[48:51]
	v_mfma_f32_16x16x32_bf16 v[36:39], v[174:177], v[198:201], v[36:39]
	v_mfma_f32_16x16x32_bf16 v[32:35], v[182:185], v[198:201], v[32:35]
	v_mfma_f32_16x16x32_bf16 v[20:23], v[174:177], v[206:209], v[20:23]
	v_mfma_f32_16x16x32_bf16 v[16:19], v[182:185], v[206:209], v[16:19]
	v_mfma_f32_16x16x32_bf16 v[4:7], v[174:177], v[216:219], v[4:7]
	v_mfma_f32_16x16x32_bf16 v[0:3], v[182:185], v[216:219], v[0:3]
	s_setprio 0
	s_barrier
	ds_read_b128 v[148:151], v146
	ds_read_b128 v[152:155], v146 offset:1024
	ds_read_b128 v[162:165], v146 offset:2048
	ds_read_b128 v[166:169], v146 offset:3072
	ds_read_b128 v[170:173], v147
	ds_read_b128 v[174:177], v147 offset:1024
	ds_read_b128 v[178:181], v147 offset:2048
	ds_read_b128 v[182:185], v147 offset:3072
	s_add_u32 s28, s54, 0xb0000
	s_addc_u32 s29, s55, 0
	s_mov_b32 m0, s61
	ds_read_b128 v[186:189], v145 offset:32768
	ds_read_b128 v[190:193], v145 offset:33792
	ds_read_b128 v[194:197], v145 offset:34816
	ds_read_b128 v[198:201], v145 offset:35840
	ds_read_b128 v[202:205], v145 offset:36864
	ds_read_b128 v[206:209], v145 offset:37888
	ds_read_b128 v[210:213], v145 offset:38912
	ds_read_b128 v[216:219], v145 offset:39936
	global_load_lds_dwordx4 v128, s[28:29]
	s_mov_b32 m0, s62
	s_nop 0
	global_load_lds_dwordx4 v132, s[28:29]
	s_waitcnt vmcnt(8)
	s_waitcnt lgkmcnt(0)
	s_barrier
	s_setprio 1
	s_waitcnt lgkmcnt(0)
	v_mfma_f32_16x16x32_bf16 v[124:127], v[148:151], v[186:189], v[124:127]
	v_mfma_f32_16x16x32_bf16 v[120:123], v[162:165], v[186:189], v[120:123]
	v_mfma_f32_16x16x32_bf16 v[108:111], v[148:151], v[194:197], v[108:111]
	v_mfma_f32_16x16x32_bf16 v[104:107], v[162:165], v[194:197], v[104:107]
	v_mfma_f32_16x16x32_bf16 v[92:95], v[148:151], v[202:205], v[92:95]
	v_mfma_f32_16x16x32_bf16 v[88:91], v[162:165], v[202:205], v[88:91]
	v_mfma_f32_16x16x32_bf16 v[76:79], v[148:151], v[210:213], v[76:79]
	v_mfma_f32_16x16x32_bf16 v[72:75], v[162:165], v[210:213], v[72:75]
	v_mfma_f32_16x16x32_bf16 v[124:127], v[152:155], v[190:193], v[124:127]
	v_mfma_f32_16x16x32_bf16 v[120:123], v[166:169], v[190:193], v[120:123]
	v_mfma_f32_16x16x32_bf16 v[108:111], v[152:155], v[198:201], v[108:111]
	v_mfma_f32_16x16x32_bf16 v[104:107], v[166:169], v[198:201], v[104:107]
	v_mfma_f32_16x16x32_bf16 v[92:95], v[152:155], v[206:209], v[92:95]
	v_mfma_f32_16x16x32_bf16 v[88:91], v[166:169], v[206:209], v[88:91]
	v_mfma_f32_16x16x32_bf16 v[76:79], v[152:155], v[216:219], v[76:79]
	v_mfma_f32_16x16x32_bf16 v[72:75], v[166:169], v[216:219], v[72:75]
	s_setprio 0
	s_setprio 1
	v_mfma_f32_16x16x32_bf16 v[116:119], v[170:173], v[186:189], v[116:119]
	v_mfma_f32_16x16x32_bf16 v[112:115], v[178:181], v[186:189], v[112:115]
	v_mfma_f32_16x16x32_bf16 v[100:103], v[170:173], v[194:197], v[100:103]
	v_mfma_f32_16x16x32_bf16 v[96:99], v[178:181], v[194:197], v[96:99]
	v_mfma_f32_16x16x32_bf16 v[84:87], v[170:173], v[202:205], v[84:87]
	v_mfma_f32_16x16x32_bf16 v[80:83], v[178:181], v[202:205], v[80:83]
	v_mfma_f32_16x16x32_bf16 v[68:71], v[170:173], v[210:213], v[68:71]
	v_mfma_f32_16x16x32_bf16 v[64:67], v[178:181], v[210:213], v[64:67]
	v_mfma_f32_16x16x32_bf16 v[116:119], v[174:177], v[190:193], v[116:119]
	v_mfma_f32_16x16x32_bf16 v[112:115], v[182:185], v[190:193], v[112:115]
	v_mfma_f32_16x16x32_bf16 v[100:103], v[174:177], v[198:201], v[100:103]
	v_mfma_f32_16x16x32_bf16 v[96:99], v[182:185], v[198:201], v[96:99]
	v_mfma_f32_16x16x32_bf16 v[84:87], v[174:177], v[206:209], v[84:87]
	v_mfma_f32_16x16x32_bf16 v[80:83], v[182:185], v[206:209], v[80:83]
	v_mfma_f32_16x16x32_bf16 v[68:71], v[174:177], v[216:219], v[68:71]
	v_mfma_f32_16x16x32_bf16 v[64:67], v[182:185], v[216:219], v[64:67]
	s_setprio 0
	s_barrier
	s_mov_b32 m0, s74
	s_add_u32 s28, s52, 0xb0080
	ds_read_b128 v[186:189], v145 offset:49152
	ds_read_b128 v[190:193], v145 offset:50176
	ds_read_b128 v[194:197], v145 offset:51200
	ds_read_b128 v[198:201], v145 offset:52224
	ds_read_b128 v[202:205], v145 offset:53248
	ds_read_b128 v[206:209], v145 offset:54272
	ds_read_b128 v[210:213], v145 offset:55296
	ds_read_b128 v[216:219], v145 offset:56320
	global_load_lds_dwordx4 v130, s[98:99]
	s_mov_b32 m0, s76
	s_addc_u32 s29, s53, 0
	global_load_lds_dwordx4 v134, s[98:99]
	s_mov_b32 m0, s77
	s_nop 0
	global_load_lds_dwordx4 v130, s[28:29]
	s_mov_b32 m0, s78
	s_nop 0
	global_load_lds_dwordx4 v134, s[28:29]
	s_mov_b32 m0, s64
	s_nop 0
	global_load_lds_dwordx4 v128, s[100:101]
	s_mov_b32 m0, s65
	s_nop 0
	global_load_lds_dwordx4 v132, s[100:101]
	s_waitcnt vmcnt(8)
	s_waitcnt lgkmcnt(0)
	s_barrier
	s_setprio 1
	s_waitcnt lgkmcnt(0)
	v_mfma_f32_16x16x32_bf16 v[60:63], v[148:151], v[186:189], v[60:63]
	v_mfma_f32_16x16x32_bf16 v[56:59], v[162:165], v[186:189], v[56:59]
	v_mfma_f32_16x16x32_bf16 v[44:47], v[148:151], v[194:197], v[44:47]
	v_mfma_f32_16x16x32_bf16 v[40:43], v[162:165], v[194:197], v[40:43]
	v_mfma_f32_16x16x32_bf16 v[28:31], v[148:151], v[202:205], v[28:31]
	v_mfma_f32_16x16x32_bf16 v[24:27], v[162:165], v[202:205], v[24:27]
	v_mfma_f32_16x16x32_bf16 v[12:15], v[148:151], v[210:213], v[12:15]
	v_mfma_f32_16x16x32_bf16 v[8:11], v[162:165], v[210:213], v[8:11]
	v_mfma_f32_16x16x32_bf16 v[60:63], v[152:155], v[190:193], v[60:63]
	v_mfma_f32_16x16x32_bf16 v[56:59], v[166:169], v[190:193], v[56:59]
	v_mfma_f32_16x16x32_bf16 v[44:47], v[152:155], v[198:201], v[44:47]
	v_mfma_f32_16x16x32_bf16 v[40:43], v[166:169], v[198:201], v[40:43]
	v_mfma_f32_16x16x32_bf16 v[28:31], v[152:155], v[206:209], v[28:31]
	v_mfma_f32_16x16x32_bf16 v[24:27], v[166:169], v[206:209], v[24:27]
	v_mfma_f32_16x16x32_bf16 v[12:15], v[152:155], v[216:219], v[12:15]
	v_mfma_f32_16x16x32_bf16 v[8:11], v[166:169], v[216:219], v[8:11]
	s_setprio 0
	s_setprio 1
	v_mfma_f32_16x16x32_bf16 v[52:55], v[170:173], v[186:189], v[52:55]
	v_mfma_f32_16x16x32_bf16 v[48:51], v[178:181], v[186:189], v[48:51]
	v_mfma_f32_16x16x32_bf16 v[36:39], v[170:173], v[194:197], v[36:39]
	v_mfma_f32_16x16x32_bf16 v[32:35], v[178:181], v[194:197], v[32:35]
	v_mfma_f32_16x16x32_bf16 v[20:23], v[170:173], v[202:205], v[20:23]
	v_mfma_f32_16x16x32_bf16 v[16:19], v[178:181], v[202:205], v[16:19]
	v_mfma_f32_16x16x32_bf16 v[4:7], v[170:173], v[210:213], v[4:7]
	v_mfma_f32_16x16x32_bf16 v[0:3], v[178:181], v[210:213], v[0:3]
	v_mfma_f32_16x16x32_bf16 v[52:55], v[174:177], v[190:193], v[52:55]
	v_mfma_f32_16x16x32_bf16 v[48:51], v[182:185], v[190:193], v[48:51]
	v_mfma_f32_16x16x32_bf16 v[36:39], v[174:177], v[198:201], v[36:39]
	v_mfma_f32_16x16x32_bf16 v[32:35], v[182:185], v[198:201], v[32:35]
	v_mfma_f32_16x16x32_bf16 v[20:23], v[174:177], v[206:209], v[20:23]
	v_mfma_f32_16x16x32_bf16 v[16:19], v[182:185], v[206:209], v[16:19]
	v_mfma_f32_16x16x32_bf16 v[4:7], v[174:177], v[216:219], v[4:7]
	v_mfma_f32_16x16x32_bf16 v[0:3], v[182:185], v[216:219], v[0:3]
	s_setprio 0
	s_barrier
	s_add_i32 s67, s67, 2
	s_cmp_gt_u32 s67, 7
	s_mov_b64 s[28:29], s[30:31]
	s_cbranch_scc0 .LBB0_581
	s_cmpk_lt_u32 s66, 0x100
	s_cbranch_scc0 .LBB0_584
	s_barrier

.LBB0_658:
	ds_read_b128 v[128:131], v177
	ds_read_b128 v[132:135], v177 offset:1024
	ds_read_b128 v[136:139], v177 offset:2048
	ds_read_b128 v[140:143], v177 offset:3072
	ds_read_b128 v[158:161], v178
	ds_read_b128 v[162:165], v178 offset:1024
	ds_read_b128 v[166:169], v178 offset:2048
	ds_read_b128 v[180:183], v178 offset:3072
	s_add_u32 s26, s24, 0x100
	s_addc_u32 s27, s25, 0
	s_cmp_eq_u32 s72, 40
	s_cselect_b32 s31, s7, s27
	s_cselect_b32 s30, s6, s26
	s_cselect_b32 s29, s23, s74
	s_cselect_b32 s28, s22, s12
	s_add_i32 m0, s57, 0xc000
	ds_read_b128 v[184:187], v179
	ds_read_b128 v[188:191], v179 offset:1024
	ds_read_b128 v[192:195], v179 offset:2048
	ds_read_b128 v[196:199], v179 offset:3072
	ds_read_b128 v[200:203], v179 offset:4096
	ds_read_b128 v[204:207], v179 offset:5120
	ds_read_b128 v[208:211], v179 offset:6144
	ds_read_b128 v[216:219], v179 offset:7168
	global_load_lds_dwordx4 v152, s[24:25]
	s_add_i32 m0, s57, 0xe000
	s_nop 0
	global_load_lds_dwordx4 v154, s[24:25]
	s_waitcnt vmcnt(8)
	s_waitcnt lgkmcnt(0)
	s_barrier
	s_setprio 1
	s_waitcnt lgkmcnt(0)
	v_mfma_f32_16x16x32_bf16 v[124:127], v[128:131], v[184:187], v[124:127]
	v_mfma_f32_16x16x32_bf16 v[120:123], v[136:139], v[184:187], v[120:123]
	v_mfma_f32_16x16x32_bf16 v[108:111], v[128:131], v[192:195], v[108:111]
	v_mfma_f32_16x16x32_bf16 v[104:107], v[136:139], v[192:195], v[104:107]
	v_mfma_f32_16x16x32_bf16 v[92:95], v[128:131], v[200:203], v[92:95]
	v_mfma_f32_16x16x32_bf16 v[88:91], v[136:139], v[200:203], v[88:91]
	v_mfma_f32_16x16x32_bf16 v[76:79], v[128:131], v[208:211], v[76:79]
	v_mfma_f32_16x16x32_bf16 v[72:75], v[136:139], v[208:211], v[72:75]
	v_mfma_f32_16x16x32_bf16 v[124:127], v[132:135], v[188:191], v[124:127]
	v_mfma_f32_16x16x32_bf16 v[120:123], v[140:143], v[188:191], v[120:123]
	v_mfma_f32_16x16x32_bf16 v[108:111], v[132:135], v[196:199], v[108:111]
	v_mfma_f32_16x16x32_bf16 v[104:107], v[140:143], v[196:199], v[104:107]
	v_mfma_f32_16x16x32_bf16 v[92:95], v[132:135], v[204:207], v[92:95]
	v_mfma_f32_16x16x32_bf16 v[88:91], v[140:143], v[204:207], v[88:91]
	v_mfma_f32_16x16x32_bf16 v[76:79], v[132:135], v[216:219], v[76:79]
	v_mfma_f32_16x16x32_bf16 v[72:75], v[140:143], v[216:219], v[72:75]
	s_setprio 0
	s_setprio 1
	v_mfma_f32_16x16x32_bf16 v[116:119], v[158:161], v[184:187], v[116:119]
	v_mfma_f32_16x16x32_bf16 v[112:115], v[166:169], v[184:187], v[112:115]
	v_mfma_f32_16x16x32_bf16 v[100:103], v[158:161], v[192:195], v[100:103]
	v_mfma_f32_16x16x32_bf16 v[96:99], v[166:169], v[192:195], v[96:99]
	v_mfma_f32_16x16x32_bf16 v[84:87], v[158:161], v[200:203], v[84:87]
	v_mfma_f32_16x16x32_bf16 v[80:83], v[166:169], v[200:203], v[80:83]
	v_mfma_f32_16x16x32_bf16 v[68:71], v[158:161], v[208:211], v[68:71]
	v_mfma_f32_16x16x32_bf16 v[64:67], v[166:169], v[208:211], v[64:67]
	v_mfma_f32_16x16x32_bf16 v[116:119], v[162:165], v[188:191], v[116:119]
	v_mfma_f32_16x16x32_bf16 v[112:115], v[180:183], v[188:191], v[112:115]
	v_mfma_f32_16x16x32_bf16 v[100:103], v[162:165], v[196:199], v[100:103]
	v_mfma_f32_16x16x32_bf16 v[96:99], v[180:183], v[196:199], v[96:99]
	v_mfma_f32_16x16x32_bf16 v[84:87], v[162:165], v[204:207], v[84:87]
	v_mfma_f32_16x16x32_bf16 v[80:83], v[180:183], v[204:207], v[80:83]
	v_mfma_f32_16x16x32_bf16 v[68:71], v[162:165], v[216:219], v[68:71]
	v_mfma_f32_16x16x32_bf16 v[64:67], v[180:183], v[216:219], v[64:67]
	s_setprio 0
	s_barrier
	s_add_u32 s98, s28, 0x80
	s_addc_u32 s99, s29, 0
	s_add_u32 s100, s30, 0x80
	s_addc_u32 s101, s31, 0
	s_add_i32 s24, s66, s56
	s_mov_b32 m0, s24
	ds_read_b128 v[184:187], v179 offset:16384
	ds_read_b128 v[188:191], v179 offset:17408
	ds_read_b128 v[192:195], v179 offset:18432
	ds_read_b128 v[196:199], v179 offset:19456
	ds_read_b128 v[200:203], v179 offset:20480
	ds_read_b128 v[204:207], v179 offset:21504
	ds_read_b128 v[208:211], v179 offset:22528
	ds_read_b128 v[216:219], v179 offset:23552
	global_load_lds_dwordx4 v146, s[28:29]
	s_add_i32 m0, s24, 0x2000
	s_add_u32 s24, s28, 0xb0000
	s_addc_u32 s25, s29, 0
	s_add_i32 s76, s67, s56
	global_load_lds_dwordx4 v150, s[28:29]
	s_mov_b32 m0, s76
	s_nop 0
	global_load_lds_dwordx4 v146, s[24:25]
	s_add_i32 m0, s76, 0x2000
	s_nop 0
	global_load_lds_dwordx4 v150, s[24:25]
	s_mov_b32 m0, s57
	s_nop 0
	global_load_lds_dwordx4 v144, s[30:31]
	s_mov_b32 m0, s58
	s_nop 0
	global_load_lds_dwordx4 v148, s[30:31]
	s_waitcnt vmcnt(8)
	s_waitcnt lgkmcnt(0)
	s_barrier
	s_setprio 1
	s_waitcnt lgkmcnt(0)
	v_mfma_f32_16x16x32_bf16 v[60:63], v[128:131], v[184:187], v[60:63]
	v_mfma_f32_16x16x32_bf16 v[56:59], v[136:139], v[184:187], v[56:59]
	v_mfma_f32_16x16x32_bf16 v[44:47], v[128:131], v[192:195], v[44:47]
	v_mfma_f32_16x16x32_bf16 v[40:43], v[136:139], v[192:195], v[40:43]
	v_mfma_f32_16x16x32_bf16 v[28:31], v[128:131], v[200:203], v[28:31]
	v_mfma_f32_16x16x32_bf16 v[24:27], v[136:139], v[200:203], v[24:27]
	v_mfma_f32_16x16x32_bf16 v[12:15], v[128:131], v[208:211], v[12:15]
	v_mfma_f32_16x16x32_bf16 v[8:11], v[136:139], v[208:211], v[8:11]
	v_mfma_f32_16x16x32_bf16 v[60:63], v[132:135], v[188:191], v[60:63]
	v_mfma_f32_16x16x32_bf16 v[56:59], v[140:143], v[188:191], v[56:59]
	v_mfma_f32_16x16x32_bf16 v[44:47], v[132:135], v[196:199], v[44:47]
	v_mfma_f32_16x16x32_bf16 v[40:43], v[140:143], v[196:199], v[40:43]
	v_mfma_f32_16x16x32_bf16 v[28:31], v[132:135], v[204:207], v[28:31]
	v_mfma_f32_16x16x32_bf16 v[24:27], v[140:143], v[204:207], v[24:27]
	v_mfma_f32_16x16x32_bf16 v[12:15], v[132:135], v[216:219], v[12:15]
	v_mfma_f32_16x16x32_bf16 v[8:11], v[140:143], v[216:219], v[8:11]
	s_setprio 0
	s_setprio 1
	v_mfma_f32_16x16x32_bf16 v[52:55], v[158:161], v[184:187], v[52:55]
	v_mfma_f32_16x16x32_bf16 v[48:51], v[166:169], v[184:187], v[48:51]
	v_mfma_f32_16x16x32_bf16 v[36:39], v[158:161], v[192:195], v[36:39]
	v_mfma_f32_16x16x32_bf16 v[32:35], v[166:169], v[192:195], v[32:35]
	v_mfma_f32_16x16x32_bf16 v[20:23], v[158:161], v[200:203], v[20:23]
	v_mfma_f32_16x16x32_bf16 v[16:19], v[166:169], v[200:203], v[16:19]
	v_mfma_f32_16x16x32_bf16 v[4:7], v[158:161], v[208:211], v[4:7]
	v_mfma_f32_16x16x32_bf16 v[0:3], v[166:169], v[208:211], v[0:3]
	v_mfma_f32_16x16x32_bf16 v[52:55], v[162:165], v[188:191], v[52:55]
	v_mfma_f32_16x16x32_bf16 v[48:51], v[180:183], v[188:191], v[48:51]
	v_mfma_f32_16x16x32_bf16 v[36:39], v[162:165], v[196:199], v[36:39]
	v_mfma_f32_16x16x32_bf16 v[32:35], v[180:183], v[196:199], v[32:35]
	v_mfma_f32_16x16x32_bf16 v[20:23], v[162:165], v[204:207], v[20:23]
	v_mfma_f32_16x16x32_bf16 v[16:19], v[180:183], v[204:207], v[16:19]
	v_mfma_f32_16x16x32_bf16 v[4:7], v[162:165], v[216:219], v[4:7]
	v_mfma_f32_16x16x32_bf16 v[0:3], v[180:183], v[216:219], v[0:3]
	s_setprio 0
	s_barrier
	s_add_i32 s76, 0, 0x18000
	s_add_i32 s77, 0, 0x1c000
	v_add_u32_e32 v140, s76, v175
	v_add_u32_e32 v180, s77, v175
	ds_read_b128 v[128:131], v140
	ds_read_b128 v[132:135], v140 offset:1024
	ds_read_b128 v[136:139], v140 offset:2048
	ds_read_b128 v[140:143], v140 offset:3072
	ds_read_b128 v[158:161], v180
	ds_read_b128 v[162:165], v180 offset:1024
	ds_read_b128 v[166:169], v180 offset:2048
	ds_read_b128 v[180:183], v180 offset:3072
	s_add_u32 s24, s30, 0xb0000
	s_addc_u32 s25, s31, 0
	s_mov_b32 m0, s59
	ds_read_b128 v[184:187], v179 offset:32768
	ds_read_b128 v[188:191], v179 offset:33792
	ds_read_b128 v[192:195], v179 offset:34816
	ds_read_b128 v[196:199], v179 offset:35840
	ds_read_b128 v[200:203], v179 offset:36864
	ds_read_b128 v[204:207], v179 offset:37888
	ds_read_b128 v[208:211], v179 offset:38912
	ds_read_b128 v[216:219], v179 offset:39936
	global_load_lds_dwordx4 v144, s[24:25]
	s_mov_b32 m0, s60
	s_nop 0
	global_load_lds_dwordx4 v148, s[24:25]
	s_waitcnt vmcnt(8)
	s_waitcnt lgkmcnt(0)
	s_barrier
	s_setprio 1
	s_waitcnt lgkmcnt(0)
	v_mfma_f32_16x16x32_bf16 v[124:127], v[128:131], v[184:187], v[124:127]
	v_mfma_f32_16x16x32_bf16 v[120:123], v[136:139], v[184:187], v[120:123]
	v_mfma_f32_16x16x32_bf16 v[108:111], v[128:131], v[192:195], v[108:111]
	v_mfma_f32_16x16x32_bf16 v[104:107], v[136:139], v[192:195], v[104:107]
	v_mfma_f32_16x16x32_bf16 v[92:95], v[128:131], v[200:203], v[92:95]
	v_mfma_f32_16x16x32_bf16 v[88:91], v[136:139], v[200:203], v[88:91]
	v_mfma_f32_16x16x32_bf16 v[76:79], v[128:131], v[208:211], v[76:79]
	v_mfma_f32_16x16x32_bf16 v[72:75], v[136:139], v[208:211], v[72:75]
	v_mfma_f32_16x16x32_bf16 v[124:127], v[132:135], v[188:191], v[124:127]
	v_mfma_f32_16x16x32_bf16 v[120:123], v[140:143], v[188:191], v[120:123]
	v_mfma_f32_16x16x32_bf16 v[108:111], v[132:135], v[196:199], v[108:111]
	v_mfma_f32_16x16x32_bf16 v[104:107], v[140:143], v[196:199], v[104:107]
	v_mfma_f32_16x16x32_bf16 v[92:95], v[132:135], v[204:207], v[92:95]
	v_mfma_f32_16x16x32_bf16 v[88:91], v[140:143], v[204:207], v[88:91]
	v_mfma_f32_16x16x32_bf16 v[76:79], v[132:135], v[216:219], v[76:79]
	v_mfma_f32_16x16x32_bf16 v[72:75], v[140:143], v[216:219], v[72:75]
	s_setprio 0
	s_setprio 1
	v_mfma_f32_16x16x32_bf16 v[116:119], v[158:161], v[184:187], v[116:119]
	v_mfma_f32_16x16x32_bf16 v[112:115], v[166:169], v[184:187], v[112:115]
	v_mfma_f32_16x16x32_bf16 v[100:103], v[158:161], v[192:195], v[100:103]
	v_mfma_f32_16x16x32_bf16 v[96:99], v[166:169], v[192:195], v[96:99]
	v_mfma_f32_16x16x32_bf16 v[84:87], v[158:161], v[200:203], v[84:87]
	v_mfma_f32_16x16x32_bf16 v[80:83], v[166:169], v[200:203], v[80:83]
	v_mfma_f32_16x16x32_bf16 v[68:71], v[158:161], v[208:211], v[68:71]
	v_mfma_f32_16x16x32_bf16 v[64:67], v[166:169], v[208:211], v[64:67]
	v_mfma_f32_16x16x32_bf16 v[116:119], v[162:165], v[188:191], v[116:119]
	v_mfma_f32_16x16x32_bf16 v[112:115], v[180:183], v[188:191], v[112:115]
	v_mfma_f32_16x16x32_bf16 v[100:103], v[162:165], v[196:199], v[100:103]
	v_mfma_f32_16x16x32_bf16 v[96:99], v[180:183], v[196:199], v[96:99]
	v_mfma_f32_16x16x32_bf16 v[84:87], v[162:165], v[204:207], v[84:87]
	v_mfma_f32_16x16x32_bf16 v[80:83], v[180:183], v[204:207], v[80:83]
	v_mfma_f32_16x16x32_bf16 v[68:71], v[162:165], v[216:219], v[68:71]
	v_mfma_f32_16x16x32_bf16 v[64:67], v[180:183], v[216:219], v[64:67]
	s_setprio 0
	s_barrier
	s_add_i32 s24, s76, s56
	s_mov_b32 m0, s24
	ds_read_b128 v[184:187], v179 offset:49152
	ds_read_b128 v[188:191], v179 offset:50176
	ds_read_b128 v[192:195], v179 offset:51200
	ds_read_b128 v[196:199], v179 offset:52224
	ds_read_b128 v[200:203], v179 offset:53248
	ds_read_b128 v[204:207], v179 offset:54272
	ds_read_b128 v[208:211], v179 offset:55296
	ds_read_b128 v[216:219], v179 offset:56320
	global_load_lds_dwordx4 v146, s[98:99]
	s_add_i32 m0, s24, 0x2000
	s_add_u32 s24, s28, 0xb0080
	s_addc_u32 s25, s29, 0
	s_add_i32 s28, s77, s56
	global_load_lds_dwordx4 v150, s[98:99]
	s_mov_b32 m0, s28
	s_nop 0
	global_load_lds_dwordx4 v146, s[24:25]
	s_add_i32 m0, s28, 0x2000
	s_nop 0
	global_load_lds_dwordx4 v150, s[24:25]
	s_mov_b32 m0, s64
	s_nop 0
	global_load_lds_dwordx4 v144, s[100:101]
	s_mov_b32 m0, s65
	s_nop 0
	global_load_lds_dwordx4 v148, s[100:101]
	s_waitcnt vmcnt(8)
	s_waitcnt lgkmcnt(0)
	s_barrier
	s_setprio 1
	s_waitcnt lgkmcnt(0)
	v_mfma_f32_16x16x32_bf16 v[60:63], v[128:131], v[184:187], v[60:63]
	v_mfma_f32_16x16x32_bf16 v[56:59], v[136:139], v[184:187], v[56:59]
	v_mfma_f32_16x16x32_bf16 v[44:47], v[128:131], v[192:195], v[44:47]
	v_mfma_f32_16x16x32_bf16 v[40:43], v[136:139], v[192:195], v[40:43]
	v_mfma_f32_16x16x32_bf16 v[28:31], v[128:131], v[200:203], v[28:31]
	v_mfma_f32_16x16x32_bf16 v[24:27], v[136:139], v[200:203], v[24:27]
	v_mfma_f32_16x16x32_bf16 v[12:15], v[128:131], v[208:211], v[12:15]
	v_mfma_f32_16x16x32_bf16 v[8:11], v[136:139], v[208:211], v[8:11]
	v_mfma_f32_16x16x32_bf16 v[60:63], v[132:135], v[188:191], v[60:63]
	v_mfma_f32_16x16x32_bf16 v[56:59], v[140:143], v[188:191], v[56:59]
	v_mfma_f32_16x16x32_bf16 v[44:47], v[132:135], v[196:199], v[44:47]
	v_mfma_f32_16x16x32_bf16 v[40:43], v[140:143], v[196:199], v[40:43]
	v_mfma_f32_16x16x32_bf16 v[28:31], v[132:135], v[204:207], v[28:31]
	v_mfma_f32_16x16x32_bf16 v[24:27], v[140:143], v[204:207], v[24:27]
	v_mfma_f32_16x16x32_bf16 v[12:15], v[132:135], v[216:219], v[12:15]
	v_mfma_f32_16x16x32_bf16 v[8:11], v[140:143], v[216:219], v[8:11]
	s_setprio 0
	s_setprio 1
	v_mfma_f32_16x16x32_bf16 v[52:55], v[158:161], v[184:187], v[52:55]
	v_mfma_f32_16x16x32_bf16 v[48:51], v[166:169], v[184:187], v[48:51]
	v_mfma_f32_16x16x32_bf16 v[36:39], v[158:161], v[192:195], v[36:39]
	v_mfma_f32_16x16x32_bf16 v[32:35], v[166:169], v[192:195], v[32:35]
	v_mfma_f32_16x16x32_bf16 v[20:23], v[158:161], v[200:203], v[20:23]
	v_mfma_f32_16x16x32_bf16 v[16:19], v[166:169], v[200:203], v[16:19]
	v_mfma_f32_16x16x32_bf16 v[4:7], v[158:161], v[208:211], v[4:7]
	v_mfma_f32_16x16x32_bf16 v[0:3], v[166:169], v[208:211], v[0:3]
	v_mfma_f32_16x16x32_bf16 v[52:55], v[162:165], v[188:191], v[52:55]
	v_mfma_f32_16x16x32_bf16 v[48:51], v[180:183], v[188:191], v[48:51]
	v_mfma_f32_16x16x32_bf16 v[36:39], v[162:165], v[196:199], v[36:39]
	v_mfma_f32_16x16x32_bf16 v[32:35], v[180:183], v[196:199], v[32:35]
	v_mfma_f32_16x16x32_bf16 v[20:23], v[162:165], v[204:207], v[20:23]
	v_mfma_f32_16x16x32_bf16 v[16:19], v[180:183], v[204:207], v[16:19]
	v_mfma_f32_16x16x32_bf16 v[4:7], v[162:165], v[216:219], v[4:7]
	v_mfma_f32_16x16x32_bf16 v[0:3], v[180:183], v[216:219], v[0:3]
	s_setprio 0
	s_barrier
	s_add_i32 s72, s72, 2
	s_add_u32 s12, s12, 0x100
	s_addc_u32 s74, s74, 0
	s_cmp_gt_u32 s72, 41
	s_mov_b64 s[24:25], s[26:27]
	s_cbranch_scc0 .LBB0_658
	s_and_b64 vcc, exec, s[18:19]
	s_cbranch_vccz .LBB0_661
	s_barrier

.LBB0_707:
	ds_read_b128 v[48:51], v196
	ds_read_b128 v[52:55], v196 offset:1024
	ds_read_b128 v[56:59], v196 offset:2048
	ds_read_b128 v[60:63], v196 offset:3072
	ds_read_b128 v[162:165], v197
	ds_read_b128 v[166:169], v197 offset:1024
	ds_read_b128 v[170:173], v197 offset:2048
	ds_read_b128 v[174:177], v197 offset:3072
	s_add_u32 s6, s4, 0xfffc0080
	s_addc_u32 s7, s5, -1
	s_cmp_eq_u32 s56, 12
	s_cselect_b32 s9, s11, s7
	s_cselect_b32 s8, s27, s6
	s_cselect_b32 s7, s25, s55
	s_cselect_b32 s6, s53, s54
	s_add_i32 m0, s63, 0xc000
	ds_read_b128 v[178:181], v198
	ds_read_b128 v[182:185], v198 offset:1024
	ds_read_b128 v[186:189], v198 offset:2048
	ds_read_b128 v[200:203], v198 offset:3072
	ds_read_b128 v[204:207], v198 offset:4096
	ds_read_b128 v[208:211], v198 offset:5120
	ds_read_b128 v[216:219], v198 offset:6144
	ds_read_b128 v[220:223], v198 offset:7168
	global_load_lds_dwordx4 v154, s[4:5]
	s_add_i32 m0, s63, 0xe000
	s_nop 0
	global_load_lds_dwordx4 v156, s[4:5]
	s_waitcnt vmcnt(8)
	s_waitcnt lgkmcnt(0)
	s_barrier
	s_setprio 1
	s_waitcnt lgkmcnt(0)
	v_mfma_f32_16x16x32_bf16 v[140:143], v[48:51], v[178:181], v[140:143]
	v_mfma_f32_16x16x32_bf16 v[136:139], v[56:59], v[178:181], v[136:139]
	v_mfma_f32_16x16x32_bf16 v[124:127], v[48:51], v[186:189], v[124:127]
	v_mfma_f32_16x16x32_bf16 v[120:123], v[56:59], v[186:189], v[120:123]
	v_mfma_f32_16x16x32_bf16 v[108:111], v[48:51], v[204:207], v[108:111]
	v_mfma_f32_16x16x32_bf16 v[104:107], v[56:59], v[204:207], v[104:107]
	v_mfma_f32_16x16x32_bf16 v[92:95], v[48:51], v[216:219], v[92:95]
	v_mfma_f32_16x16x32_bf16 v[88:91], v[56:59], v[216:219], v[88:91]
	v_mfma_f32_16x16x32_bf16 v[140:143], v[52:55], v[182:185], v[140:143]
	v_mfma_f32_16x16x32_bf16 v[136:139], v[60:63], v[182:185], v[136:139]
	v_mfma_f32_16x16x32_bf16 v[124:127], v[52:55], v[200:203], v[124:127]
	v_mfma_f32_16x16x32_bf16 v[120:123], v[60:63], v[200:203], v[120:123]
	v_mfma_f32_16x16x32_bf16 v[108:111], v[52:55], v[208:211], v[108:111]
	v_mfma_f32_16x16x32_bf16 v[104:107], v[60:63], v[208:211], v[104:107]
	v_mfma_f32_16x16x32_bf16 v[92:95], v[52:55], v[220:223], v[92:95]
	v_mfma_f32_16x16x32_bf16 v[88:91], v[60:63], v[220:223], v[88:91]
	s_setprio 0
	s_setprio 1
	v_mfma_f32_16x16x32_bf16 v[132:135], v[162:165], v[178:181], v[132:135]
	v_mfma_f32_16x16x32_bf16 v[128:131], v[170:173], v[178:181], v[128:131]
	v_mfma_f32_16x16x32_bf16 v[116:119], v[162:165], v[186:189], v[116:119]
	v_mfma_f32_16x16x32_bf16 v[112:115], v[170:173], v[186:189], v[112:115]
	v_mfma_f32_16x16x32_bf16 v[100:103], v[162:165], v[204:207], v[100:103]
	v_mfma_f32_16x16x32_bf16 v[96:99], v[170:173], v[204:207], v[96:99]
	v_mfma_f32_16x16x32_bf16 v[84:87], v[162:165], v[216:219], v[84:87]
	v_mfma_f32_16x16x32_bf16 v[80:83], v[170:173], v[216:219], v[80:83]
	v_mfma_f32_16x16x32_bf16 v[132:135], v[166:169], v[182:185], v[132:135]
	v_mfma_f32_16x16x32_bf16 v[128:131], v[174:177], v[182:185], v[128:131]
	v_mfma_f32_16x16x32_bf16 v[116:119], v[166:169], v[200:203], v[116:119]
	v_mfma_f32_16x16x32_bf16 v[112:115], v[174:177], v[200:203], v[112:115]
	v_mfma_f32_16x16x32_bf16 v[100:103], v[166:169], v[208:211], v[100:103]
	v_mfma_f32_16x16x32_bf16 v[96:99], v[174:177], v[208:211], v[96:99]
	v_mfma_f32_16x16x32_bf16 v[84:87], v[166:169], v[220:223], v[84:87]
	v_mfma_f32_16x16x32_bf16 v[80:83], v[174:177], v[220:223], v[80:83]
	s_setprio 0
	s_barrier
	s_add_u32 s98, s6, 0x80
	s_addc_u32 s99, s7, 0
	s_add_u32 s100, s8, 0x80
	s_addc_u32 s101, s9, 0
	s_add_i32 s57, s87, s62
	s_mov_b32 m0, s57
	ds_read_b128 v[178:181], v198 offset:16384
	ds_read_b128 v[182:185], v198 offset:17408
	ds_read_b128 v[186:189], v198 offset:18432
	ds_read_b128 v[200:203], v198 offset:19456
	ds_read_b128 v[204:207], v198 offset:20480
	ds_read_b128 v[208:211], v198 offset:21504
	ds_read_b128 v[216:219], v198 offset:22528
	ds_read_b128 v[220:223], v198 offset:23552
	global_load_lds_dwordx4 v144, s[6:7]
	s_add_i32 m0, s57, 0x2000
	s_add_u32 s58, s6, 0x40000
	s_addc_u32 s59, s7, 0
	s_add_i32 s57, s88, s62
	global_load_lds_dwordx4 v146, s[6:7]
	s_mov_b32 m0, s57
	s_nop 0
	global_load_lds_dwordx4 v144, s[58:59]
	s_add_i32 m0, s57, 0x2000
	s_nop 0
	global_load_lds_dwordx4 v146, s[58:59]
	s_mov_b32 m0, s63
	s_nop 0
	global_load_lds_dwordx4 v144, s[8:9]
	s_mov_b32 m0, s64
	s_nop 0
	global_load_lds_dwordx4 v146, s[8:9]
	s_waitcnt vmcnt(8)
	s_waitcnt lgkmcnt(0)
	s_barrier
	s_setprio 1
	s_waitcnt lgkmcnt(0)
	v_mfma_f32_16x16x32_bf16 v[76:79], v[48:51], v[178:181], v[76:79]
	v_mfma_f32_16x16x32_bf16 v[72:75], v[56:59], v[178:181], v[72:75]
	v_mfma_f32_16x16x32_bf16 v[44:47], v[48:51], v[186:189], v[44:47]
	v_mfma_f32_16x16x32_bf16 v[40:43], v[56:59], v[186:189], v[40:43]
	v_mfma_f32_16x16x32_bf16 v[28:31], v[48:51], v[204:207], v[28:31]
	v_mfma_f32_16x16x32_bf16 v[24:27], v[56:59], v[204:207], v[24:27]
	v_mfma_f32_16x16x32_bf16 v[12:15], v[48:51], v[216:219], v[12:15]
	v_mfma_f32_16x16x32_bf16 v[8:11], v[56:59], v[216:219], v[8:11]
	v_mfma_f32_16x16x32_bf16 v[76:79], v[52:55], v[182:185], v[76:79]
	v_mfma_f32_16x16x32_bf16 v[72:75], v[60:63], v[182:185], v[72:75]
	v_mfma_f32_16x16x32_bf16 v[44:47], v[52:55], v[200:203], v[44:47]
	v_mfma_f32_16x16x32_bf16 v[40:43], v[60:63], v[200:203], v[40:43]
	v_mfma_f32_16x16x32_bf16 v[28:31], v[52:55], v[208:211], v[28:31]
	v_mfma_f32_16x16x32_bf16 v[24:27], v[60:63], v[208:211], v[24:27]
	v_mfma_f32_16x16x32_bf16 v[12:15], v[52:55], v[220:223], v[12:15]
	v_mfma_f32_16x16x32_bf16 v[8:11], v[60:63], v[220:223], v[8:11]
	s_setprio 0
	s_setprio 1
	v_mfma_f32_16x16x32_bf16 v[36:39], v[162:165], v[186:189], v[36:39]
	v_mfma_f32_16x16x32_bf16 v[32:35], v[170:173], v[186:189], v[32:35]
	v_mfma_f32_16x16x32_bf16 v[20:23], v[162:165], v[204:207], v[20:23]
	v_mfma_f32_16x16x32_bf16 v[16:19], v[170:173], v[204:207], v[16:19]
	v_mfma_f32_16x16x32_bf16 v[4:7], v[162:165], v[216:219], v[4:7]
	v_mfma_f32_16x16x32_bf16 v[0:3], v[170:173], v[216:219], v[0:3]
	v_mfma_f32_16x16x32_bf16 v[48:51], v[162:165], v[178:181], v[68:71]
	v_mfma_f32_16x16x32_bf16 v[52:55], v[170:173], v[178:181], v[64:67]
	v_mfma_f32_16x16x32_bf16 v[36:39], v[166:169], v[200:203], v[36:39]
	v_mfma_f32_16x16x32_bf16 v[32:35], v[174:177], v[200:203], v[32:35]
	v_mfma_f32_16x16x32_bf16 v[20:23], v[166:169], v[208:211], v[20:23]
	v_mfma_f32_16x16x32_bf16 v[16:19], v[174:177], v[208:211], v[16:19]
	v_mfma_f32_16x16x32_bf16 v[4:7], v[166:169], v[220:223], v[4:7]
	v_mfma_f32_16x16x32_bf16 v[0:3], v[174:177], v[220:223], v[0:3]
	v_mfma_f32_16x16x32_bf16 v[48:51], v[166:169], v[182:185], v[48:51]
	v_mfma_f32_16x16x32_bf16 v[52:55], v[174:177], v[182:185], v[52:55]
	s_setprio 0
	s_barrier
	s_add_i32 s57, 0, 0x18000
	s_add_i32 s58, 0, 0x1c000
	v_add_u32_e32 v68, s57, v193
	v_add_u32_e32 v174, s58, v193
	ds_read_b128 v[56:59], v68
	ds_read_b128 v[60:63], v68 offset:1024
	ds_read_b128 v[64:67], v68 offset:2048
	ds_read_b128 v[68:71], v68 offset:3072
	ds_read_b128 v[162:165], v174
	ds_read_b128 v[166:169], v174 offset:1024
	ds_read_b128 v[170:173], v174 offset:2048
	ds_read_b128 v[174:177], v174 offset:3072
	s_add_u32 s8, s8, 0x40000
	s_addc_u32 s9, s9, 0
	s_mov_b32 m0, s65
	ds_read_b128 v[178:181], v198 offset:32768
	ds_read_b128 v[182:185], v198 offset:33792
	ds_read_b128 v[186:189], v198 offset:34816
	ds_read_b128 v[200:203], v198 offset:35840
	ds_read_b128 v[204:207], v198 offset:36864
	ds_read_b128 v[208:211], v198 offset:37888
	ds_read_b128 v[216:219], v198 offset:38912
	ds_read_b128 v[220:223], v198 offset:39936
	global_load_lds_dwordx4 v144, s[8:9]
	s_mov_b32 m0, s66
	s_nop 0
	global_load_lds_dwordx4 v146, s[8:9]
	s_waitcnt vmcnt(8)
	s_waitcnt lgkmcnt(0)
	s_barrier
	s_setprio 1
	s_waitcnt lgkmcnt(0)
	v_mfma_f32_16x16x32_bf16 v[140:143], v[56:59], v[178:181], v[140:143]
	v_mfma_f32_16x16x32_bf16 v[136:139], v[64:67], v[178:181], v[136:139]
	v_mfma_f32_16x16x32_bf16 v[124:127], v[56:59], v[186:189], v[124:127]
	v_mfma_f32_16x16x32_bf16 v[120:123], v[64:67], v[186:189], v[120:123]
	v_mfma_f32_16x16x32_bf16 v[108:111], v[56:59], v[204:207], v[108:111]
	v_mfma_f32_16x16x32_bf16 v[104:107], v[64:67], v[204:207], v[104:107]
	v_mfma_f32_16x16x32_bf16 v[92:95], v[56:59], v[216:219], v[92:95]
	v_mfma_f32_16x16x32_bf16 v[88:91], v[64:67], v[216:219], v[88:91]
	v_mfma_f32_16x16x32_bf16 v[140:143], v[60:63], v[182:185], v[140:143]
	v_mfma_f32_16x16x32_bf16 v[136:139], v[68:71], v[182:185], v[136:139]
	v_mfma_f32_16x16x32_bf16 v[124:127], v[60:63], v[200:203], v[124:127]
	v_mfma_f32_16x16x32_bf16 v[120:123], v[68:71], v[200:203], v[120:123]
	v_mfma_f32_16x16x32_bf16 v[108:111], v[60:63], v[208:211], v[108:111]
	v_mfma_f32_16x16x32_bf16 v[104:107], v[68:71], v[208:211], v[104:107]
	v_mfma_f32_16x16x32_bf16 v[92:95], v[60:63], v[220:223], v[92:95]
	v_mfma_f32_16x16x32_bf16 v[88:91], v[68:71], v[220:223], v[88:91]
	s_setprio 0
	s_setprio 1
	v_mfma_f32_16x16x32_bf16 v[132:135], v[162:165], v[178:181], v[132:135]
	v_mfma_f32_16x16x32_bf16 v[128:131], v[170:173], v[178:181], v[128:131]
	v_mfma_f32_16x16x32_bf16 v[116:119], v[162:165], v[186:189], v[116:119]
	v_mfma_f32_16x16x32_bf16 v[112:115], v[170:173], v[186:189], v[112:115]
	v_mfma_f32_16x16x32_bf16 v[100:103], v[162:165], v[204:207], v[100:103]
	v_mfma_f32_16x16x32_bf16 v[96:99], v[170:173], v[204:207], v[96:99]
	v_mfma_f32_16x16x32_bf16 v[84:87], v[162:165], v[216:219], v[84:87]
	v_mfma_f32_16x16x32_bf16 v[80:83], v[170:173], v[216:219], v[80:83]
	v_mfma_f32_16x16x32_bf16 v[132:135], v[166:169], v[182:185], v[132:135]
	v_mfma_f32_16x16x32_bf16 v[128:131], v[174:177], v[182:185], v[128:131]
	v_mfma_f32_16x16x32_bf16 v[116:119], v[166:169], v[200:203], v[116:119]
	v_mfma_f32_16x16x32_bf16 v[112:115], v[174:177], v[200:203], v[112:115]
	v_mfma_f32_16x16x32_bf16 v[100:103], v[166:169], v[208:211], v[100:103]
	v_mfma_f32_16x16x32_bf16 v[96:99], v[174:177], v[208:211], v[96:99]
	v_mfma_f32_16x16x32_bf16 v[84:87], v[166:169], v[220:223], v[84:87]
	v_mfma_f32_16x16x32_bf16 v[80:83], v[174:177], v[220:223], v[80:83]
	s_setprio 0
	s_barrier
	s_add_i32 s8, s57, s62
	s_mov_b32 m0, s8
	ds_read_b128 v[178:181], v198 offset:49152
	ds_read_b128 v[182:185], v198 offset:50176
	ds_read_b128 v[186:189], v198 offset:51200
	ds_read_b128 v[200:203], v198 offset:52224
	ds_read_b128 v[204:207], v198 offset:53248
	ds_read_b128 v[208:211], v198 offset:54272
	ds_read_b128 v[216:219], v198 offset:55296
	ds_read_b128 v[220:223], v198 offset:56320
	global_load_lds_dwordx4 v144, s[98:99]
	s_add_i32 m0, s8, 0x2000
	s_add_u32 s6, s6, 0x40080
	s_addc_u32 s7, s7, 0
	s_add_i32 s8, s58, s62
	global_load_lds_dwordx4 v146, s[98:99]
	s_mov_b32 m0, s8
	s_nop 0
	global_load_lds_dwordx4 v144, s[6:7]
	s_add_i32 m0, s8, 0x2000
	s_nop 0
	global_load_lds_dwordx4 v146, s[6:7]
	s_mov_b32 m0, s81
	s_nop 0
	global_load_lds_dwordx4 v144, s[100:101]
	s_mov_b32 m0, s82
	s_nop 0
	global_load_lds_dwordx4 v146, s[100:101]
	s_waitcnt vmcnt(8)
	s_waitcnt lgkmcnt(0)
	s_barrier
	s_setprio 1
	s_waitcnt lgkmcnt(0)
	v_mfma_f32_16x16x32_bf16 v[76:79], v[56:59], v[178:181], v[76:79]
	v_mfma_f32_16x16x32_bf16 v[72:75], v[64:67], v[178:181], v[72:75]
	v_mfma_f32_16x16x32_bf16 v[44:47], v[56:59], v[186:189], v[44:47]
	v_mfma_f32_16x16x32_bf16 v[40:43], v[64:67], v[186:189], v[40:43]
	v_mfma_f32_16x16x32_bf16 v[28:31], v[56:59], v[204:207], v[28:31]
	v_mfma_f32_16x16x32_bf16 v[24:27], v[64:67], v[204:207], v[24:27]
	v_mfma_f32_16x16x32_bf16 v[12:15], v[56:59], v[216:219], v[12:15]
	v_mfma_f32_16x16x32_bf16 v[8:11], v[64:67], v[216:219], v[8:11]
	v_mfma_f32_16x16x32_bf16 v[76:79], v[60:63], v[182:185], v[76:79]
	v_mfma_f32_16x16x32_bf16 v[72:75], v[68:71], v[182:185], v[72:75]
	v_mfma_f32_16x16x32_bf16 v[44:47], v[60:63], v[200:203], v[44:47]
	v_mfma_f32_16x16x32_bf16 v[40:43], v[68:71], v[200:203], v[40:43]
	v_mfma_f32_16x16x32_bf16 v[28:31], v[60:63], v[208:211], v[28:31]
	v_mfma_f32_16x16x32_bf16 v[24:27], v[68:71], v[208:211], v[24:27]
	v_mfma_f32_16x16x32_bf16 v[12:15], v[60:63], v[220:223], v[12:15]
	v_mfma_f32_16x16x32_bf16 v[8:11], v[68:71], v[220:223], v[8:11]
	s_setprio 0
	s_setprio 1
	v_mfma_f32_16x16x32_bf16 v[48:51], v[162:165], v[178:181], v[48:51]
	v_mfma_f32_16x16x32_bf16 v[68:71], v[166:169], v[182:185], v[48:51]
	v_mfma_f32_16x16x32_bf16 v[48:51], v[170:173], v[178:181], v[52:55]
	v_mfma_f32_16x16x32_bf16 v[36:39], v[162:165], v[186:189], v[36:39]
	v_mfma_f32_16x16x32_bf16 v[32:35], v[170:173], v[186:189], v[32:35]
	v_mfma_f32_16x16x32_bf16 v[20:23], v[162:165], v[204:207], v[20:23]
	v_mfma_f32_16x16x32_bf16 v[16:19], v[170:173], v[204:207], v[16:19]
	v_mfma_f32_16x16x32_bf16 v[4:7], v[162:165], v[216:219], v[4:7]
	v_mfma_f32_16x16x32_bf16 v[0:3], v[170:173], v[216:219], v[0:3]
	v_mfma_f32_16x16x32_bf16 v[64:67], v[174:177], v[182:185], v[48:51]
	v_mfma_f32_16x16x32_bf16 v[36:39], v[166:169], v[200:203], v[36:39]
	v_mfma_f32_16x16x32_bf16 v[32:35], v[174:177], v[200:203], v[32:35]
	v_mfma_f32_16x16x32_bf16 v[20:23], v[166:169], v[208:211], v[20:23]
	v_mfma_f32_16x16x32_bf16 v[16:19], v[174:177], v[208:211], v[16:19]
	v_mfma_f32_16x16x32_bf16 v[4:7], v[166:169], v[220:223], v[4:7]
	v_mfma_f32_16x16x32_bf16 v[0:3], v[174:177], v[220:223], v[0:3]
	s_setprio 0
	s_barrier
	s_add_i32 s56, s56, 2
	s_add_u32 s4, s4, 0x100
	s_addc_u32 s5, s5, 0
	s_add_u32 s54, s54, 0x100
	s_addc_u32 s55, s55, 0
	s_cmp_gt_u32 s56, 13
	s_cbranch_scc0 .LBB0_707
	s_and_b64 vcc, exec, s[22:23]
	s_cbranch_vccz .LBB0_710
	s_barrier

.LBB0_950:
	s_add_u32 s54, s94, s52
	s_addc_u32 s55, s95, s53
	s_add_u32 s54, s54, 0x14d00100
	s_addc_u32 s55, s55, 0
	s_add_u32 s60, s96, s52
	s_addc_u32 s61, s97, s53
	s_add_i32 vcc_hi, 0, 0x10000
	s_cmpk_eq_i32 s52, 0x700
	s_cselect_b32 s57, s7, s55
	s_cselect_b32 s56, s6, s54
	v_add_u32_e32 v141, vcc_hi, v133
	s_cselect_b32 s55, s5, s61
	s_cselect_b32 s54, s4, s60
	s_add_i32 s78, 0, 0x14000
	ds_read_b128 v[142:145], v141
	ds_read_b128 v[146:149], v141 offset:1024
	ds_read_b128 v[150:153], v141 offset:2048
	ds_read_b128 v[154:157], v141 offset:3072
	v_add_u32_e32 v141, s78, v133
	ds_read_b128 v[158:161], v141
	ds_read_b128 v[162:165], v141 offset:1024
	ds_read_b128 v[166:169], v141 offset:2048
	ds_read_b128 v[170:173], v141 offset:3072
	v_lshl_add_u64 v[186:187], v[134:135], 0, s[52:53]
	s_add_i32 m0, s87, 0xc000
	ds_read_b128 v[174:177], v140
	ds_read_b128 v[178:181], v140 offset:1024
	ds_read_b128 v[182:185], v140 offset:2048
	ds_read_b128 v[190:193], v140 offset:3072
	ds_read_b128 v[206:209], v140 offset:4096
	ds_read_b128 v[210:213], v140 offset:5120
	ds_read_b128 v[216:219], v140 offset:6144
	ds_read_b128 v[220:223], v140 offset:7168
	global_load_lds_dwordx4 v[186:187], off
	v_lshl_add_u64 v[186:187], v[136:137], 0, s[52:53]
	s_add_i32 m0, s87, 0xe000
	s_nop 0
	global_load_lds_dwordx4 v[186:187], off
	s_waitcnt vmcnt(8)
	s_waitcnt lgkmcnt(0)
	s_barrier
	s_setprio 1
	s_waitcnt lgkmcnt(0)
	v_mfma_f32_16x16x32_bf16 v[126:129], v[142:145], v[174:177], v[126:129]
	v_mfma_f32_16x16x32_bf16 v[122:125], v[150:153], v[174:177], v[122:125]
	v_mfma_f32_16x16x32_bf16 v[110:113], v[142:145], v[182:185], v[110:113]
	v_mfma_f32_16x16x32_bf16 v[106:109], v[150:153], v[182:185], v[106:109]
	v_mfma_f32_16x16x32_bf16 v[94:97], v[142:145], v[206:209], v[94:97]
	v_mfma_f32_16x16x32_bf16 v[90:93], v[150:153], v[206:209], v[90:93]
	v_mfma_f32_16x16x32_bf16 v[78:81], v[142:145], v[216:219], v[78:81]
	v_mfma_f32_16x16x32_bf16 v[74:77], v[150:153], v[216:219], v[74:77]
	v_mfma_f32_16x16x32_bf16 v[126:129], v[146:149], v[178:181], v[126:129]
	v_mfma_f32_16x16x32_bf16 v[122:125], v[154:157], v[178:181], v[122:125]
	v_mfma_f32_16x16x32_bf16 v[110:113], v[146:149], v[190:193], v[110:113]
	v_mfma_f32_16x16x32_bf16 v[106:109], v[154:157], v[190:193], v[106:109]
	v_mfma_f32_16x16x32_bf16 v[94:97], v[146:149], v[210:213], v[94:97]
	v_mfma_f32_16x16x32_bf16 v[90:93], v[154:157], v[210:213], v[90:93]
	v_mfma_f32_16x16x32_bf16 v[78:81], v[146:149], v[220:223], v[78:81]
	v_mfma_f32_16x16x32_bf16 v[74:77], v[154:157], v[220:223], v[74:77]
	s_setprio 0
	s_setprio 1
	v_mfma_f32_16x16x32_bf16 v[118:121], v[158:161], v[174:177], v[118:121]
	v_mfma_f32_16x16x32_bf16 v[114:117], v[166:169], v[174:177], v[114:117]
	v_mfma_f32_16x16x32_bf16 v[102:105], v[158:161], v[182:185], v[102:105]
	v_mfma_f32_16x16x32_bf16 v[98:101], v[166:169], v[182:185], v[98:101]
	v_mfma_f32_16x16x32_bf16 v[86:89], v[158:161], v[206:209], v[86:89]
	v_mfma_f32_16x16x32_bf16 v[82:85], v[166:169], v[206:209], v[82:85]
	v_mfma_f32_16x16x32_bf16 v[70:73], v[158:161], v[216:219], v[70:73]
	v_mfma_f32_16x16x32_bf16 v[66:69], v[166:169], v[216:219], v[66:69]
	v_mfma_f32_16x16x32_bf16 v[118:121], v[162:165], v[178:181], v[118:121]
	v_mfma_f32_16x16x32_bf16 v[114:117], v[170:173], v[178:181], v[114:117]
	v_mfma_f32_16x16x32_bf16 v[102:105], v[162:165], v[190:193], v[102:105]
	v_mfma_f32_16x16x32_bf16 v[98:101], v[170:173], v[190:193], v[98:101]
	v_mfma_f32_16x16x32_bf16 v[86:89], v[162:165], v[210:213], v[86:89]
	v_mfma_f32_16x16x32_bf16 v[82:85], v[170:173], v[210:213], v[82:85]
	v_mfma_f32_16x16x32_bf16 v[70:73], v[162:165], v[220:223], v[70:73]
	v_mfma_f32_16x16x32_bf16 v[66:69], v[170:173], v[220:223], v[66:69]
	s_setprio 0
	s_barrier
	s_add_u32 s98, s54, 0x80
	s_addc_u32 s99, s55, 0
	s_add_u32 s100, s56, 0x80
	s_addc_u32 s101, s57, 0
	s_add_i32 s60, vcc_hi, s86
	s_mov_b32 m0, s60
	ds_read_b128 v[174:177], v140 offset:16384
	ds_read_b128 v[178:181], v140 offset:17408
	ds_read_b128 v[182:185], v140 offset:18432
	ds_read_b128 v[190:193], v140 offset:19456
	ds_read_b128 v[206:209], v140 offset:20480
	ds_read_b128 v[210:213], v140 offset:21504
	ds_read_b128 v[216:219], v140 offset:22528
	ds_read_b128 v[220:223], v140 offset:23552
	global_load_lds_dwordx4 v0, s[54:55]
	s_add_i32 m0, s60, 0x2000
	s_add_u32 s60, s54, 0x40000
	s_addc_u32 s61, s55, 0
	s_add_i32 s78, s78, s86
	global_load_lds_dwordx4 v130, s[54:55]
	s_mov_b32 m0, s78
	s_nop 0
	global_load_lds_dwordx4 v0, s[60:61]
	s_add_i32 m0, s78, 0x2000
	s_nop 0
	global_load_lds_dwordx4 v130, s[60:61]
	s_mov_b32 m0, s87
	s_nop 0
	global_load_lds_dwordx4 v0, s[56:57]
	s_mov_b32 m0, s88
	s_nop 0
	global_load_lds_dwordx4 v130, s[56:57]
	s_waitcnt vmcnt(8)
	s_waitcnt lgkmcnt(0)
	s_barrier
	s_setprio 1
	s_waitcnt lgkmcnt(0)
	v_mfma_f32_16x16x32_bf16 v[62:65], v[142:145], v[174:177], v[62:65]
	v_mfma_f32_16x16x32_bf16 v[58:61], v[150:153], v[174:177], v[58:61]
	v_mfma_f32_16x16x32_bf16 v[46:49], v[142:145], v[182:185], v[46:49]
	v_mfma_f32_16x16x32_bf16 v[42:45], v[150:153], v[182:185], v[42:45]
	v_mfma_f32_16x16x32_bf16 v[30:33], v[142:145], v[206:209], v[30:33]
	v_mfma_f32_16x16x32_bf16 v[26:29], v[150:153], v[206:209], v[26:29]
	v_mfma_f32_16x16x32_bf16 v[14:17], v[142:145], v[216:219], v[14:17]
	v_mfma_f32_16x16x32_bf16 v[10:13], v[150:153], v[216:219], v[10:13]
	v_mfma_f32_16x16x32_bf16 v[62:65], v[146:149], v[178:181], v[62:65]
	v_mfma_f32_16x16x32_bf16 v[58:61], v[154:157], v[178:181], v[58:61]
	v_mfma_f32_16x16x32_bf16 v[46:49], v[146:149], v[190:193], v[46:49]
	v_mfma_f32_16x16x32_bf16 v[42:45], v[154:157], v[190:193], v[42:45]
	v_mfma_f32_16x16x32_bf16 v[30:33], v[146:149], v[210:213], v[30:33]
	v_mfma_f32_16x16x32_bf16 v[26:29], v[154:157], v[210:213], v[26:29]
	v_mfma_f32_16x16x32_bf16 v[14:17], v[146:149], v[220:223], v[14:17]
	v_mfma_f32_16x16x32_bf16 v[10:13], v[154:157], v[220:223], v[10:13]
	s_setprio 0
	s_setprio 1
	v_mfma_f32_16x16x32_bf16 v[54:57], v[158:161], v[174:177], v[54:57]
	v_mfma_f32_16x16x32_bf16 v[50:53], v[166:169], v[174:177], v[50:53]
	v_mfma_f32_16x16x32_bf16 v[38:41], v[158:161], v[182:185], v[38:41]
	v_mfma_f32_16x16x32_bf16 v[34:37], v[166:169], v[182:185], v[34:37]
	v_mfma_f32_16x16x32_bf16 v[22:25], v[158:161], v[206:209], v[22:25]
	v_mfma_f32_16x16x32_bf16 v[18:21], v[166:169], v[206:209], v[18:21]
	v_mfma_f32_16x16x32_bf16 v[6:9], v[158:161], v[216:219], v[6:9]
	v_mfma_f32_16x16x32_bf16 v[2:5], v[166:169], v[216:219], v[2:5]
	v_mfma_f32_16x16x32_bf16 v[54:57], v[162:165], v[178:181], v[54:57]
	v_mfma_f32_16x16x32_bf16 v[50:53], v[170:173], v[178:181], v[50:53]
	v_mfma_f32_16x16x32_bf16 v[38:41], v[162:165], v[190:193], v[38:41]
	v_mfma_f32_16x16x32_bf16 v[34:37], v[170:173], v[190:193], v[34:37]
	v_mfma_f32_16x16x32_bf16 v[22:25], v[162:165], v[210:213], v[22:25]
	v_mfma_f32_16x16x32_bf16 v[18:21], v[170:173], v[210:213], v[18:21]
	v_mfma_f32_16x16x32_bf16 v[6:9], v[162:165], v[220:223], v[6:9]
	v_mfma_f32_16x16x32_bf16 v[2:5], v[170:173], v[220:223], v[2:5]
	s_setprio 0
	s_barrier
	s_add_i32 s60, 0, 0x18000
	v_add_u32_e32 v141, s60, v133
	s_add_i32 s61, 0, 0x1c000
	ds_read_b128 v[142:145], v141
	ds_read_b128 v[146:149], v141 offset:1024
	ds_read_b128 v[150:153], v141 offset:2048
	ds_read_b128 v[154:157], v141 offset:3072
	v_add_u32_e32 v141, s61, v133
	ds_read_b128 v[158:161], v141
	ds_read_b128 v[162:165], v141 offset:1024
	ds_read_b128 v[166:169], v141 offset:2048
	ds_read_b128 v[170:173], v141 offset:3072
	s_add_u32 s56, s56, 0x40000
	s_addc_u32 s57, s57, 0
	s_mov_b32 m0, s89
	ds_read_b128 v[174:177], v140 offset:32768
	ds_read_b128 v[178:181], v140 offset:33792
	ds_read_b128 v[182:185], v140 offset:34816
	ds_read_b128 v[190:193], v140 offset:35840
	ds_read_b128 v[206:209], v140 offset:36864
	ds_read_b128 v[210:213], v140 offset:37888
	ds_read_b128 v[216:219], v140 offset:38912
	ds_read_b128 v[220:223], v140 offset:39936
	global_load_lds_dwordx4 v0, s[56:57]
	s_mov_b32 m0, s90
	s_nop 0
	global_load_lds_dwordx4 v130, s[56:57]
	s_waitcnt vmcnt(8)
	s_waitcnt lgkmcnt(0)
	s_barrier
	s_setprio 1
	s_waitcnt lgkmcnt(0)
	v_mfma_f32_16x16x32_bf16 v[126:129], v[142:145], v[174:177], v[126:129]
	v_mfma_f32_16x16x32_bf16 v[122:125], v[150:153], v[174:177], v[122:125]
	v_mfma_f32_16x16x32_bf16 v[110:113], v[142:145], v[182:185], v[110:113]
	v_mfma_f32_16x16x32_bf16 v[106:109], v[150:153], v[182:185], v[106:109]
	v_mfma_f32_16x16x32_bf16 v[94:97], v[142:145], v[206:209], v[94:97]
	v_mfma_f32_16x16x32_bf16 v[90:93], v[150:153], v[206:209], v[90:93]
	v_mfma_f32_16x16x32_bf16 v[78:81], v[142:145], v[216:219], v[78:81]
	v_mfma_f32_16x16x32_bf16 v[74:77], v[150:153], v[216:219], v[74:77]
	v_mfma_f32_16x16x32_bf16 v[126:129], v[146:149], v[178:181], v[126:129]
	v_mfma_f32_16x16x32_bf16 v[122:125], v[154:157], v[178:181], v[122:125]
	v_mfma_f32_16x16x32_bf16 v[110:113], v[146:149], v[190:193], v[110:113]
	v_mfma_f32_16x16x32_bf16 v[106:109], v[154:157], v[190:193], v[106:109]
	v_mfma_f32_16x16x32_bf16 v[94:97], v[146:149], v[210:213], v[94:97]
	v_mfma_f32_16x16x32_bf16 v[90:93], v[154:157], v[210:213], v[90:93]
	v_mfma_f32_16x16x32_bf16 v[78:81], v[146:149], v[220:223], v[78:81]
	v_mfma_f32_16x16x32_bf16 v[74:77], v[154:157], v[220:223], v[74:77]
	s_setprio 0
	s_setprio 1
	v_mfma_f32_16x16x32_bf16 v[118:121], v[158:161], v[174:177], v[118:121]
	v_mfma_f32_16x16x32_bf16 v[114:117], v[166:169], v[174:177], v[114:117]
	v_mfma_f32_16x16x32_bf16 v[102:105], v[158:161], v[182:185], v[102:105]
	v_mfma_f32_16x16x32_bf16 v[98:101], v[166:169], v[182:185], v[98:101]
	v_mfma_f32_16x16x32_bf16 v[86:89], v[158:161], v[206:209], v[86:89]
	v_mfma_f32_16x16x32_bf16 v[82:85], v[166:169], v[206:209], v[82:85]
	v_mfma_f32_16x16x32_bf16 v[70:73], v[158:161], v[216:219], v[70:73]
	v_mfma_f32_16x16x32_bf16 v[66:69], v[166:169], v[216:219], v[66:69]
	v_mfma_f32_16x16x32_bf16 v[118:121], v[162:165], v[178:181], v[118:121]
	v_mfma_f32_16x16x32_bf16 v[114:117], v[170:173], v[178:181], v[114:117]
	v_mfma_f32_16x16x32_bf16 v[102:105], v[162:165], v[190:193], v[102:105]
	v_mfma_f32_16x16x32_bf16 v[98:101], v[170:173], v[190:193], v[98:101]
	v_mfma_f32_16x16x32_bf16 v[86:89], v[162:165], v[210:213], v[86:89]
	v_mfma_f32_16x16x32_bf16 v[82:85], v[170:173], v[210:213], v[82:85]
	v_mfma_f32_16x16x32_bf16 v[70:73], v[162:165], v[220:223], v[70:73]
	v_mfma_f32_16x16x32_bf16 v[66:69], v[170:173], v[220:223], v[66:69]
	s_setprio 0
	s_barrier
	s_add_i32 s56, s60, s86
	s_mov_b32 m0, s56
	ds_read_b128 v[174:177], v140 offset:49152
	ds_read_b128 v[178:181], v140 offset:50176
	ds_read_b128 v[182:185], v140 offset:51200
	ds_read_b128 v[190:193], v140 offset:52224
	ds_read_b128 v[206:209], v140 offset:53248
	ds_read_b128 v[210:213], v140 offset:54272
	ds_read_b128 v[216:219], v140 offset:55296
	ds_read_b128 v[220:223], v140 offset:56320
	global_load_lds_dwordx4 v0, s[98:99]
	s_add_i32 m0, s56, 0x2000
	s_add_u32 s54, s54, 0x40080
	s_addc_u32 s55, s55, 0
	s_add_i32 s56, s61, s86
	global_load_lds_dwordx4 v130, s[98:99]
	s_mov_b32 m0, s56
	s_nop 0
	global_load_lds_dwordx4 v0, s[54:55]
	s_add_i32 m0, s56, 0x2000
	s_nop 0
	global_load_lds_dwordx4 v130, s[54:55]
	s_mov_b32 m0, s92
	s_nop 0
	global_load_lds_dwordx4 v0, s[100:101]
	s_mov_b32 m0, s93
	s_nop 0
	global_load_lds_dwordx4 v130, s[100:101]
	s_waitcnt vmcnt(8)
	s_waitcnt lgkmcnt(0)
	s_barrier
	s_setprio 1
	s_waitcnt lgkmcnt(0)
	v_mfma_f32_16x16x32_bf16 v[62:65], v[142:145], v[174:177], v[62:65]
	v_mfma_f32_16x16x32_bf16 v[58:61], v[150:153], v[174:177], v[58:61]
	v_mfma_f32_16x16x32_bf16 v[46:49], v[142:145], v[182:185], v[46:49]
	v_mfma_f32_16x16x32_bf16 v[42:45], v[150:153], v[182:185], v[42:45]
	v_mfma_f32_16x16x32_bf16 v[30:33], v[142:145], v[206:209], v[30:33]
	v_mfma_f32_16x16x32_bf16 v[26:29], v[150:153], v[206:209], v[26:29]
	v_mfma_f32_16x16x32_bf16 v[14:17], v[142:145], v[216:219], v[14:17]
	v_mfma_f32_16x16x32_bf16 v[10:13], v[150:153], v[216:219], v[10:13]
	v_mfma_f32_16x16x32_bf16 v[62:65], v[146:149], v[178:181], v[62:65]
	v_mfma_f32_16x16x32_bf16 v[58:61], v[154:157], v[178:181], v[58:61]
	v_mfma_f32_16x16x32_bf16 v[46:49], v[146:149], v[190:193], v[46:49]
	v_mfma_f32_16x16x32_bf16 v[42:45], v[154:157], v[190:193], v[42:45]
	v_mfma_f32_16x16x32_bf16 v[30:33], v[146:149], v[210:213], v[30:33]
	v_mfma_f32_16x16x32_bf16 v[26:29], v[154:157], v[210:213], v[26:29]
	v_mfma_f32_16x16x32_bf16 v[14:17], v[146:149], v[220:223], v[14:17]
	v_mfma_f32_16x16x32_bf16 v[10:13], v[154:157], v[220:223], v[10:13]
	s_setprio 0
	s_setprio 1
	v_mfma_f32_16x16x32_bf16 v[54:57], v[158:161], v[174:177], v[54:57]
	v_mfma_f32_16x16x32_bf16 v[50:53], v[166:169], v[174:177], v[50:53]
	v_mfma_f32_16x16x32_bf16 v[38:41], v[158:161], v[182:185], v[38:41]
	v_mfma_f32_16x16x32_bf16 v[34:37], v[166:169], v[182:185], v[34:37]
	v_mfma_f32_16x16x32_bf16 v[22:25], v[158:161], v[206:209], v[22:25]
	v_mfma_f32_16x16x32_bf16 v[18:21], v[166:169], v[206:209], v[18:21]
	v_mfma_f32_16x16x32_bf16 v[6:9], v[158:161], v[216:219], v[6:9]
	v_mfma_f32_16x16x32_bf16 v[2:5], v[166:169], v[216:219], v[2:5]
	v_mfma_f32_16x16x32_bf16 v[54:57], v[162:165], v[178:181], v[54:57]
	v_mfma_f32_16x16x32_bf16 v[50:53], v[170:173], v[178:181], v[50:53]
	v_mfma_f32_16x16x32_bf16 v[38:41], v[162:165], v[190:193], v[38:41]
	v_mfma_f32_16x16x32_bf16 v[34:37], v[170:173], v[190:193], v[34:37]
	v_mfma_f32_16x16x32_bf16 v[22:25], v[162:165], v[210:213], v[22:25]
	v_mfma_f32_16x16x32_bf16 v[18:21], v[170:173], v[210:213], v[18:21]
	v_mfma_f32_16x16x32_bf16 v[6:9], v[162:165], v[220:223], v[6:9]
	v_mfma_f32_16x16x32_bf16 v[2:5], v[170:173], v[220:223], v[2:5]
	s_setprio 0
	s_barrier
	s_add_i32 vcc_lo, vcc_lo, 2
	s_add_u32 s52, s52, 0x100
	s_addc_u32 s53, s53, 0
	s_cmp_gt_u32 vcc_lo, 13
	s_cbranch_scc0 .LBB0_950
	s_cmpk_lt_u32 s85, 0x100
	s_cbranch_scc0 .LBB0_953
	s_barrier

.LBB0_1005:
	s_add_u32 s54, s93, s52
	s_addc_u32 s55, s94, s53
	s_add_u32 s54, s54, 0x8a00100
	s_addc_u32 s55, s55, 0
	s_add_u32 s60, s95, s52
	s_addc_u32 s61, s96, s53
	s_add_i32 vcc_lo, 0, 0x10000
	s_cmpk_eq_i32 s52, 0x700
	s_cselect_b32 s57, s7, s55
	s_cselect_b32 s56, s6, s54
	v_add_u32_e32 v143, vcc_lo, v141
	s_cselect_b32 s55, s5, s61
	s_cselect_b32 s54, s4, s60
	s_add_i32 s60, 0, 0x14000
	ds_read_b128 v[144:147], v143
	ds_read_b128 v[148:151], v143 offset:1024
	ds_read_b128 v[152:155], v143 offset:2048
	ds_read_b128 v[160:163], v143 offset:3072
	v_add_u32_e32 v143, s60, v141
	ds_read_b128 v[164:167], v143
	ds_read_b128 v[168:171], v143 offset:1024
	ds_read_b128 v[172:175], v143 offset:2048
	ds_read_b128 v[176:179], v143 offset:3072
	v_lshl_add_u64 v[156:157], v[136:137], 0, s[52:53]
	s_add_i32 m0, s87, 0xc000
	ds_read_b128 v[180:183], v142
	ds_read_b128 v[184:187], v142 offset:1024
	ds_read_b128 v[190:193], v142 offset:2048
	ds_read_b128 v[206:209], v142 offset:3072
	ds_read_b128 v[210:213], v142 offset:4096
	ds_read_b128 v[216:219], v142 offset:5120
	ds_read_b128 v[220:223], v142 offset:6144
	ds_read_b128 v[224:227], v142 offset:7168
	global_load_lds_dwordx4 v[156:157], off
	v_lshl_add_u64 v[156:157], v[138:139], 0, s[52:53]
	s_add_i32 m0, s87, 0xe000
	s_nop 0
	global_load_lds_dwordx4 v[156:157], off
	s_waitcnt vmcnt(8)
	s_waitcnt lgkmcnt(0)
	s_barrier
	s_setprio 1
	s_waitcnt lgkmcnt(0)
	v_mfma_f32_16x16x32_bf16 v[126:129], v[144:147], v[180:183], v[126:129]
	v_mfma_f32_16x16x32_bf16 v[122:125], v[152:155], v[180:183], v[122:125]
	v_mfma_f32_16x16x32_bf16 v[110:113], v[144:147], v[190:193], v[110:113]
	v_mfma_f32_16x16x32_bf16 v[106:109], v[152:155], v[190:193], v[106:109]
	v_mfma_f32_16x16x32_bf16 v[94:97], v[144:147], v[210:213], v[94:97]
	v_mfma_f32_16x16x32_bf16 v[90:93], v[152:155], v[210:213], v[90:93]
	v_mfma_f32_16x16x32_bf16 v[78:81], v[144:147], v[220:223], v[78:81]
	v_mfma_f32_16x16x32_bf16 v[74:77], v[152:155], v[220:223], v[74:77]
	v_mfma_f32_16x16x32_bf16 v[126:129], v[148:151], v[184:187], v[126:129]
	v_mfma_f32_16x16x32_bf16 v[122:125], v[160:163], v[184:187], v[122:125]
	v_mfma_f32_16x16x32_bf16 v[110:113], v[148:151], v[206:209], v[110:113]
	v_mfma_f32_16x16x32_bf16 v[106:109], v[160:163], v[206:209], v[106:109]
	v_mfma_f32_16x16x32_bf16 v[94:97], v[148:151], v[216:219], v[94:97]
	v_mfma_f32_16x16x32_bf16 v[90:93], v[160:163], v[216:219], v[90:93]
	v_mfma_f32_16x16x32_bf16 v[78:81], v[148:151], v[224:227], v[78:81]
	v_mfma_f32_16x16x32_bf16 v[74:77], v[160:163], v[224:227], v[74:77]
	s_setprio 0
	s_setprio 1
	v_mfma_f32_16x16x32_bf16 v[118:121], v[164:167], v[180:183], v[118:121]
	v_mfma_f32_16x16x32_bf16 v[114:117], v[172:175], v[180:183], v[114:117]
	v_mfma_f32_16x16x32_bf16 v[102:105], v[164:167], v[190:193], v[102:105]
	v_mfma_f32_16x16x32_bf16 v[98:101], v[172:175], v[190:193], v[98:101]
	v_mfma_f32_16x16x32_bf16 v[86:89], v[164:167], v[210:213], v[86:89]
	v_mfma_f32_16x16x32_bf16 v[82:85], v[172:175], v[210:213], v[82:85]
	v_mfma_f32_16x16x32_bf16 v[70:73], v[164:167], v[220:223], v[70:73]
	v_mfma_f32_16x16x32_bf16 v[66:69], v[172:175], v[220:223], v[66:69]
	v_mfma_f32_16x16x32_bf16 v[118:121], v[168:171], v[184:187], v[118:121]
	v_mfma_f32_16x16x32_bf16 v[114:117], v[176:179], v[184:187], v[114:117]
	v_mfma_f32_16x16x32_bf16 v[102:105], v[168:171], v[206:209], v[102:105]
	v_mfma_f32_16x16x32_bf16 v[98:101], v[176:179], v[206:209], v[98:101]
	v_mfma_f32_16x16x32_bf16 v[86:89], v[168:171], v[216:219], v[86:89]
	v_mfma_f32_16x16x32_bf16 v[82:85], v[176:179], v[216:219], v[82:85]
	v_mfma_f32_16x16x32_bf16 v[70:73], v[168:171], v[224:227], v[70:73]
	v_mfma_f32_16x16x32_bf16 v[66:69], v[176:179], v[224:227], v[66:69]
	s_setprio 0
	s_barrier
	s_add_i32 s61, vcc_lo, s86
	v_lshl_add_u64 v[156:157], s[54:55], 0, v[0:1]
	s_mov_b32 m0, s61
	ds_read_b128 v[180:183], v142 offset:16384
	ds_read_b128 v[184:187], v142 offset:17408
	ds_read_b128 v[190:193], v142 offset:18432
	ds_read_b128 v[206:209], v142 offset:19456
	ds_read_b128 v[210:213], v142 offset:20480
	ds_read_b128 v[216:219], v142 offset:21504
	ds_read_b128 v[220:223], v142 offset:22528
	ds_read_b128 v[224:227], v142 offset:23552
	global_load_lds_dwordx4 v0, s[54:55]
	s_add_i32 m0, s61, 0x2000
	s_add_u32 vcc_lo, s54, 0x40000
	v_lshl_add_u64 v[228:229], s[54:55], 0, v[134:135]
	s_addc_u32 vcc_hi, s55, 0
	s_add_i32 s60, s60, s86
	global_load_lds_dwordx4 v134, s[54:55]
	s_mov_b32 m0, s60
	v_lshl_add_u64 v[232:233], s[56:57], 0, v[132:133]
	global_load_lds_dwordx4 v0, vcc
	s_add_i32 m0, s60, 0x2000
	s_nop 0
	global_load_lds_dwordx4 v134, vcc
	v_lshl_add_u64 v[230:231], s[56:57], 0, v[130:131]
	s_mov_b32 m0, s87
	s_nop 0
	global_load_lds_dwordx4 v130, s[56:57]
	s_mov_b32 m0, s88
	s_nop 0
	global_load_lds_dwordx4 v132, s[56:57]
	s_waitcnt vmcnt(8)
	s_waitcnt lgkmcnt(0)
	s_barrier
	s_setprio 1
	s_waitcnt lgkmcnt(0)
	v_mfma_f32_16x16x32_bf16 v[62:65], v[144:147], v[180:183], v[62:65]
	v_mfma_f32_16x16x32_bf16 v[58:61], v[152:155], v[180:183], v[58:61]
	v_mfma_f32_16x16x32_bf16 v[46:49], v[144:147], v[190:193], v[46:49]
	v_mfma_f32_16x16x32_bf16 v[42:45], v[152:155], v[190:193], v[42:45]
	v_mfma_f32_16x16x32_bf16 v[30:33], v[144:147], v[210:213], v[30:33]
	v_mfma_f32_16x16x32_bf16 v[26:29], v[152:155], v[210:213], v[26:29]
	v_mfma_f32_16x16x32_bf16 v[14:17], v[144:147], v[220:223], v[14:17]
	v_mfma_f32_16x16x32_bf16 v[10:13], v[152:155], v[220:223], v[10:13]
	v_mfma_f32_16x16x32_bf16 v[62:65], v[148:151], v[184:187], v[62:65]
	v_mfma_f32_16x16x32_bf16 v[58:61], v[160:163], v[184:187], v[58:61]
	v_mfma_f32_16x16x32_bf16 v[46:49], v[148:151], v[206:209], v[46:49]
	v_mfma_f32_16x16x32_bf16 v[42:45], v[160:163], v[206:209], v[42:45]
	v_mfma_f32_16x16x32_bf16 v[30:33], v[148:151], v[216:219], v[30:33]
	v_mfma_f32_16x16x32_bf16 v[26:29], v[160:163], v[216:219], v[26:29]
	v_mfma_f32_16x16x32_bf16 v[14:17], v[148:151], v[224:227], v[14:17]
	v_mfma_f32_16x16x32_bf16 v[10:13], v[160:163], v[224:227], v[10:13]
	s_setprio 0
	s_setprio 1
	v_mfma_f32_16x16x32_bf16 v[54:57], v[164:167], v[180:183], v[54:57]
	v_mfma_f32_16x16x32_bf16 v[50:53], v[172:175], v[180:183], v[50:53]
	v_mfma_f32_16x16x32_bf16 v[38:41], v[164:167], v[190:193], v[38:41]
	v_mfma_f32_16x16x32_bf16 v[34:37], v[172:175], v[190:193], v[34:37]
	v_mfma_f32_16x16x32_bf16 v[22:25], v[164:167], v[210:213], v[22:25]
	v_mfma_f32_16x16x32_bf16 v[18:21], v[172:175], v[210:213], v[18:21]
	v_mfma_f32_16x16x32_bf16 v[6:9], v[164:167], v[220:223], v[6:9]
	v_mfma_f32_16x16x32_bf16 v[2:5], v[172:175], v[220:223], v[2:5]
	v_mfma_f32_16x16x32_bf16 v[54:57], v[168:171], v[184:187], v[54:57]
	v_mfma_f32_16x16x32_bf16 v[50:53], v[176:179], v[184:187], v[50:53]
	v_mfma_f32_16x16x32_bf16 v[38:41], v[168:171], v[206:209], v[38:41]
	v_mfma_f32_16x16x32_bf16 v[34:37], v[176:179], v[206:209], v[34:37]
	v_mfma_f32_16x16x32_bf16 v[22:25], v[168:171], v[216:219], v[22:25]
	v_mfma_f32_16x16x32_bf16 v[18:21], v[176:179], v[216:219], v[18:21]
	v_mfma_f32_16x16x32_bf16 v[6:9], v[168:171], v[224:227], v[6:9]
	v_mfma_f32_16x16x32_bf16 v[2:5], v[176:179], v[224:227], v[2:5]
	s_setprio 0
	s_barrier
	s_add_i32 s60, 0, 0x18000
	v_add_u32_e32 v143, s60, v141
	s_add_i32 s61, 0, 0x1c000
	ds_read_b128 v[144:147], v143
	ds_read_b128 v[148:151], v143 offset:1024
	ds_read_b128 v[152:155], v143 offset:2048
	ds_read_b128 v[160:163], v143 offset:3072
	v_add_u32_e32 v143, s61, v141
	ds_read_b128 v[164:167], v143
	ds_read_b128 v[168:171], v143 offset:1024
	ds_read_b128 v[172:175], v143 offset:2048
	ds_read_b128 v[176:179], v143 offset:3072
	s_add_u32 s56, s56, 0x40000
	s_addc_u32 s57, s57, 0
	s_mov_b32 m0, s89
	ds_read_b128 v[180:183], v142 offset:32768
	ds_read_b128 v[184:187], v142 offset:33792
	ds_read_b128 v[190:193], v142 offset:34816
	ds_read_b128 v[206:209], v142 offset:35840
	ds_read_b128 v[210:213], v142 offset:36864
	ds_read_b128 v[216:219], v142 offset:37888
	ds_read_b128 v[220:223], v142 offset:38912
	ds_read_b128 v[224:227], v142 offset:39936
	global_load_lds_dwordx4 v130, s[56:57]
	s_mov_b32 m0, s90
	s_nop 0
	global_load_lds_dwordx4 v132, s[56:57]
	s_waitcnt vmcnt(8)
	s_waitcnt lgkmcnt(0)
	s_barrier
	s_setprio 1
	s_waitcnt lgkmcnt(0)
	v_mfma_f32_16x16x32_bf16 v[126:129], v[144:147], v[180:183], v[126:129]
	v_mfma_f32_16x16x32_bf16 v[122:125], v[152:155], v[180:183], v[122:125]
	v_mfma_f32_16x16x32_bf16 v[110:113], v[144:147], v[190:193], v[110:113]
	v_mfma_f32_16x16x32_bf16 v[106:109], v[152:155], v[190:193], v[106:109]
	v_mfma_f32_16x16x32_bf16 v[94:97], v[144:147], v[210:213], v[94:97]
	v_mfma_f32_16x16x32_bf16 v[90:93], v[152:155], v[210:213], v[90:93]
	v_mfma_f32_16x16x32_bf16 v[78:81], v[144:147], v[220:223], v[78:81]
	v_mfma_f32_16x16x32_bf16 v[74:77], v[152:155], v[220:223], v[74:77]
	v_mfma_f32_16x16x32_bf16 v[126:129], v[148:151], v[184:187], v[126:129]
	v_mfma_f32_16x16x32_bf16 v[122:125], v[160:163], v[184:187], v[122:125]
	v_mfma_f32_16x16x32_bf16 v[110:113], v[148:151], v[206:209], v[110:113]
	v_mfma_f32_16x16x32_bf16 v[106:109], v[160:163], v[206:209], v[106:109]
	v_mfma_f32_16x16x32_bf16 v[94:97], v[148:151], v[216:219], v[94:97]
	v_mfma_f32_16x16x32_bf16 v[90:93], v[160:163], v[216:219], v[90:93]
	v_mfma_f32_16x16x32_bf16 v[78:81], v[148:151], v[224:227], v[78:81]
	v_mfma_f32_16x16x32_bf16 v[74:77], v[160:163], v[224:227], v[74:77]
	s_setprio 0
	s_setprio 1
	v_mfma_f32_16x16x32_bf16 v[118:121], v[164:167], v[180:183], v[118:121]
	v_mfma_f32_16x16x32_bf16 v[114:117], v[172:175], v[180:183], v[114:117]
	v_mfma_f32_16x16x32_bf16 v[102:105], v[164:167], v[190:193], v[102:105]
	v_mfma_f32_16x16x32_bf16 v[98:101], v[172:175], v[190:193], v[98:101]
	v_mfma_f32_16x16x32_bf16 v[86:89], v[164:167], v[210:213], v[86:89]
	v_mfma_f32_16x16x32_bf16 v[82:85], v[172:175], v[210:213], v[82:85]
	v_mfma_f32_16x16x32_bf16 v[70:73], v[164:167], v[220:223], v[70:73]
	v_mfma_f32_16x16x32_bf16 v[66:69], v[172:175], v[220:223], v[66:69]
	v_mfma_f32_16x16x32_bf16 v[118:121], v[168:171], v[184:187], v[118:121]
	v_mfma_f32_16x16x32_bf16 v[114:117], v[176:179], v[184:187], v[114:117]
	v_mfma_f32_16x16x32_bf16 v[102:105], v[168:171], v[206:209], v[102:105]
	v_mfma_f32_16x16x32_bf16 v[98:101], v[176:179], v[206:209], v[98:101]
	v_mfma_f32_16x16x32_bf16 v[86:89], v[168:171], v[216:219], v[86:89]
	v_mfma_f32_16x16x32_bf16 v[82:85], v[176:179], v[216:219], v[82:85]
	v_mfma_f32_16x16x32_bf16 v[70:73], v[168:171], v[224:227], v[70:73]
	v_mfma_f32_16x16x32_bf16 v[66:69], v[176:179], v[224:227], v[66:69]
	s_setprio 0
	s_barrier
	s_add_i32 s56, s60, s86
	v_lshl_add_u64 v[156:157], v[156:157], 0, s[20:21]
	s_mov_b32 m0, s56
	ds_read_b128 v[180:183], v142 offset:49152
	ds_read_b128 v[184:187], v142 offset:50176
	ds_read_b128 v[190:193], v142 offset:51200
	ds_read_b128 v[206:209], v142 offset:52224
	ds_read_b128 v[210:213], v142 offset:53248
	ds_read_b128 v[216:219], v142 offset:54272
	ds_read_b128 v[220:223], v142 offset:55296
	ds_read_b128 v[224:227], v142 offset:56320
	global_load_lds_dwordx4 v[156:157], off
	s_add_i32 m0, s56, 0x2000
	s_add_u32 s54, s54, 0x40080
	v_lshl_add_u64 v[156:157], v[228:229], 0, s[20:21]
	s_addc_u32 s55, s55, 0
	s_add_i32 s56, s61, s86
	global_load_lds_dwordx4 v[156:157], off
	s_mov_b32 m0, s56
	s_nop 0
	global_load_lds_dwordx4 v0, s[54:55]
	s_add_i32 m0, s56, 0x2000
	s_nop 0
	global_load_lds_dwordx4 v134, s[54:55]
	v_lshl_add_u64 v[156:157], v[230:231], 0, s[20:21]
	s_mov_b32 m0, s91
	s_nop 0
	global_load_lds_dwordx4 v[156:157], off
	v_lshl_add_u64 v[156:157], v[232:233], 0, s[20:21]
	s_mov_b32 m0, s92
	s_nop 0
	global_load_lds_dwordx4 v[156:157], off
	s_waitcnt vmcnt(8)
	s_waitcnt lgkmcnt(0)
	s_barrier
	s_setprio 1
	s_waitcnt lgkmcnt(0)
	v_mfma_f32_16x16x32_bf16 v[62:65], v[144:147], v[180:183], v[62:65]
	v_mfma_f32_16x16x32_bf16 v[58:61], v[152:155], v[180:183], v[58:61]
	v_mfma_f32_16x16x32_bf16 v[46:49], v[144:147], v[190:193], v[46:49]
	v_mfma_f32_16x16x32_bf16 v[42:45], v[152:155], v[190:193], v[42:45]
	v_mfma_f32_16x16x32_bf16 v[30:33], v[144:147], v[210:213], v[30:33]
	v_mfma_f32_16x16x32_bf16 v[26:29], v[152:155], v[210:213], v[26:29]
	v_mfma_f32_16x16x32_bf16 v[14:17], v[144:147], v[220:223], v[14:17]
	v_mfma_f32_16x16x32_bf16 v[10:13], v[152:155], v[220:223], v[10:13]
	v_mfma_f32_16x16x32_bf16 v[62:65], v[148:151], v[184:187], v[62:65]
	v_mfma_f32_16x16x32_bf16 v[58:61], v[160:163], v[184:187], v[58:61]
	v_mfma_f32_16x16x32_bf16 v[46:49], v[148:151], v[206:209], v[46:49]
	v_mfma_f32_16x16x32_bf16 v[42:45], v[160:163], v[206:209], v[42:45]
	v_mfma_f32_16x16x32_bf16 v[30:33], v[148:151], v[216:219], v[30:33]
	v_mfma_f32_16x16x32_bf16 v[26:29], v[160:163], v[216:219], v[26:29]
	v_mfma_f32_16x16x32_bf16 v[14:17], v[148:151], v[224:227], v[14:17]
	v_mfma_f32_16x16x32_bf16 v[10:13], v[160:163], v[224:227], v[10:13]
	s_setprio 0
	s_setprio 1
	v_mfma_f32_16x16x32_bf16 v[54:57], v[164:167], v[180:183], v[54:57]
	v_mfma_f32_16x16x32_bf16 v[50:53], v[172:175], v[180:183], v[50:53]
	v_mfma_f32_16x16x32_bf16 v[38:41], v[164:167], v[190:193], v[38:41]
	v_mfma_f32_16x16x32_bf16 v[34:37], v[172:175], v[190:193], v[34:37]
	v_mfma_f32_16x16x32_bf16 v[22:25], v[164:167], v[210:213], v[22:25]
	v_mfma_f32_16x16x32_bf16 v[18:21], v[172:175], v[210:213], v[18:21]
	v_mfma_f32_16x16x32_bf16 v[6:9], v[164:167], v[220:223], v[6:9]
	v_mfma_f32_16x16x32_bf16 v[2:5], v[172:175], v[220:223], v[2:5]
	v_mfma_f32_16x16x32_bf16 v[54:57], v[168:171], v[184:187], v[54:57]
	v_mfma_f32_16x16x32_bf16 v[50:53], v[176:179], v[184:187], v[50:53]
	v_mfma_f32_16x16x32_bf16 v[38:41], v[168:171], v[206:209], v[38:41]
	v_mfma_f32_16x16x32_bf16 v[34:37], v[176:179], v[206:209], v[34:37]
	v_mfma_f32_16x16x32_bf16 v[22:25], v[168:171], v[216:219], v[22:25]
	v_mfma_f32_16x16x32_bf16 v[18:21], v[176:179], v[216:219], v[18:21]
	v_mfma_f32_16x16x32_bf16 v[6:9], v[168:171], v[224:227], v[6:9]
	v_mfma_f32_16x16x32_bf16 v[2:5], v[176:179], v[224:227], v[2:5]
	s_setprio 0
	s_barrier
	s_add_i32 s97, s97, 2
	s_add_u32 s52, s52, 0x100
	s_addc_u32 s53, s53, 0
	s_cmp_gt_u32 s97, 13
	s_cbranch_scc0 .LBB0_1005
	s_cmpk_lt_u32 s85, 0x100
	s_cbranch_scc0 .LBB0_1008
	s_barrier

.LBB0_1160:
	ds_read_b128 v[128:131], v179
	ds_read_b128 v[132:135], v179 offset:1024
	ds_read_b128 v[136:139], v179 offset:2048
	ds_read_b128 v[140:143], v179 offset:3072
	ds_read_b128 v[160:163], v180
	ds_read_b128 v[164:167], v180 offset:1024
	ds_read_b128 v[168:171], v180 offset:2048
	ds_read_b128 v[182:185], v180 offset:3072
	s_add_u32 s44, s30, 0xfffc0080
	s_addc_u32 s45, s31, -1
	s_cmp_eq_u32 s72, 12
	s_cselect_b32 s53, s23, s45
	s_cselect_b32 s52, s29, s44
	s_cselect_b32 s45, s21, s71
	s_cselect_b32 s44, s69, s70
	s_add_i32 m0, s57, 0xc000
	ds_read_b128 v[186:189], v181
	ds_read_b128 v[190:193], v181 offset:1024
	ds_read_b128 v[194:197], v181 offset:2048
	ds_read_b128 v[198:201], v181 offset:3072
	ds_read_b128 v[202:205], v181 offset:4096
	ds_read_b128 v[206:209], v181 offset:5120
	ds_read_b128 v[210:213], v181 offset:6144
	ds_read_b128 v[216:219], v181 offset:7168
	global_load_lds_dwordx4 v152, s[30:31]
	s_add_i32 m0, s57, 0xe000
	s_nop 0
	global_load_lds_dwordx4 v154, s[30:31]
	s_waitcnt vmcnt(8)
	s_waitcnt lgkmcnt(0)
	s_barrier
	s_setprio 1
	s_waitcnt lgkmcnt(0)
	v_mfma_f32_16x16x32_bf16 v[124:127], v[128:131], v[186:189], v[124:127]
	v_mfma_f32_16x16x32_bf16 v[120:123], v[136:139], v[186:189], v[120:123]
	v_mfma_f32_16x16x32_bf16 v[108:111], v[128:131], v[194:197], v[108:111]
	v_mfma_f32_16x16x32_bf16 v[104:107], v[136:139], v[194:197], v[104:107]
	v_mfma_f32_16x16x32_bf16 v[92:95], v[128:131], v[202:205], v[92:95]
	v_mfma_f32_16x16x32_bf16 v[88:91], v[136:139], v[202:205], v[88:91]
	v_mfma_f32_16x16x32_bf16 v[76:79], v[128:131], v[210:213], v[76:79]
	v_mfma_f32_16x16x32_bf16 v[72:75], v[136:139], v[210:213], v[72:75]
	v_mfma_f32_16x16x32_bf16 v[124:127], v[132:135], v[190:193], v[124:127]
	v_mfma_f32_16x16x32_bf16 v[120:123], v[140:143], v[190:193], v[120:123]
	v_mfma_f32_16x16x32_bf16 v[108:111], v[132:135], v[198:201], v[108:111]
	v_mfma_f32_16x16x32_bf16 v[104:107], v[140:143], v[198:201], v[104:107]
	v_mfma_f32_16x16x32_bf16 v[92:95], v[132:135], v[206:209], v[92:95]
	v_mfma_f32_16x16x32_bf16 v[88:91], v[140:143], v[206:209], v[88:91]
	v_mfma_f32_16x16x32_bf16 v[76:79], v[132:135], v[216:219], v[76:79]
	v_mfma_f32_16x16x32_bf16 v[72:75], v[140:143], v[216:219], v[72:75]
	s_setprio 0
	s_setprio 1
	v_mfma_f32_16x16x32_bf16 v[116:119], v[160:163], v[186:189], v[116:119]
	v_mfma_f32_16x16x32_bf16 v[112:115], v[168:171], v[186:189], v[112:115]
	v_mfma_f32_16x16x32_bf16 v[100:103], v[160:163], v[194:197], v[100:103]
	v_mfma_f32_16x16x32_bf16 v[96:99], v[168:171], v[194:197], v[96:99]
	v_mfma_f32_16x16x32_bf16 v[84:87], v[160:163], v[202:205], v[84:87]
	v_mfma_f32_16x16x32_bf16 v[80:83], v[168:171], v[202:205], v[80:83]
	v_mfma_f32_16x16x32_bf16 v[68:71], v[160:163], v[210:213], v[68:71]
	v_mfma_f32_16x16x32_bf16 v[64:67], v[168:171], v[210:213], v[64:67]
	v_mfma_f32_16x16x32_bf16 v[116:119], v[164:167], v[190:193], v[116:119]
	v_mfma_f32_16x16x32_bf16 v[112:115], v[182:185], v[190:193], v[112:115]
	v_mfma_f32_16x16x32_bf16 v[100:103], v[164:167], v[198:201], v[100:103]
	v_mfma_f32_16x16x32_bf16 v[96:99], v[182:185], v[198:201], v[96:99]
	v_mfma_f32_16x16x32_bf16 v[84:87], v[164:167], v[206:209], v[84:87]
	v_mfma_f32_16x16x32_bf16 v[80:83], v[182:185], v[206:209], v[80:83]
	v_mfma_f32_16x16x32_bf16 v[68:71], v[164:167], v[216:219], v[68:71]
	v_mfma_f32_16x16x32_bf16 v[64:67], v[182:185], v[216:219], v[64:67]
	s_setprio 0
	s_barrier
	s_add_u32 s98, s44, 0x80
	s_addc_u32 s99, s45, 0
	s_add_u32 s100, s52, 0x80
	s_addc_u32 s101, s53, 0
	s_add_i32 s73, s66, s56
	s_mov_b32 m0, s73
	ds_read_b128 v[186:189], v181 offset:16384
	ds_read_b128 v[190:193], v181 offset:17408
	ds_read_b128 v[194:197], v181 offset:18432
	ds_read_b128 v[198:201], v181 offset:19456
	ds_read_b128 v[202:205], v181 offset:20480
	ds_read_b128 v[206:209], v181 offset:21504
	ds_read_b128 v[210:213], v181 offset:22528
	ds_read_b128 v[216:219], v181 offset:23552
	global_load_lds_dwordx4 v146, s[44:45]
	s_add_i32 m0, s73, 0x2000
	s_add_u32 s76, s44, 0x40000
	s_addc_u32 s77, s45, 0
	s_add_i32 s73, s67, s56
	global_load_lds_dwordx4 v150, s[44:45]
	s_mov_b32 m0, s73
	s_nop 0
	global_load_lds_dwordx4 v146, s[76:77]
	s_add_i32 m0, s73, 0x2000
	s_nop 0
	global_load_lds_dwordx4 v150, s[76:77]
	s_mov_b32 m0, s57
	s_nop 0
	global_load_lds_dwordx4 v144, s[52:53]
	s_mov_b32 m0, s58
	s_nop 0
	global_load_lds_dwordx4 v148, s[52:53]
	s_waitcnt vmcnt(8)
	s_waitcnt lgkmcnt(0)
	s_barrier
	s_setprio 1
	s_waitcnt lgkmcnt(0)
	v_mfma_f32_16x16x32_bf16 v[60:63], v[128:131], v[186:189], v[60:63]
	v_mfma_f32_16x16x32_bf16 v[56:59], v[136:139], v[186:189], v[56:59]
	v_mfma_f32_16x16x32_bf16 v[44:47], v[128:131], v[194:197], v[44:47]
	v_mfma_f32_16x16x32_bf16 v[40:43], v[136:139], v[194:197], v[40:43]
	v_mfma_f32_16x16x32_bf16 v[28:31], v[128:131], v[202:205], v[28:31]
	v_mfma_f32_16x16x32_bf16 v[24:27], v[136:139], v[202:205], v[24:27]
	v_mfma_f32_16x16x32_bf16 v[12:15], v[128:131], v[210:213], v[12:15]
	v_mfma_f32_16x16x32_bf16 v[8:11], v[136:139], v[210:213], v[8:11]
	v_mfma_f32_16x16x32_bf16 v[60:63], v[132:135], v[190:193], v[60:63]
	v_mfma_f32_16x16x32_bf16 v[56:59], v[140:143], v[190:193], v[56:59]
	v_mfma_f32_16x16x32_bf16 v[44:47], v[132:135], v[198:201], v[44:47]
	v_mfma_f32_16x16x32_bf16 v[40:43], v[140:143], v[198:201], v[40:43]
	v_mfma_f32_16x16x32_bf16 v[28:31], v[132:135], v[206:209], v[28:31]
	v_mfma_f32_16x16x32_bf16 v[24:27], v[140:143], v[206:209], v[24:27]
	v_mfma_f32_16x16x32_bf16 v[12:15], v[132:135], v[216:219], v[12:15]
	v_mfma_f32_16x16x32_bf16 v[8:11], v[140:143], v[216:219], v[8:11]
	s_setprio 0
	s_setprio 1
	v_mfma_f32_16x16x32_bf16 v[52:55], v[160:163], v[186:189], v[52:55]
	v_mfma_f32_16x16x32_bf16 v[48:51], v[168:171], v[186:189], v[48:51]
	v_mfma_f32_16x16x32_bf16 v[36:39], v[160:163], v[194:197], v[36:39]
	v_mfma_f32_16x16x32_bf16 v[32:35], v[168:171], v[194:197], v[32:35]
	v_mfma_f32_16x16x32_bf16 v[20:23], v[160:163], v[202:205], v[20:23]
	v_mfma_f32_16x16x32_bf16 v[16:19], v[168:171], v[202:205], v[16:19]
	v_mfma_f32_16x16x32_bf16 v[4:7], v[160:163], v[210:213], v[4:7]
	v_mfma_f32_16x16x32_bf16 v[0:3], v[168:171], v[210:213], v[0:3]
	v_mfma_f32_16x16x32_bf16 v[52:55], v[164:167], v[190:193], v[52:55]
	v_mfma_f32_16x16x32_bf16 v[48:51], v[182:185], v[190:193], v[48:51]
	v_mfma_f32_16x16x32_bf16 v[36:39], v[164:167], v[198:201], v[36:39]
	v_mfma_f32_16x16x32_bf16 v[32:35], v[182:185], v[198:201], v[32:35]
	v_mfma_f32_16x16x32_bf16 v[20:23], v[164:167], v[206:209], v[20:23]
	v_mfma_f32_16x16x32_bf16 v[16:19], v[182:185], v[206:209], v[16:19]
	v_mfma_f32_16x16x32_bf16 v[4:7], v[164:167], v[216:219], v[4:7]
	v_mfma_f32_16x16x32_bf16 v[0:3], v[182:185], v[216:219], v[0:3]
	s_setprio 0
	s_barrier
	s_add_i32 s73, 0, 0x18000
	s_add_i32 s74, 0, 0x1c000
	v_add_u32_e32 v140, s73, v177
	v_add_u32_e32 v182, s74, v177
	ds_read_b128 v[128:131], v140
	ds_read_b128 v[132:135], v140 offset:1024
	ds_read_b128 v[136:139], v140 offset:2048
	ds_read_b128 v[140:143], v140 offset:3072
	ds_read_b128 v[160:163], v182
	ds_read_b128 v[164:167], v182 offset:1024
	ds_read_b128 v[168:171], v182 offset:2048
	ds_read_b128 v[182:185], v182 offset:3072
	s_add_u32 s52, s52, 0x40000
	s_addc_u32 s53, s53, 0
	s_mov_b32 m0, s59
	ds_read_b128 v[186:189], v181 offset:32768
	ds_read_b128 v[190:193], v181 offset:33792
	ds_read_b128 v[194:197], v181 offset:34816
	ds_read_b128 v[198:201], v181 offset:35840
	ds_read_b128 v[202:205], v181 offset:36864
	ds_read_b128 v[206:209], v181 offset:37888
	ds_read_b128 v[210:213], v181 offset:38912
	ds_read_b128 v[216:219], v181 offset:39936
	global_load_lds_dwordx4 v144, s[52:53]
	s_mov_b32 m0, s60
	s_nop 0
	global_load_lds_dwordx4 v148, s[52:53]
	s_waitcnt vmcnt(8)
	s_waitcnt lgkmcnt(0)
	s_barrier
	s_setprio 1
	s_waitcnt lgkmcnt(0)
	v_mfma_f32_16x16x32_bf16 v[124:127], v[128:131], v[186:189], v[124:127]
	v_mfma_f32_16x16x32_bf16 v[120:123], v[136:139], v[186:189], v[120:123]
	v_mfma_f32_16x16x32_bf16 v[108:111], v[128:131], v[194:197], v[108:111]
	v_mfma_f32_16x16x32_bf16 v[104:107], v[136:139], v[194:197], v[104:107]
	v_mfma_f32_16x16x32_bf16 v[92:95], v[128:131], v[202:205], v[92:95]
	v_mfma_f32_16x16x32_bf16 v[88:91], v[136:139], v[202:205], v[88:91]
	v_mfma_f32_16x16x32_bf16 v[76:79], v[128:131], v[210:213], v[76:79]
	v_mfma_f32_16x16x32_bf16 v[72:75], v[136:139], v[210:213], v[72:75]
	v_mfma_f32_16x16x32_bf16 v[124:127], v[132:135], v[190:193], v[124:127]
	v_mfma_f32_16x16x32_bf16 v[120:123], v[140:143], v[190:193], v[120:123]
	v_mfma_f32_16x16x32_bf16 v[108:111], v[132:135], v[198:201], v[108:111]
	v_mfma_f32_16x16x32_bf16 v[104:107], v[140:143], v[198:201], v[104:107]
	v_mfma_f32_16x16x32_bf16 v[92:95], v[132:135], v[206:209], v[92:95]
	v_mfma_f32_16x16x32_bf16 v[88:91], v[140:143], v[206:209], v[88:91]
	v_mfma_f32_16x16x32_bf16 v[76:79], v[132:135], v[216:219], v[76:79]
	v_mfma_f32_16x16x32_bf16 v[72:75], v[140:143], v[216:219], v[72:75]
	s_setprio 0
	s_setprio 1
	v_mfma_f32_16x16x32_bf16 v[116:119], v[160:163], v[186:189], v[116:119]
	v_mfma_f32_16x16x32_bf16 v[112:115], v[168:171], v[186:189], v[112:115]
	v_mfma_f32_16x16x32_bf16 v[100:103], v[160:163], v[194:197], v[100:103]
	v_mfma_f32_16x16x32_bf16 v[96:99], v[168:171], v[194:197], v[96:99]
	v_mfma_f32_16x16x32_bf16 v[84:87], v[160:163], v[202:205], v[84:87]
	v_mfma_f32_16x16x32_bf16 v[80:83], v[168:171], v[202:205], v[80:83]
	v_mfma_f32_16x16x32_bf16 v[68:71], v[160:163], v[210:213], v[68:71]
	v_mfma_f32_16x16x32_bf16 v[64:67], v[168:171], v[210:213], v[64:67]
	v_mfma_f32_16x16x32_bf16 v[116:119], v[164:167], v[190:193], v[116:119]
	v_mfma_f32_16x16x32_bf16 v[112:115], v[182:185], v[190:193], v[112:115]
	v_mfma_f32_16x16x32_bf16 v[100:103], v[164:167], v[198:201], v[100:103]
	v_mfma_f32_16x16x32_bf16 v[96:99], v[182:185], v[198:201], v[96:99]
	v_mfma_f32_16x16x32_bf16 v[84:87], v[164:167], v[206:209], v[84:87]
	v_mfma_f32_16x16x32_bf16 v[80:83], v[182:185], v[206:209], v[80:83]
	v_mfma_f32_16x16x32_bf16 v[68:71], v[164:167], v[216:219], v[68:71]
	v_mfma_f32_16x16x32_bf16 v[64:67], v[182:185], v[216:219], v[64:67]
	s_setprio 0
	s_barrier
	s_add_i32 s52, s73, s56
	s_mov_b32 m0, s52
	ds_read_b128 v[186:189], v181 offset:49152
	ds_read_b128 v[190:193], v181 offset:50176
	ds_read_b128 v[194:197], v181 offset:51200
	ds_read_b128 v[198:201], v181 offset:52224
	ds_read_b128 v[202:205], v181 offset:53248
	ds_read_b128 v[206:209], v181 offset:54272
	ds_read_b128 v[210:213], v181 offset:55296
	ds_read_b128 v[216:219], v181 offset:56320
	global_load_lds_dwordx4 v146, s[98:99]
	s_add_i32 m0, s52, 0x2000
	s_add_u32 s44, s44, 0x40080
	s_addc_u32 s45, s45, 0
	s_add_i32 s52, s74, s56
	global_load_lds_dwordx4 v150, s[98:99]
	s_mov_b32 m0, s52
	s_nop 0
	global_load_lds_dwordx4 v146, s[44:45]
	s_add_i32 m0, s52, 0x2000
	s_nop 0
	global_load_lds_dwordx4 v150, s[44:45]
	s_mov_b32 m0, s64
	s_nop 0
	global_load_lds_dwordx4 v144, s[100:101]
	s_mov_b32 m0, s65
	s_nop 0
	global_load_lds_dwordx4 v148, s[100:101]
	s_waitcnt vmcnt(8)
	s_waitcnt lgkmcnt(0)
	s_barrier
	s_setprio 1
	s_waitcnt lgkmcnt(0)
	v_mfma_f32_16x16x32_bf16 v[60:63], v[128:131], v[186:189], v[60:63]
	v_mfma_f32_16x16x32_bf16 v[56:59], v[136:139], v[186:189], v[56:59]
	v_mfma_f32_16x16x32_bf16 v[44:47], v[128:131], v[194:197], v[44:47]
	v_mfma_f32_16x16x32_bf16 v[40:43], v[136:139], v[194:197], v[40:43]
	v_mfma_f32_16x16x32_bf16 v[28:31], v[128:131], v[202:205], v[28:31]
	v_mfma_f32_16x16x32_bf16 v[24:27], v[136:139], v[202:205], v[24:27]
	v_mfma_f32_16x16x32_bf16 v[12:15], v[128:131], v[210:213], v[12:15]
	v_mfma_f32_16x16x32_bf16 v[8:11], v[136:139], v[210:213], v[8:11]
	v_mfma_f32_16x16x32_bf16 v[60:63], v[132:135], v[190:193], v[60:63]
	v_mfma_f32_16x16x32_bf16 v[56:59], v[140:143], v[190:193], v[56:59]
	v_mfma_f32_16x16x32_bf16 v[44:47], v[132:135], v[198:201], v[44:47]
	v_mfma_f32_16x16x32_bf16 v[40:43], v[140:143], v[198:201], v[40:43]
	v_mfma_f32_16x16x32_bf16 v[28:31], v[132:135], v[206:209], v[28:31]
	v_mfma_f32_16x16x32_bf16 v[24:27], v[140:143], v[206:209], v[24:27]
	v_mfma_f32_16x16x32_bf16 v[12:15], v[132:135], v[216:219], v[12:15]
	v_mfma_f32_16x16x32_bf16 v[8:11], v[140:143], v[216:219], v[8:11]
	s_setprio 0
	s_setprio 1
	v_mfma_f32_16x16x32_bf16 v[52:55], v[160:163], v[186:189], v[52:55]
	v_mfma_f32_16x16x32_bf16 v[48:51], v[168:171], v[186:189], v[48:51]
	v_mfma_f32_16x16x32_bf16 v[36:39], v[160:163], v[194:197], v[36:39]
	v_mfma_f32_16x16x32_bf16 v[32:35], v[168:171], v[194:197], v[32:35]
	v_mfma_f32_16x16x32_bf16 v[20:23], v[160:163], v[202:205], v[20:23]
	v_mfma_f32_16x16x32_bf16 v[16:19], v[168:171], v[202:205], v[16:19]
	v_mfma_f32_16x16x32_bf16 v[4:7], v[160:163], v[210:213], v[4:7]
	v_mfma_f32_16x16x32_bf16 v[0:3], v[168:171], v[210:213], v[0:3]
	v_mfma_f32_16x16x32_bf16 v[52:55], v[164:167], v[190:193], v[52:55]
	v_mfma_f32_16x16x32_bf16 v[48:51], v[182:185], v[190:193], v[48:51]
	v_mfma_f32_16x16x32_bf16 v[36:39], v[164:167], v[198:201], v[36:39]
	v_mfma_f32_16x16x32_bf16 v[32:35], v[182:185], v[198:201], v[32:35]
	v_mfma_f32_16x16x32_bf16 v[20:23], v[164:167], v[206:209], v[20:23]
	v_mfma_f32_16x16x32_bf16 v[16:19], v[182:185], v[206:209], v[16:19]
	v_mfma_f32_16x16x32_bf16 v[4:7], v[164:167], v[216:219], v[4:7]
	v_mfma_f32_16x16x32_bf16 v[0:3], v[182:185], v[216:219], v[0:3]
	s_setprio 0
	s_barrier
	s_add_i32 s72, s72, 2
	s_add_u32 s30, s30, 0x100
	s_addc_u32 s31, s31, 0
	s_add_u32 s70, s70, 0x100
	s_addc_u32 s71, s71, 0
	s_cmp_gt_u32 s72, 13
	s_cbranch_scc0 .LBB0_1160
	s_and_b64 vcc, exec, s[16:17]
	s_cbranch_vccz .LBB0_1163
	s_barrier

.LBB0_1209:
	ds_read_b128 v[146:149], v216
	ds_read_b128 v[150:153], v216 offset:1024
	ds_read_b128 v[154:157], v216 offset:2048
	ds_read_b128 v[158:161], v216 offset:3072
	ds_read_b128 v[162:165], v217
	ds_read_b128 v[166:169], v217 offset:1024
	ds_read_b128 v[170:173], v217 offset:2048
	ds_read_b128 v[174:177], v217 offset:3072
	s_add_u32 s62, s60, 0xfffc0080
	s_addc_u32 s63, s61, -1
	s_cmp_eq_u32 s89, 12
	s_cselect_b32 s65, s51, s63
	s_cselect_b32 s64, s57, s62
	s_cselect_b32 s63, s45, s88
	s_cselect_b32 s62, s59, s87
	s_add_i32 m0, s69, 0xc000
	ds_read_b128 v[178:181], v218
	ds_read_b128 v[182:185], v218 offset:1024
	ds_read_b128 v[186:189], v218 offset:2048
	ds_read_b128 v[190:193], v218 offset:3072
	ds_read_b128 v[194:197], v218 offset:4096
	ds_read_b128 v[198:201], v218 offset:5120
	ds_read_b128 v[202:205], v218 offset:6144
	ds_read_b128 v[206:209], v218 offset:7168
	global_load_lds_dwordx4 v138, s[60:61]
	s_add_i32 m0, s69, 0xe000
	s_nop 0
	global_load_lds_dwordx4 v140, s[60:61]
	s_waitcnt vmcnt(8)
	s_waitcnt lgkmcnt(0)
	s_barrier
	s_setprio 1
	s_waitcnt lgkmcnt(0)
	v_mfma_f32_16x16x32_bf16 v[124:127], v[146:149], v[178:181], v[124:127]
	v_mfma_f32_16x16x32_bf16 v[60:63], v[154:157], v[178:181], v[60:63]
	v_mfma_f32_16x16x32_bf16 v[116:119], v[146:149], v[186:189], v[116:119]
	v_mfma_f32_16x16x32_bf16 v[52:55], v[154:157], v[186:189], v[52:55]
	v_mfma_f32_16x16x32_bf16 v[112:115], v[146:149], v[194:197], v[112:115]
	v_mfma_f32_16x16x32_bf16 v[48:51], v[154:157], v[194:197], v[48:51]
	v_mfma_f32_16x16x32_bf16 v[108:111], v[146:149], v[202:205], v[108:111]
	v_mfma_f32_16x16x32_bf16 v[40:43], v[154:157], v[202:205], v[40:43]
	v_mfma_f32_16x16x32_bf16 v[124:127], v[150:153], v[182:185], v[124:127]
	v_mfma_f32_16x16x32_bf16 v[60:63], v[158:161], v[182:185], v[60:63]
	v_mfma_f32_16x16x32_bf16 v[116:119], v[150:153], v[190:193], v[116:119]
	v_mfma_f32_16x16x32_bf16 v[52:55], v[158:161], v[190:193], v[52:55]
	v_mfma_f32_16x16x32_bf16 v[112:115], v[150:153], v[198:201], v[112:115]
	v_mfma_f32_16x16x32_bf16 v[48:51], v[158:161], v[198:201], v[48:51]
	v_mfma_f32_16x16x32_bf16 v[108:111], v[150:153], v[206:209], v[108:111]
	v_mfma_f32_16x16x32_bf16 v[40:43], v[158:161], v[206:209], v[40:43]
	s_setprio 0
	s_setprio 1
	v_mfma_f32_16x16x32_bf16 v[120:123], v[162:165], v[178:181], v[120:123]
	v_mfma_f32_16x16x32_bf16 v[56:59], v[170:173], v[178:181], v[56:59]
	v_mfma_f32_16x16x32_bf16 v[104:107], v[162:165], v[186:189], v[104:107]
	v_mfma_f32_16x16x32_bf16 v[44:47], v[170:173], v[186:189], v[44:47]
	v_mfma_f32_16x16x32_bf16 v[100:103], v[162:165], v[194:197], v[100:103]
	v_mfma_f32_16x16x32_bf16 v[36:39], v[170:173], v[194:197], v[36:39]
	v_mfma_f32_16x16x32_bf16 v[96:99], v[162:165], v[202:205], v[96:99]
	v_mfma_f32_16x16x32_bf16 v[32:35], v[170:173], v[202:205], v[32:35]
	v_mfma_f32_16x16x32_bf16 v[120:123], v[166:169], v[182:185], v[120:123]
	v_mfma_f32_16x16x32_bf16 v[56:59], v[174:177], v[182:185], v[56:59]
	v_mfma_f32_16x16x32_bf16 v[104:107], v[166:169], v[190:193], v[104:107]
	v_mfma_f32_16x16x32_bf16 v[44:47], v[174:177], v[190:193], v[44:47]
	v_mfma_f32_16x16x32_bf16 v[100:103], v[166:169], v[198:201], v[100:103]
	v_mfma_f32_16x16x32_bf16 v[36:39], v[174:177], v[198:201], v[36:39]
	v_mfma_f32_16x16x32_bf16 v[96:99], v[166:169], v[206:209], v[96:99]
	v_mfma_f32_16x16x32_bf16 v[32:35], v[174:177], v[206:209], v[32:35]
	s_setprio 0
	s_barrier
	s_add_u32 s98, s62, 0x80
	s_addc_u32 s99, s63, 0
	s_add_u32 s100, s64, 0x80
	s_addc_u32 s101, s65, 0
	s_add_i32 s90, s82, s68
	s_mov_b32 m0, s90
	ds_read_b128 v[178:181], v218 offset:16384
	ds_read_b128 v[182:185], v218 offset:17408
	ds_read_b128 v[186:189], v218 offset:18432
	ds_read_b128 v[190:193], v218 offset:19456
	ds_read_b128 v[194:197], v218 offset:20480
	ds_read_b128 v[198:201], v218 offset:21504
	ds_read_b128 v[202:205], v218 offset:22528
	ds_read_b128 v[206:209], v218 offset:23552
	global_load_lds_dwordx4 v128, s[62:63]
	s_add_i32 m0, s90, 0x2000
	s_add_u32 s90, s62, 0x40000
	s_addc_u32 s91, s63, 0
	s_add_i32 s92, s83, s68
	global_load_lds_dwordx4 v130, s[62:63]
	s_mov_b32 m0, s92
	s_nop 0
	global_load_lds_dwordx4 v128, s[90:91]
	s_add_i32 m0, s92, 0x2000
	s_nop 0
	global_load_lds_dwordx4 v130, s[90:91]
	s_mov_b32 m0, s69
	s_nop 0
	global_load_lds_dwordx4 v128, s[64:65]
	s_mov_b32 m0, s70
	s_nop 0
	global_load_lds_dwordx4 v130, s[64:65]
	s_waitcnt vmcnt(8)
	s_waitcnt lgkmcnt(0)
	s_barrier
	s_setprio 1
	s_waitcnt lgkmcnt(0)
	v_mfma_f32_16x16x32_bf16 v[92:95], v[146:149], v[178:181], v[92:95]
	v_mfma_f32_16x16x32_bf16 v[28:31], v[154:157], v[178:181], v[28:31]
	v_mfma_f32_16x16x32_bf16 v[84:87], v[146:149], v[186:189], v[84:87]
	v_mfma_f32_16x16x32_bf16 v[20:23], v[154:157], v[186:189], v[20:23]
	v_mfma_f32_16x16x32_bf16 v[80:83], v[146:149], v[194:197], v[80:83]
	v_mfma_f32_16x16x32_bf16 v[16:19], v[154:157], v[194:197], v[16:19]
	v_mfma_f32_16x16x32_bf16 v[76:79], v[146:149], v[202:205], v[76:79]
	v_mfma_f32_16x16x32_bf16 v[8:11], v[154:157], v[202:205], v[8:11]
	v_mfma_f32_16x16x32_bf16 v[92:95], v[150:153], v[182:185], v[92:95]
	v_mfma_f32_16x16x32_bf16 v[28:31], v[158:161], v[182:185], v[28:31]
	v_mfma_f32_16x16x32_bf16 v[84:87], v[150:153], v[190:193], v[84:87]
	v_mfma_f32_16x16x32_bf16 v[20:23], v[158:161], v[190:193], v[20:23]
	v_mfma_f32_16x16x32_bf16 v[80:83], v[150:153], v[198:201], v[80:83]
	v_mfma_f32_16x16x32_bf16 v[16:19], v[158:161], v[198:201], v[16:19]
	v_mfma_f32_16x16x32_bf16 v[76:79], v[150:153], v[206:209], v[76:79]
	v_mfma_f32_16x16x32_bf16 v[8:11], v[158:161], v[206:209], v[8:11]
	s_setprio 0
	s_setprio 1
	v_mfma_f32_16x16x32_bf16 v[88:91], v[162:165], v[178:181], v[88:91]
	v_mfma_f32_16x16x32_bf16 v[24:27], v[170:173], v[178:181], v[24:27]
	v_mfma_f32_16x16x32_bf16 v[72:75], v[162:165], v[186:189], v[72:75]
	v_mfma_f32_16x16x32_bf16 v[12:15], v[170:173], v[186:189], v[12:15]
	v_mfma_f32_16x16x32_bf16 v[68:71], v[162:165], v[194:197], v[68:71]
	v_mfma_f32_16x16x32_bf16 v[4:7], v[170:173], v[194:197], v[4:7]
	v_mfma_f32_16x16x32_bf16 v[64:67], v[162:165], v[202:205], v[64:67]
	v_mfma_f32_16x16x32_bf16 v[0:3], v[170:173], v[202:205], v[0:3]
	v_mfma_f32_16x16x32_bf16 v[88:91], v[166:169], v[182:185], v[88:91]
	v_mfma_f32_16x16x32_bf16 v[24:27], v[174:177], v[182:185], v[24:27]
	v_mfma_f32_16x16x32_bf16 v[72:75], v[166:169], v[190:193], v[72:75]
	v_mfma_f32_16x16x32_bf16 v[12:15], v[174:177], v[190:193], v[12:15]
	v_mfma_f32_16x16x32_bf16 v[68:71], v[166:169], v[198:201], v[68:71]
	v_mfma_f32_16x16x32_bf16 v[4:7], v[174:177], v[198:201], v[4:7]
	v_mfma_f32_16x16x32_bf16 v[64:67], v[166:169], v[206:209], v[64:67]
	v_mfma_f32_16x16x32_bf16 v[0:3], v[174:177], v[206:209], v[0:3]
	s_setprio 0
	s_barrier
	s_add_i32 s90, 0, 0x18000
	s_add_i32 s91, 0, 0x1c000
	v_add_u32_e32 v158, s90, v211
	v_add_u32_e32 v174, s91, v211
	ds_read_b128 v[146:149], v158
	ds_read_b128 v[150:153], v158 offset:1024
	ds_read_b128 v[154:157], v158 offset:2048
	ds_read_b128 v[158:161], v158 offset:3072
	ds_read_b128 v[162:165], v174
	ds_read_b128 v[166:169], v174 offset:1024
	ds_read_b128 v[170:173], v174 offset:2048
	ds_read_b128 v[174:177], v174 offset:3072
	s_add_u32 s64, s64, 0x40000
	s_addc_u32 s65, s65, 0
	s_mov_b32 m0, s71
	ds_read_b128 v[178:181], v218 offset:32768
	ds_read_b128 v[182:185], v218 offset:33792
	ds_read_b128 v[186:189], v218 offset:34816
	ds_read_b128 v[190:193], v218 offset:35840
	ds_read_b128 v[194:197], v218 offset:36864
	ds_read_b128 v[198:201], v218 offset:37888
	ds_read_b128 v[202:205], v218 offset:38912
	ds_read_b128 v[206:209], v218 offset:39936
	global_load_lds_dwordx4 v128, s[64:65]
	s_mov_b32 m0, s72
	s_nop 0
	global_load_lds_dwordx4 v130, s[64:65]
	s_waitcnt vmcnt(8)
	s_waitcnt lgkmcnt(0)
	s_barrier
	s_setprio 1
	s_waitcnt lgkmcnt(0)
	v_mfma_f32_16x16x32_bf16 v[124:127], v[146:149], v[178:181], v[124:127]
	v_mfma_f32_16x16x32_bf16 v[60:63], v[154:157], v[178:181], v[60:63]
	v_mfma_f32_16x16x32_bf16 v[116:119], v[146:149], v[186:189], v[116:119]
	v_mfma_f32_16x16x32_bf16 v[52:55], v[154:157], v[186:189], v[52:55]
	v_mfma_f32_16x16x32_bf16 v[112:115], v[146:149], v[194:197], v[112:115]
	v_mfma_f32_16x16x32_bf16 v[48:51], v[154:157], v[194:197], v[48:51]
	v_mfma_f32_16x16x32_bf16 v[108:111], v[146:149], v[202:205], v[108:111]
	v_mfma_f32_16x16x32_bf16 v[40:43], v[154:157], v[202:205], v[40:43]
	v_mfma_f32_16x16x32_bf16 v[124:127], v[150:153], v[182:185], v[124:127]
	v_mfma_f32_16x16x32_bf16 v[60:63], v[158:161], v[182:185], v[60:63]
	v_mfma_f32_16x16x32_bf16 v[116:119], v[150:153], v[190:193], v[116:119]
	v_mfma_f32_16x16x32_bf16 v[52:55], v[158:161], v[190:193], v[52:55]
	v_mfma_f32_16x16x32_bf16 v[112:115], v[150:153], v[198:201], v[112:115]
	v_mfma_f32_16x16x32_bf16 v[48:51], v[158:161], v[198:201], v[48:51]
	v_mfma_f32_16x16x32_bf16 v[108:111], v[150:153], v[206:209], v[108:111]
	v_mfma_f32_16x16x32_bf16 v[40:43], v[158:161], v[206:209], v[40:43]
	s_setprio 0
	s_setprio 1
	v_mfma_f32_16x16x32_bf16 v[120:123], v[162:165], v[178:181], v[120:123]
	v_mfma_f32_16x16x32_bf16 v[56:59], v[170:173], v[178:181], v[56:59]
	v_mfma_f32_16x16x32_bf16 v[104:107], v[162:165], v[186:189], v[104:107]
	v_mfma_f32_16x16x32_bf16 v[44:47], v[170:173], v[186:189], v[44:47]
	v_mfma_f32_16x16x32_bf16 v[100:103], v[162:165], v[194:197], v[100:103]
	v_mfma_f32_16x16x32_bf16 v[36:39], v[170:173], v[194:197], v[36:39]
	v_mfma_f32_16x16x32_bf16 v[96:99], v[162:165], v[202:205], v[96:99]
	v_mfma_f32_16x16x32_bf16 v[32:35], v[170:173], v[202:205], v[32:35]
	v_mfma_f32_16x16x32_bf16 v[120:123], v[166:169], v[182:185], v[120:123]
	v_mfma_f32_16x16x32_bf16 v[56:59], v[174:177], v[182:185], v[56:59]
	v_mfma_f32_16x16x32_bf16 v[104:107], v[166:169], v[190:193], v[104:107]
	v_mfma_f32_16x16x32_bf16 v[44:47], v[174:177], v[190:193], v[44:47]
	v_mfma_f32_16x16x32_bf16 v[100:103], v[166:169], v[198:201], v[100:103]
	v_mfma_f32_16x16x32_bf16 v[36:39], v[174:177], v[198:201], v[36:39]
	v_mfma_f32_16x16x32_bf16 v[96:99], v[166:169], v[206:209], v[96:99]
	v_mfma_f32_16x16x32_bf16 v[32:35], v[174:177], v[206:209], v[32:35]
	s_setprio 0
	s_barrier
	s_add_i32 s64, s90, s68
	s_mov_b32 m0, s64
	ds_read_b128 v[178:181], v218 offset:49152
	ds_read_b128 v[182:185], v218 offset:50176
	ds_read_b128 v[186:189], v218 offset:51200
	ds_read_b128 v[190:193], v218 offset:52224
	ds_read_b128 v[194:197], v218 offset:53248
	ds_read_b128 v[198:201], v218 offset:54272
	ds_read_b128 v[202:205], v218 offset:55296
	ds_read_b128 v[206:209], v218 offset:56320
	global_load_lds_dwordx4 v128, s[98:99]
	s_add_i32 m0, s64, 0x2000
	s_add_u32 s62, s62, 0x40080
	s_addc_u32 s63, s63, 0
	s_add_i32 s64, s91, s68
	global_load_lds_dwordx4 v130, s[98:99]
	s_mov_b32 m0, s64
	s_nop 0
	global_load_lds_dwordx4 v128, s[62:63]
	s_add_i32 m0, s64, 0x2000
	s_nop 0
	global_load_lds_dwordx4 v130, s[62:63]
	s_mov_b32 m0, s79
	s_nop 0
	global_load_lds_dwordx4 v128, s[100:101]
	s_mov_b32 m0, s80
	s_nop 0
	global_load_lds_dwordx4 v130, s[100:101]
	s_waitcnt vmcnt(8)
	s_waitcnt lgkmcnt(0)
	s_barrier
	s_setprio 1
	s_waitcnt lgkmcnt(0)
	v_mfma_f32_16x16x32_bf16 v[92:95], v[146:149], v[178:181], v[92:95]
	v_mfma_f32_16x16x32_bf16 v[28:31], v[154:157], v[178:181], v[28:31]
	v_mfma_f32_16x16x32_bf16 v[84:87], v[146:149], v[186:189], v[84:87]
	v_mfma_f32_16x16x32_bf16 v[20:23], v[154:157], v[186:189], v[20:23]
	v_mfma_f32_16x16x32_bf16 v[80:83], v[146:149], v[194:197], v[80:83]
	v_mfma_f32_16x16x32_bf16 v[16:19], v[154:157], v[194:197], v[16:19]
	v_mfma_f32_16x16x32_bf16 v[76:79], v[146:149], v[202:205], v[76:79]
	v_mfma_f32_16x16x32_bf16 v[8:11], v[154:157], v[202:205], v[8:11]
	v_mfma_f32_16x16x32_bf16 v[92:95], v[150:153], v[182:185], v[92:95]
	v_mfma_f32_16x16x32_bf16 v[28:31], v[158:161], v[182:185], v[28:31]
	v_mfma_f32_16x16x32_bf16 v[84:87], v[150:153], v[190:193], v[84:87]
	v_mfma_f32_16x16x32_bf16 v[20:23], v[158:161], v[190:193], v[20:23]
	v_mfma_f32_16x16x32_bf16 v[80:83], v[150:153], v[198:201], v[80:83]
	v_mfma_f32_16x16x32_bf16 v[16:19], v[158:161], v[198:201], v[16:19]
	v_mfma_f32_16x16x32_bf16 v[76:79], v[150:153], v[206:209], v[76:79]
	v_mfma_f32_16x16x32_bf16 v[8:11], v[158:161], v[206:209], v[8:11]
	s_setprio 0
	s_setprio 1
	v_mfma_f32_16x16x32_bf16 v[88:91], v[162:165], v[178:181], v[88:91]
	v_mfma_f32_16x16x32_bf16 v[24:27], v[170:173], v[178:181], v[24:27]
	v_mfma_f32_16x16x32_bf16 v[72:75], v[162:165], v[186:189], v[72:75]
	v_mfma_f32_16x16x32_bf16 v[12:15], v[170:173], v[186:189], v[12:15]
	v_mfma_f32_16x16x32_bf16 v[68:71], v[162:165], v[194:197], v[68:71]
	v_mfma_f32_16x16x32_bf16 v[4:7], v[170:173], v[194:197], v[4:7]
	v_mfma_f32_16x16x32_bf16 v[64:67], v[162:165], v[202:205], v[64:67]
	v_mfma_f32_16x16x32_bf16 v[0:3], v[170:173], v[202:205], v[0:3]
	v_mfma_f32_16x16x32_bf16 v[88:91], v[166:169], v[182:185], v[88:91]
	v_mfma_f32_16x16x32_bf16 v[24:27], v[174:177], v[182:185], v[24:27]
	v_mfma_f32_16x16x32_bf16 v[72:75], v[166:169], v[190:193], v[72:75]
	v_mfma_f32_16x16x32_bf16 v[12:15], v[174:177], v[190:193], v[12:15]
	v_mfma_f32_16x16x32_bf16 v[68:71], v[166:169], v[198:201], v[68:71]
	v_mfma_f32_16x16x32_bf16 v[4:7], v[174:177], v[198:201], v[4:7]
	v_mfma_f32_16x16x32_bf16 v[64:67], v[166:169], v[206:209], v[64:67]
	v_mfma_f32_16x16x32_bf16 v[0:3], v[174:177], v[206:209], v[0:3]
	s_setprio 0
	s_barrier
	s_add_i32 s89, s89, 2
	s_add_u32 s60, s60, 0x100
	s_addc_u32 s61, s61, 0
	s_add_u32 s87, s87, 0x100
	s_addc_u32 s88, s88, 0
	s_cmp_gt_u32 s89, 13
	s_cbranch_scc0 .LBB0_1209
	s_and_b64 vcc, exec, s[22:23]
	s_cbranch_vccz .LBB0_1212
	s_barrier

.LBB0_1288:
	ds_read_b128 v[144:147], v138
	ds_read_b128 v[148:151], v138 offset:1024
	ds_read_b128 v[152:155], v138 offset:2048
	ds_read_b128 v[156:159], v138 offset:3072
	ds_read_b128 v[160:163], v139
	ds_read_b128 v[164:167], v139 offset:1024
	ds_read_b128 v[168:171], v139 offset:2048
	ds_read_b128 v[172:175], v139 offset:3072
	s_or_b32 s26, s30, 1
	s_lshl_b64 s[82:83], s[26:27], 7
	s_add_i32 s26, s30, 2
	s_lshl_b64 s[42:43], s[26:27], 7
	s_cmp_lg_u32 s30, s70
	s_cselect_b32 s30, s42, 0
	s_cselect_b32 s31, s43, 0
	s_add_u32 s42, s24, s30
	s_addc_u32 s43, s25, s31
	s_add_u32 s30, s22, s30
	s_addc_u32 s31, s23, s31
	s_add_u32 s82, s24, s82
	s_addc_u32 s83, s25, s83
	s_add_u32 s82, s82, 0xb0000
	s_addc_u32 s83, s83, 0
	s_mov_b32 m0, s71
	ds_read_b128 v[176:179], v141
	ds_read_b128 v[180:183], v141 offset:1024
	ds_read_b128 v[184:187], v141 offset:2048
	ds_read_b128 v[188:191], v141 offset:3072
	ds_read_b128 v[192:195], v141 offset:4096
	ds_read_b128 v[196:199], v141 offset:5120
	ds_read_b128 v[200:203], v141 offset:6144
	ds_read_b128 v[204:207], v141 offset:7168
	global_load_lds_dwordx4 v128, s[82:83]
	s_mov_b32 m0, s72
	s_nop 0
	global_load_lds_dwordx4 v132, s[82:83]
	s_waitcnt vmcnt(8)
	s_waitcnt lgkmcnt(0)
	s_barrier
	s_setprio 1
	s_waitcnt lgkmcnt(0)
	v_mfma_f32_16x16x32_bf16 v[124:127], v[144:147], v[176:179], v[124:127]
	v_mfma_f32_16x16x32_bf16 v[120:123], v[152:155], v[176:179], v[120:123]
	v_mfma_f32_16x16x32_bf16 v[116:119], v[144:147], v[184:187], v[116:119]
	v_mfma_f32_16x16x32_bf16 v[112:115], v[152:155], v[184:187], v[112:115]
	v_mfma_f32_16x16x32_bf16 v[108:111], v[144:147], v[192:195], v[108:111]
	v_mfma_f32_16x16x32_bf16 v[104:107], v[152:155], v[192:195], v[104:107]
	v_mfma_f32_16x16x32_bf16 v[100:103], v[144:147], v[200:203], v[100:103]
	v_mfma_f32_16x16x32_bf16 v[96:99], v[152:155], v[200:203], v[96:99]
	v_mfma_f32_16x16x32_bf16 v[124:127], v[148:151], v[180:183], v[124:127]
	v_mfma_f32_16x16x32_bf16 v[120:123], v[156:159], v[180:183], v[120:123]
	v_mfma_f32_16x16x32_bf16 v[116:119], v[148:151], v[188:191], v[116:119]
	v_mfma_f32_16x16x32_bf16 v[112:115], v[156:159], v[188:191], v[112:115]
	v_mfma_f32_16x16x32_bf16 v[108:111], v[148:151], v[196:199], v[108:111]
	v_mfma_f32_16x16x32_bf16 v[104:107], v[156:159], v[196:199], v[104:107]
	v_mfma_f32_16x16x32_bf16 v[100:103], v[148:151], v[204:207], v[100:103]
	v_mfma_f32_16x16x32_bf16 v[96:99], v[156:159], v[204:207], v[96:99]
	s_setprio 0
	s_setprio 1
	v_mfma_f32_16x16x32_bf16 v[92:95], v[160:163], v[176:179], v[92:95]
	v_mfma_f32_16x16x32_bf16 v[88:91], v[168:171], v[176:179], v[88:91]
	v_mfma_f32_16x16x32_bf16 v[84:87], v[160:163], v[184:187], v[84:87]
	v_mfma_f32_16x16x32_bf16 v[80:83], v[168:171], v[184:187], v[80:83]
	v_mfma_f32_16x16x32_bf16 v[76:79], v[160:163], v[192:195], v[76:79]
	v_mfma_f32_16x16x32_bf16 v[72:75], v[168:171], v[192:195], v[72:75]
	v_mfma_f32_16x16x32_bf16 v[68:71], v[160:163], v[200:203], v[68:71]
	v_mfma_f32_16x16x32_bf16 v[64:67], v[168:171], v[200:203], v[64:67]
	v_mfma_f32_16x16x32_bf16 v[92:95], v[164:167], v[180:183], v[92:95]
	v_mfma_f32_16x16x32_bf16 v[88:91], v[172:175], v[180:183], v[88:91]
	v_mfma_f32_16x16x32_bf16 v[84:87], v[164:167], v[188:191], v[84:87]
	v_mfma_f32_16x16x32_bf16 v[80:83], v[172:175], v[188:191], v[80:83]
	v_mfma_f32_16x16x32_bf16 v[76:79], v[164:167], v[196:199], v[76:79]
	v_mfma_f32_16x16x32_bf16 v[72:75], v[172:175], v[196:199], v[72:75]
	v_mfma_f32_16x16x32_bf16 v[68:71], v[164:167], v[204:207], v[68:71]
	v_mfma_f32_16x16x32_bf16 v[64:67], v[172:175], v[204:207], v[64:67]
	s_setprio 0
	s_barrier
	s_add_u32 s98, s30, 0x80
	s_addc_u32 s99, s31, 0
	s_add_u32 s100, s42, 0x80
	s_addc_u32 s101, s43, 0
	s_mov_b32 m0, s73
	s_add_u32 s82, s30, 0xb0000
	ds_read_b128 v[176:179], v141 offset:16384
	ds_read_b128 v[180:183], v141 offset:17408
	ds_read_b128 v[184:187], v141 offset:18432
	ds_read_b128 v[188:191], v141 offset:19456
	ds_read_b128 v[192:195], v141 offset:20480
	ds_read_b128 v[196:199], v141 offset:21504
	ds_read_b128 v[200:203], v141 offset:22528
	ds_read_b128 v[204:207], v141 offset:23552
	global_load_lds_dwordx4 v130, s[30:31]
	s_mov_b32 m0, s74
	s_addc_u32 s83, s31, 0
	global_load_lds_dwordx4 v134, s[30:31]
	s_mov_b32 m0, s76
	s_nop 0
	global_load_lds_dwordx4 v130, s[82:83]
	s_mov_b32 m0, s77
	s_nop 0
	global_load_lds_dwordx4 v134, s[82:83]
	s_mov_b32 m0, s62
	s_nop 0
	global_load_lds_dwordx4 v128, s[42:43]
	s_mov_b32 m0, s63
	s_nop 0
	global_load_lds_dwordx4 v132, s[42:43]
	s_waitcnt vmcnt(8)
	s_waitcnt lgkmcnt(0)
	s_barrier
	s_setprio 1
	s_waitcnt lgkmcnt(0)
	v_mfma_f32_16x16x32_bf16 v[60:63], v[144:147], v[176:179], v[60:63]
	v_mfma_f32_16x16x32_bf16 v[56:59], v[152:155], v[176:179], v[56:59]
	v_mfma_f32_16x16x32_bf16 v[52:55], v[144:147], v[184:187], v[52:55]
	v_mfma_f32_16x16x32_bf16 v[48:51], v[152:155], v[184:187], v[48:51]
	v_mfma_f32_16x16x32_bf16 v[44:47], v[144:147], v[192:195], v[44:47]
	v_mfma_f32_16x16x32_bf16 v[40:43], v[152:155], v[192:195], v[40:43]
	v_mfma_f32_16x16x32_bf16 v[36:39], v[144:147], v[200:203], v[36:39]
	v_mfma_f32_16x16x32_bf16 v[32:35], v[152:155], v[200:203], v[32:35]
	v_mfma_f32_16x16x32_bf16 v[60:63], v[148:151], v[180:183], v[60:63]
	v_mfma_f32_16x16x32_bf16 v[56:59], v[156:159], v[180:183], v[56:59]
	v_mfma_f32_16x16x32_bf16 v[52:55], v[148:151], v[188:191], v[52:55]
	v_mfma_f32_16x16x32_bf16 v[48:51], v[156:159], v[188:191], v[48:51]
	v_mfma_f32_16x16x32_bf16 v[44:47], v[148:151], v[196:199], v[44:47]
	v_mfma_f32_16x16x32_bf16 v[40:43], v[156:159], v[196:199], v[40:43]
	v_mfma_f32_16x16x32_bf16 v[36:39], v[148:151], v[204:207], v[36:39]
	v_mfma_f32_16x16x32_bf16 v[32:35], v[156:159], v[204:207], v[32:35]
	s_setprio 0
	s_setprio 1
	v_mfma_f32_16x16x32_bf16 v[28:31], v[160:163], v[176:179], v[28:31]
	v_mfma_f32_16x16x32_bf16 v[24:27], v[168:171], v[176:179], v[24:27]
	v_mfma_f32_16x16x32_bf16 v[20:23], v[160:163], v[184:187], v[20:23]
	v_mfma_f32_16x16x32_bf16 v[16:19], v[168:171], v[184:187], v[16:19]
	v_mfma_f32_16x16x32_bf16 v[12:15], v[160:163], v[192:195], v[12:15]
	v_mfma_f32_16x16x32_bf16 v[8:11], v[168:171], v[192:195], v[8:11]
	v_mfma_f32_16x16x32_bf16 v[4:7], v[160:163], v[200:203], v[4:7]
	v_mfma_f32_16x16x32_bf16 v[0:3], v[168:171], v[200:203], v[0:3]
	v_mfma_f32_16x16x32_bf16 v[28:31], v[164:167], v[180:183], v[28:31]
	v_mfma_f32_16x16x32_bf16 v[24:27], v[172:175], v[180:183], v[24:27]
	v_mfma_f32_16x16x32_bf16 v[20:23], v[164:167], v[188:191], v[20:23]
	v_mfma_f32_16x16x32_bf16 v[16:19], v[172:175], v[188:191], v[16:19]
	v_mfma_f32_16x16x32_bf16 v[12:15], v[164:167], v[196:199], v[12:15]
	v_mfma_f32_16x16x32_bf16 v[8:11], v[172:175], v[196:199], v[8:11]
	v_mfma_f32_16x16x32_bf16 v[4:7], v[164:167], v[204:207], v[4:7]
	v_mfma_f32_16x16x32_bf16 v[0:3], v[172:175], v[204:207], v[0:3]
	s_setprio 0
	s_barrier
	ds_read_b128 v[144:147], v142
	ds_read_b128 v[148:151], v142 offset:1024
	ds_read_b128 v[152:155], v142 offset:2048
	ds_read_b128 v[156:159], v142 offset:3072
	ds_read_b128 v[160:163], v143
	ds_read_b128 v[164:167], v143 offset:1024
	ds_read_b128 v[168:171], v143 offset:2048
	ds_read_b128 v[172:175], v143 offset:3072
	s_add_u32 s42, s42, 0xb0000
	s_addc_u32 s43, s43, 0
	s_mov_b32 m0, s64
	ds_read_b128 v[176:179], v141 offset:32768
	ds_read_b128 v[180:183], v141 offset:33792
	ds_read_b128 v[184:187], v141 offset:34816
	ds_read_b128 v[188:191], v141 offset:35840
	ds_read_b128 v[192:195], v141 offset:36864
	ds_read_b128 v[196:199], v141 offset:37888
	ds_read_b128 v[200:203], v141 offset:38912
	ds_read_b128 v[204:207], v141 offset:39936
	global_load_lds_dwordx4 v128, s[42:43]
	s_mov_b32 m0, s65
	s_nop 0
	global_load_lds_dwordx4 v132, s[42:43]
	s_waitcnt vmcnt(8)
	s_waitcnt lgkmcnt(0)
	s_barrier
	s_setprio 1
	s_waitcnt lgkmcnt(0)
	v_mfma_f32_16x16x32_bf16 v[124:127], v[144:147], v[176:179], v[124:127]
	v_mfma_f32_16x16x32_bf16 v[120:123], v[152:155], v[176:179], v[120:123]
	v_mfma_f32_16x16x32_bf16 v[116:119], v[144:147], v[184:187], v[116:119]
	v_mfma_f32_16x16x32_bf16 v[112:115], v[152:155], v[184:187], v[112:115]
	v_mfma_f32_16x16x32_bf16 v[108:111], v[144:147], v[192:195], v[108:111]
	v_mfma_f32_16x16x32_bf16 v[104:107], v[152:155], v[192:195], v[104:107]
	v_mfma_f32_16x16x32_bf16 v[100:103], v[144:147], v[200:203], v[100:103]
	v_mfma_f32_16x16x32_bf16 v[96:99], v[152:155], v[200:203], v[96:99]
	v_mfma_f32_16x16x32_bf16 v[124:127], v[148:151], v[180:183], v[124:127]
	v_mfma_f32_16x16x32_bf16 v[120:123], v[156:159], v[180:183], v[120:123]
	v_mfma_f32_16x16x32_bf16 v[116:119], v[148:151], v[188:191], v[116:119]
	v_mfma_f32_16x16x32_bf16 v[112:115], v[156:159], v[188:191], v[112:115]
	v_mfma_f32_16x16x32_bf16 v[108:111], v[148:151], v[196:199], v[108:111]
	v_mfma_f32_16x16x32_bf16 v[104:107], v[156:159], v[196:199], v[104:107]
	v_mfma_f32_16x16x32_bf16 v[100:103], v[148:151], v[204:207], v[100:103]
	v_mfma_f32_16x16x32_bf16 v[96:99], v[156:159], v[204:207], v[96:99]
	s_setprio 0
	s_setprio 1
	v_mfma_f32_16x16x32_bf16 v[92:95], v[160:163], v[176:179], v[92:95]
	v_mfma_f32_16x16x32_bf16 v[88:91], v[168:171], v[176:179], v[88:91]
	v_mfma_f32_16x16x32_bf16 v[84:87], v[160:163], v[184:187], v[84:87]
	v_mfma_f32_16x16x32_bf16 v[80:83], v[168:171], v[184:187], v[80:83]
	v_mfma_f32_16x16x32_bf16 v[76:79], v[160:163], v[192:195], v[76:79]
	v_mfma_f32_16x16x32_bf16 v[72:75], v[168:171], v[192:195], v[72:75]
	v_mfma_f32_16x16x32_bf16 v[68:71], v[160:163], v[200:203], v[68:71]
	v_mfma_f32_16x16x32_bf16 v[64:67], v[168:171], v[200:203], v[64:67]
	v_mfma_f32_16x16x32_bf16 v[92:95], v[164:167], v[180:183], v[92:95]
	v_mfma_f32_16x16x32_bf16 v[88:91], v[172:175], v[180:183], v[88:91]
	v_mfma_f32_16x16x32_bf16 v[84:87], v[164:167], v[188:191], v[84:87]
	v_mfma_f32_16x16x32_bf16 v[80:83], v[172:175], v[188:191], v[80:83]
	v_mfma_f32_16x16x32_bf16 v[76:79], v[164:167], v[196:199], v[76:79]
	v_mfma_f32_16x16x32_bf16 v[72:75], v[172:175], v[196:199], v[72:75]
	v_mfma_f32_16x16x32_bf16 v[68:71], v[164:167], v[204:207], v[68:71]
	v_mfma_f32_16x16x32_bf16 v[64:67], v[172:175], v[204:207], v[64:67]
	s_setprio 0
	s_barrier
	s_mov_b32 m0, s78
	s_add_u32 s30, s30, 0xb0080
	ds_read_b128 v[176:179], v141 offset:49152
	ds_read_b128 v[180:183], v141 offset:50176
	ds_read_b128 v[184:187], v141 offset:51200
	ds_read_b128 v[188:191], v141 offset:52224
	ds_read_b128 v[192:195], v141 offset:53248
	ds_read_b128 v[196:199], v141 offset:54272
	ds_read_b128 v[200:203], v141 offset:55296
	ds_read_b128 v[204:207], v141 offset:56320
	global_load_lds_dwordx4 v130, s[98:99]
	s_mov_b32 m0, s79
	s_addc_u32 s31, s31, 0
	global_load_lds_dwordx4 v134, s[98:99]
	s_mov_b32 m0, s80
	s_nop 0
	global_load_lds_dwordx4 v130, s[30:31]
	s_mov_b32 m0, s81
	s_nop 0
	global_load_lds_dwordx4 v134, s[30:31]
	s_mov_b32 m0, s68
	s_nop 0
	global_load_lds_dwordx4 v128, s[100:101]
	s_mov_b32 m0, s69
	s_nop 0
	global_load_lds_dwordx4 v132, s[100:101]
	s_waitcnt vmcnt(8)
	s_waitcnt lgkmcnt(0)
	s_barrier
	s_setprio 1
	s_waitcnt lgkmcnt(0)
	v_mfma_f32_16x16x32_bf16 v[60:63], v[144:147], v[176:179], v[60:63]
	v_mfma_f32_16x16x32_bf16 v[56:59], v[152:155], v[176:179], v[56:59]
	v_mfma_f32_16x16x32_bf16 v[52:55], v[144:147], v[184:187], v[52:55]
	v_mfma_f32_16x16x32_bf16 v[48:51], v[152:155], v[184:187], v[48:51]
	v_mfma_f32_16x16x32_bf16 v[44:47], v[144:147], v[192:195], v[44:47]
	v_mfma_f32_16x16x32_bf16 v[40:43], v[152:155], v[192:195], v[40:43]
	v_mfma_f32_16x16x32_bf16 v[36:39], v[144:147], v[200:203], v[36:39]
	v_mfma_f32_16x16x32_bf16 v[32:35], v[152:155], v[200:203], v[32:35]
	v_mfma_f32_16x16x32_bf16 v[60:63], v[148:151], v[180:183], v[60:63]
	v_mfma_f32_16x16x32_bf16 v[56:59], v[156:159], v[180:183], v[56:59]
	v_mfma_f32_16x16x32_bf16 v[52:55], v[148:151], v[188:191], v[52:55]
	v_mfma_f32_16x16x32_bf16 v[48:51], v[156:159], v[188:191], v[48:51]
	v_mfma_f32_16x16x32_bf16 v[44:47], v[148:151], v[196:199], v[44:47]
	v_mfma_f32_16x16x32_bf16 v[40:43], v[156:159], v[196:199], v[40:43]
	v_mfma_f32_16x16x32_bf16 v[36:39], v[148:151], v[204:207], v[36:39]
	v_mfma_f32_16x16x32_bf16 v[32:35], v[156:159], v[204:207], v[32:35]
	s_setprio 0
	s_setprio 1
	v_mfma_f32_16x16x32_bf16 v[28:31], v[160:163], v[176:179], v[28:31]
	v_mfma_f32_16x16x32_bf16 v[24:27], v[168:171], v[176:179], v[24:27]
	v_mfma_f32_16x16x32_bf16 v[20:23], v[160:163], v[184:187], v[20:23]
	v_mfma_f32_16x16x32_bf16 v[16:19], v[168:171], v[184:187], v[16:19]
	v_mfma_f32_16x16x32_bf16 v[12:15], v[160:163], v[192:195], v[12:15]
	v_mfma_f32_16x16x32_bf16 v[8:11], v[168:171], v[192:195], v[8:11]
	v_mfma_f32_16x16x32_bf16 v[4:7], v[160:163], v[200:203], v[4:7]
	v_mfma_f32_16x16x32_bf16 v[0:3], v[168:171], v[200:203], v[0:3]
	v_mfma_f32_16x16x32_bf16 v[28:31], v[164:167], v[180:183], v[28:31]
	v_mfma_f32_16x16x32_bf16 v[24:27], v[172:175], v[180:183], v[24:27]
	v_mfma_f32_16x16x32_bf16 v[20:23], v[164:167], v[188:191], v[20:23]
	v_mfma_f32_16x16x32_bf16 v[16:19], v[172:175], v[188:191], v[16:19]
	v_mfma_f32_16x16x32_bf16 v[12:15], v[164:167], v[196:199], v[12:15]
	v_mfma_f32_16x16x32_bf16 v[8:11], v[172:175], v[196:199], v[8:11]
	v_mfma_f32_16x16x32_bf16 v[4:7], v[164:167], v[204:207], v[4:7]
	v_mfma_f32_16x16x32_bf16 v[0:3], v[172:175], v[204:207], v[0:3]
	s_setprio 0
	s_barrier
	s_cmp_ge_u32 s26, s67
	s_mov_b32 s30, s26
	s_cbranch_scc0 .LBB0_1288
	s_cmpk_lt_u32 s61, 0x100
	s_cbranch_scc0 .LBB0_1291
	s_barrier

.LBB0_1302:
	ds_read_b128 v[150:153], v145
	ds_read_b128 v[154:157], v145 offset:1024
	ds_read_b128 v[158:161], v145 offset:2048
	ds_read_b128 v[162:165], v145 offset:3072
	ds_read_b128 v[166:169], v146
	ds_read_b128 v[170:173], v146 offset:1024
	ds_read_b128 v[174:177], v146 offset:2048
	ds_read_b128 v[178:181], v146 offset:3072
	s_add_u32 s30, s28, 0x100
	s_addc_u32 s31, s29, 0
	s_cmp_lg_u32 s52, 6
	s_cselect_b32 s40, s30, 0
	s_cselect_b32 s41, s31, 0
	s_add_u32 s42, s24, s40
	s_addc_u32 s43, s25, s41
	s_add_u32 s40, s22, s40
	s_addc_u32 s41, s23, s41
	s_mov_b32 m0, s53
	v_lshl_add_u64 v[216:217], v[136:137], 0, s[28:29]
	ds_read_b128 v[182:185], v147
	ds_read_b128 v[186:189], v147 offset:1024
	ds_read_b128 v[190:193], v147 offset:2048
	ds_read_b128 v[194:197], v147 offset:3072
	ds_read_b128 v[198:201], v147 offset:4096
	ds_read_b128 v[202:205], v147 offset:5120
	ds_read_b128 v[206:209], v147 offset:6144
	ds_read_b128 v[210:213], v147 offset:7168
	global_load_lds_dwordx4 v[216:217], off
	v_lshl_add_u64 v[216:217], v[138:139], 0, s[28:29]
	s_mov_b32 m0, s61
	s_nop 0
	global_load_lds_dwordx4 v[216:217], off
	s_waitcnt vmcnt(8)
	s_waitcnt lgkmcnt(0)
	s_barrier
	s_setprio 1
	s_waitcnt lgkmcnt(0)
	v_mfma_f32_16x16x32_bf16 v[124:127], v[150:153], v[182:185], v[124:127]
	v_mfma_f32_16x16x32_bf16 v[120:123], v[158:161], v[182:185], v[120:123]
	v_mfma_f32_16x16x32_bf16 v[108:111], v[150:153], v[190:193], v[108:111]
	v_mfma_f32_16x16x32_bf16 v[104:107], v[158:161], v[190:193], v[104:107]
	v_mfma_f32_16x16x32_bf16 v[92:95], v[150:153], v[198:201], v[92:95]
	v_mfma_f32_16x16x32_bf16 v[88:91], v[158:161], v[198:201], v[88:91]
	v_mfma_f32_16x16x32_bf16 v[76:79], v[150:153], v[206:209], v[76:79]
	v_mfma_f32_16x16x32_bf16 v[72:75], v[158:161], v[206:209], v[72:75]
	v_mfma_f32_16x16x32_bf16 v[124:127], v[154:157], v[186:189], v[124:127]
	v_mfma_f32_16x16x32_bf16 v[120:123], v[162:165], v[186:189], v[120:123]
	v_mfma_f32_16x16x32_bf16 v[108:111], v[154:157], v[194:197], v[108:111]
	v_mfma_f32_16x16x32_bf16 v[104:107], v[162:165], v[194:197], v[104:107]
	v_mfma_f32_16x16x32_bf16 v[92:95], v[154:157], v[202:205], v[92:95]
	v_mfma_f32_16x16x32_bf16 v[88:91], v[162:165], v[202:205], v[88:91]
	v_mfma_f32_16x16x32_bf16 v[76:79], v[154:157], v[210:213], v[76:79]
	v_mfma_f32_16x16x32_bf16 v[72:75], v[162:165], v[210:213], v[72:75]
	s_setprio 0
	s_setprio 1
	v_mfma_f32_16x16x32_bf16 v[116:119], v[166:169], v[182:185], v[116:119]
	v_mfma_f32_16x16x32_bf16 v[112:115], v[174:177], v[182:185], v[112:115]
	v_mfma_f32_16x16x32_bf16 v[100:103], v[166:169], v[190:193], v[100:103]
	v_mfma_f32_16x16x32_bf16 v[96:99], v[174:177], v[190:193], v[96:99]
	v_mfma_f32_16x16x32_bf16 v[84:87], v[166:169], v[198:201], v[84:87]
	v_mfma_f32_16x16x32_bf16 v[80:83], v[174:177], v[198:201], v[80:83]
	v_mfma_f32_16x16x32_bf16 v[68:71], v[166:169], v[206:209], v[68:71]
	v_mfma_f32_16x16x32_bf16 v[64:67], v[174:177], v[206:209], v[64:67]
	v_mfma_f32_16x16x32_bf16 v[116:119], v[170:173], v[186:189], v[116:119]
	v_mfma_f32_16x16x32_bf16 v[112:115], v[178:181], v[186:189], v[112:115]
	v_mfma_f32_16x16x32_bf16 v[100:103], v[170:173], v[194:197], v[100:103]
	v_mfma_f32_16x16x32_bf16 v[96:99], v[178:181], v[194:197], v[96:99]
	v_mfma_f32_16x16x32_bf16 v[84:87], v[170:173], v[202:205], v[84:87]
	v_mfma_f32_16x16x32_bf16 v[80:83], v[178:181], v[202:205], v[80:83]
	v_mfma_f32_16x16x32_bf16 v[68:71], v[170:173], v[210:213], v[68:71]
	v_mfma_f32_16x16x32_bf16 v[64:67], v[178:181], v[210:213], v[64:67]
	s_setprio 0
	s_barrier
	s_add_u32 s98, s40, 0x80
	s_addc_u32 s99, s41, 0
	s_add_u32 s100, s42, 0x80
	s_addc_u32 s101, s43, 0
	s_mov_b32 m0, s62
	s_add_u32 s28, s40, 0xb0000
	ds_read_b128 v[182:185], v147 offset:16384
	ds_read_b128 v[186:189], v147 offset:17408
	ds_read_b128 v[190:193], v147 offset:18432
	ds_read_b128 v[194:197], v147 offset:19456
	ds_read_b128 v[198:201], v147 offset:20480
	ds_read_b128 v[202:205], v147 offset:21504
	ds_read_b128 v[206:209], v147 offset:22528
	ds_read_b128 v[210:213], v147 offset:23552
	global_load_lds_dwordx4 v130, s[40:41]
	s_mov_b32 m0, s63
	s_addc_u32 s29, s41, 0
	global_load_lds_dwordx4 v134, s[40:41]
	s_mov_b32 m0, s64
	s_nop 0
	global_load_lds_dwordx4 v130, s[28:29]
	s_mov_b32 m0, s65
	s_nop 0
	global_load_lds_dwordx4 v134, s[28:29]
	s_mov_b32 m0, s57
	s_nop 0
	global_load_lds_dwordx4 v128, s[42:43]
	s_mov_b32 m0, s54
	s_nop 0
	global_load_lds_dwordx4 v132, s[42:43]
	s_waitcnt vmcnt(8)
	s_waitcnt lgkmcnt(0)
	s_barrier
	s_setprio 1
	s_waitcnt lgkmcnt(0)
	v_mfma_f32_16x16x32_bf16 v[60:63], v[150:153], v[182:185], v[60:63]
	v_mfma_f32_16x16x32_bf16 v[56:59], v[158:161], v[182:185], v[56:59]
	v_mfma_f32_16x16x32_bf16 v[44:47], v[150:153], v[190:193], v[44:47]
	v_mfma_f32_16x16x32_bf16 v[40:43], v[158:161], v[190:193], v[40:43]
	v_mfma_f32_16x16x32_bf16 v[36:39], v[150:153], v[198:201], v[36:39]
	v_mfma_f32_16x16x32_bf16 v[24:27], v[158:161], v[198:201], v[24:27]
	v_mfma_f32_16x16x32_bf16 v[16:19], v[150:153], v[206:209], v[16:19]
	v_mfma_f32_16x16x32_bf16 v[8:11], v[158:161], v[206:209], v[8:11]
	v_mfma_f32_16x16x32_bf16 v[60:63], v[154:157], v[186:189], v[60:63]
	v_mfma_f32_16x16x32_bf16 v[56:59], v[162:165], v[186:189], v[56:59]
	v_mfma_f32_16x16x32_bf16 v[44:47], v[154:157], v[194:197], v[44:47]
	v_mfma_f32_16x16x32_bf16 v[40:43], v[162:165], v[194:197], v[40:43]
	v_mfma_f32_16x16x32_bf16 v[36:39], v[154:157], v[202:205], v[36:39]
	v_mfma_f32_16x16x32_bf16 v[24:27], v[162:165], v[202:205], v[24:27]
	v_mfma_f32_16x16x32_bf16 v[16:19], v[154:157], v[210:213], v[16:19]
	v_mfma_f32_16x16x32_bf16 v[8:11], v[162:165], v[210:213], v[8:11]
	s_setprio 0
	s_setprio 1
	v_mfma_f32_16x16x32_bf16 v[52:55], v[166:169], v[182:185], v[52:55]
	v_mfma_f32_16x16x32_bf16 v[48:51], v[174:177], v[182:185], v[48:51]
	v_mfma_f32_16x16x32_bf16 v[32:35], v[166:169], v[190:193], v[32:35]
	v_mfma_f32_16x16x32_bf16 v[28:31], v[174:177], v[190:193], v[28:31]
	v_mfma_f32_16x16x32_bf16 v[20:23], v[166:169], v[198:201], v[20:23]
	v_mfma_f32_16x16x32_bf16 v[12:15], v[174:177], v[198:201], v[12:15]
	v_mfma_f32_16x16x32_bf16 v[4:7], v[166:169], v[206:209], v[4:7]
	v_mfma_f32_16x16x32_bf16 v[0:3], v[174:177], v[206:209], v[0:3]
	v_mfma_f32_16x16x32_bf16 v[52:55], v[170:173], v[186:189], v[52:55]
	v_mfma_f32_16x16x32_bf16 v[48:51], v[178:181], v[186:189], v[48:51]
	v_mfma_f32_16x16x32_bf16 v[32:35], v[170:173], v[194:197], v[32:35]
	v_mfma_f32_16x16x32_bf16 v[28:31], v[178:181], v[194:197], v[28:31]
	v_mfma_f32_16x16x32_bf16 v[20:23], v[170:173], v[202:205], v[20:23]
	v_mfma_f32_16x16x32_bf16 v[12:15], v[178:181], v[202:205], v[12:15]
	v_mfma_f32_16x16x32_bf16 v[4:7], v[170:173], v[210:213], v[4:7]
	v_mfma_f32_16x16x32_bf16 v[0:3], v[178:181], v[210:213], v[0:3]
	s_setprio 0
	s_barrier
	ds_read_b128 v[150:153], v148
	ds_read_b128 v[154:157], v148 offset:1024
	ds_read_b128 v[158:161], v148 offset:2048
	ds_read_b128 v[162:165], v148 offset:3072
	ds_read_b128 v[166:169], v149
	ds_read_b128 v[170:173], v149 offset:1024
	ds_read_b128 v[174:177], v149 offset:2048
	ds_read_b128 v[178:181], v149 offset:3072
	s_add_u32 s28, s42, 0xb0000
	s_addc_u32 s29, s43, 0
	s_mov_b32 m0, s55
	ds_read_b128 v[182:185], v147 offset:32768
	ds_read_b128 v[186:189], v147 offset:33792
	ds_read_b128 v[190:193], v147 offset:34816
	ds_read_b128 v[194:197], v147 offset:35840
	ds_read_b128 v[198:201], v147 offset:36864
	ds_read_b128 v[202:205], v147 offset:37888
	ds_read_b128 v[206:209], v147 offset:38912
	ds_read_b128 v[210:213], v147 offset:39936
	global_load_lds_dwordx4 v128, s[28:29]
	s_mov_b32 m0, s56
	s_nop 0
	global_load_lds_dwordx4 v132, s[28:29]
	s_waitcnt vmcnt(8)
	s_waitcnt lgkmcnt(0)
	s_barrier
	s_setprio 1
	s_waitcnt lgkmcnt(0)
	v_mfma_f32_16x16x32_bf16 v[124:127], v[150:153], v[182:185], v[124:127]
	v_mfma_f32_16x16x32_bf16 v[120:123], v[158:161], v[182:185], v[120:123]
	v_mfma_f32_16x16x32_bf16 v[108:111], v[150:153], v[190:193], v[108:111]
	v_mfma_f32_16x16x32_bf16 v[104:107], v[158:161], v[190:193], v[104:107]
	v_mfma_f32_16x16x32_bf16 v[92:95], v[150:153], v[198:201], v[92:95]
	v_mfma_f32_16x16x32_bf16 v[88:91], v[158:161], v[198:201], v[88:91]
	v_mfma_f32_16x16x32_bf16 v[76:79], v[150:153], v[206:209], v[76:79]
	v_mfma_f32_16x16x32_bf16 v[72:75], v[158:161], v[206:209], v[72:75]
	v_mfma_f32_16x16x32_bf16 v[124:127], v[154:157], v[186:189], v[124:127]
	v_mfma_f32_16x16x32_bf16 v[120:123], v[162:165], v[186:189], v[120:123]
	v_mfma_f32_16x16x32_bf16 v[108:111], v[154:157], v[194:197], v[108:111]
	v_mfma_f32_16x16x32_bf16 v[104:107], v[162:165], v[194:197], v[104:107]
	v_mfma_f32_16x16x32_bf16 v[92:95], v[154:157], v[202:205], v[92:95]
	v_mfma_f32_16x16x32_bf16 v[88:91], v[162:165], v[202:205], v[88:91]
	v_mfma_f32_16x16x32_bf16 v[76:79], v[154:157], v[210:213], v[76:79]
	v_mfma_f32_16x16x32_bf16 v[72:75], v[162:165], v[210:213], v[72:75]
	s_setprio 0
	s_setprio 1
	v_mfma_f32_16x16x32_bf16 v[116:119], v[166:169], v[182:185], v[116:119]
	v_mfma_f32_16x16x32_bf16 v[112:115], v[174:177], v[182:185], v[112:115]
	v_mfma_f32_16x16x32_bf16 v[100:103], v[166:169], v[190:193], v[100:103]
	v_mfma_f32_16x16x32_bf16 v[96:99], v[174:177], v[190:193], v[96:99]
	v_mfma_f32_16x16x32_bf16 v[84:87], v[166:169], v[198:201], v[84:87]
	v_mfma_f32_16x16x32_bf16 v[80:83], v[174:177], v[198:201], v[80:83]
	v_mfma_f32_16x16x32_bf16 v[68:71], v[166:169], v[206:209], v[68:71]
	v_mfma_f32_16x16x32_bf16 v[64:67], v[174:177], v[206:209], v[64:67]
	v_mfma_f32_16x16x32_bf16 v[116:119], v[170:173], v[186:189], v[116:119]
	v_mfma_f32_16x16x32_bf16 v[112:115], v[178:181], v[186:189], v[112:115]
	v_mfma_f32_16x16x32_bf16 v[100:103], v[170:173], v[194:197], v[100:103]
	v_mfma_f32_16x16x32_bf16 v[96:99], v[178:181], v[194:197], v[96:99]
	v_mfma_f32_16x16x32_bf16 v[84:87], v[170:173], v[202:205], v[84:87]
	v_mfma_f32_16x16x32_bf16 v[80:83], v[178:181], v[202:205], v[80:83]
	v_mfma_f32_16x16x32_bf16 v[68:71], v[170:173], v[210:213], v[68:71]
	v_mfma_f32_16x16x32_bf16 v[64:67], v[178:181], v[210:213], v[64:67]
	s_setprio 0
	s_barrier
	s_mov_b32 m0, s66
	s_add_u32 s28, s40, 0xb0080
	ds_read_b128 v[182:185], v147 offset:49152
	ds_read_b128 v[186:189], v147 offset:50176
	ds_read_b128 v[190:193], v147 offset:51200
	ds_read_b128 v[194:197], v147 offset:52224
	ds_read_b128 v[198:201], v147 offset:53248
	ds_read_b128 v[202:205], v147 offset:54272
	ds_read_b128 v[206:209], v147 offset:55296
	ds_read_b128 v[210:213], v147 offset:56320
	global_load_lds_dwordx4 v130, s[98:99]
	s_mov_b32 m0, s67
	s_addc_u32 s29, s41, 0
	global_load_lds_dwordx4 v134, s[98:99]
	s_mov_b32 m0, s68
	s_nop 0
	global_load_lds_dwordx4 v130, s[28:29]
	s_mov_b32 m0, s69
	s_nop 0
	global_load_lds_dwordx4 v134, s[28:29]
	s_mov_b32 m0, s58
	s_nop 0
	global_load_lds_dwordx4 v128, s[100:101]
	s_mov_b32 m0, s59
	s_nop 0
	global_load_lds_dwordx4 v132, s[100:101]
	s_waitcnt vmcnt(8)
	s_waitcnt lgkmcnt(0)
	s_barrier
	s_setprio 1
	s_waitcnt lgkmcnt(0)
	v_mfma_f32_16x16x32_bf16 v[60:63], v[150:153], v[182:185], v[60:63]
	v_mfma_f32_16x16x32_bf16 v[56:59], v[158:161], v[182:185], v[56:59]
	v_mfma_f32_16x16x32_bf16 v[44:47], v[150:153], v[190:193], v[44:47]
	v_mfma_f32_16x16x32_bf16 v[40:43], v[158:161], v[190:193], v[40:43]
	v_mfma_f32_16x16x32_bf16 v[36:39], v[150:153], v[198:201], v[36:39]
	v_mfma_f32_16x16x32_bf16 v[24:27], v[158:161], v[198:201], v[24:27]
	v_mfma_f32_16x16x32_bf16 v[16:19], v[150:153], v[206:209], v[16:19]
	v_mfma_f32_16x16x32_bf16 v[8:11], v[158:161], v[206:209], v[8:11]
	v_mfma_f32_16x16x32_bf16 v[60:63], v[154:157], v[186:189], v[60:63]
	v_mfma_f32_16x16x32_bf16 v[56:59], v[162:165], v[186:189], v[56:59]
	v_mfma_f32_16x16x32_bf16 v[44:47], v[154:157], v[194:197], v[44:47]
	v_mfma_f32_16x16x32_bf16 v[40:43], v[162:165], v[194:197], v[40:43]
	v_mfma_f32_16x16x32_bf16 v[36:39], v[154:157], v[202:205], v[36:39]
	v_mfma_f32_16x16x32_bf16 v[24:27], v[162:165], v[202:205], v[24:27]
	v_mfma_f32_16x16x32_bf16 v[16:19], v[154:157], v[210:213], v[16:19]
	v_mfma_f32_16x16x32_bf16 v[8:11], v[162:165], v[210:213], v[8:11]
	s_setprio 0
	s_setprio 1
	v_mfma_f32_16x16x32_bf16 v[52:55], v[166:169], v[182:185], v[52:55]
	v_mfma_f32_16x16x32_bf16 v[48:51], v[174:177], v[182:185], v[48:51]
	v_mfma_f32_16x16x32_bf16 v[32:35], v[166:169], v[190:193], v[32:35]
	v_mfma_f32_16x16x32_bf16 v[28:31], v[174:177], v[190:193], v[28:31]
	v_mfma_f32_16x16x32_bf16 v[20:23], v[166:169], v[198:201], v[20:23]
	v_mfma_f32_16x16x32_bf16 v[12:15], v[174:177], v[198:201], v[12:15]
	v_mfma_f32_16x16x32_bf16 v[4:7], v[166:169], v[206:209], v[4:7]
	v_mfma_f32_16x16x32_bf16 v[0:3], v[174:177], v[206:209], v[0:3]
	v_mfma_f32_16x16x32_bf16 v[52:55], v[170:173], v[186:189], v[52:55]
	v_mfma_f32_16x16x32_bf16 v[48:51], v[178:181], v[186:189], v[48:51]
	v_mfma_f32_16x16x32_bf16 v[32:35], v[170:173], v[194:197], v[32:35]
	v_mfma_f32_16x16x32_bf16 v[28:31], v[178:181], v[194:197], v[28:31]
	v_mfma_f32_16x16x32_bf16 v[20:23], v[170:173], v[202:205], v[20:23]
	v_mfma_f32_16x16x32_bf16 v[12:15], v[178:181], v[202:205], v[12:15]
	v_mfma_f32_16x16x32_bf16 v[4:7], v[170:173], v[210:213], v[4:7]
	v_mfma_f32_16x16x32_bf16 v[0:3], v[178:181], v[210:213], v[0:3]
	s_setprio 0
	s_barrier
	s_add_i32 s52, s52, 2
	s_cmp_gt_u32 s52, 7
	s_mov_b64 s[28:29], s[30:31]
	s_cbranch_scc0 .LBB0_1302
	s_cmpk_lt_u32 s60, 0x100
	s_cbranch_scc0 .LBB0_1305
	s_barrier

.LBB0_1361:
	ds_read_b128 v[142:145], v157
	ds_read_b128 v[146:149], v157 offset:1024
	ds_read_b128 v[150:153], v157 offset:2048
	ds_read_b128 v[160:163], v157 offset:3072
	ds_read_b128 v[164:167], v158
	ds_read_b128 v[168:171], v158 offset:1024
	ds_read_b128 v[172:175], v158 offset:2048
	ds_read_b128 v[176:179], v158 offset:3072
	s_add_u32 s16, s14, 0x100
	s_addc_u32 s17, s15, 0
	s_cmp_eq_u32 s51, 40
	s_cselect_b32 s21, s3, s17
	s_cselect_b32 s20, s2, s16
	s_cselect_b32 s19, s13, s50
	s_cselect_b32 s18, s12, s45
	s_add_i32 m0, s29, 0xc000
	ds_read_b128 v[180:183], v159
	ds_read_b128 v[184:187], v159 offset:1024
	ds_read_b128 v[188:191], v159 offset:2048
	ds_read_b128 v[192:195], v159 offset:3072
	ds_read_b128 v[196:199], v159 offset:4096
	ds_read_b128 v[200:203], v159 offset:5120
	ds_read_b128 v[204:207], v159 offset:6144
	ds_read_b128 v[208:211], v159 offset:7168
	global_load_lds_dwordx4 v136, s[14:15]
	s_add_i32 m0, s29, 0xe000
	s_nop 0
	global_load_lds_dwordx4 v138, s[14:15]
	s_waitcnt vmcnt(8)
	s_waitcnt lgkmcnt(0)
	s_barrier
	s_setprio 1
	s_waitcnt lgkmcnt(0)
	v_mfma_f32_16x16x32_bf16 v[124:127], v[142:145], v[180:183], v[124:127]
	v_mfma_f32_16x16x32_bf16 v[120:123], v[150:153], v[180:183], v[120:123]
	v_mfma_f32_16x16x32_bf16 v[108:111], v[142:145], v[188:191], v[108:111]
	v_mfma_f32_16x16x32_bf16 v[104:107], v[150:153], v[188:191], v[104:107]
	v_mfma_f32_16x16x32_bf16 v[92:95], v[142:145], v[196:199], v[92:95]
	v_mfma_f32_16x16x32_bf16 v[88:91], v[150:153], v[196:199], v[88:91]
	v_mfma_f32_16x16x32_bf16 v[80:83], v[142:145], v[204:207], v[80:83]
	v_mfma_f32_16x16x32_bf16 v[72:75], v[150:153], v[204:207], v[72:75]
	v_mfma_f32_16x16x32_bf16 v[124:127], v[146:149], v[184:187], v[124:127]
	v_mfma_f32_16x16x32_bf16 v[120:123], v[160:163], v[184:187], v[120:123]
	v_mfma_f32_16x16x32_bf16 v[108:111], v[146:149], v[192:195], v[108:111]
	v_mfma_f32_16x16x32_bf16 v[104:107], v[160:163], v[192:195], v[104:107]
	v_mfma_f32_16x16x32_bf16 v[92:95], v[146:149], v[200:203], v[92:95]
	v_mfma_f32_16x16x32_bf16 v[88:91], v[160:163], v[200:203], v[88:91]
	v_mfma_f32_16x16x32_bf16 v[80:83], v[146:149], v[208:211], v[80:83]
	v_mfma_f32_16x16x32_bf16 v[72:75], v[160:163], v[208:211], v[72:75]
	s_setprio 0
	s_setprio 1
	v_mfma_f32_16x16x32_bf16 v[116:119], v[164:167], v[180:183], v[116:119]
	v_mfma_f32_16x16x32_bf16 v[112:115], v[172:175], v[180:183], v[112:115]
	v_mfma_f32_16x16x32_bf16 v[100:103], v[164:167], v[188:191], v[100:103]
	v_mfma_f32_16x16x32_bf16 v[96:99], v[172:175], v[188:191], v[96:99]
	v_mfma_f32_16x16x32_bf16 v[84:87], v[164:167], v[196:199], v[84:87]
	v_mfma_f32_16x16x32_bf16 v[76:79], v[172:175], v[196:199], v[76:79]
	v_mfma_f32_16x16x32_bf16 v[68:71], v[164:167], v[204:207], v[68:71]
	v_mfma_f32_16x16x32_bf16 v[64:67], v[172:175], v[204:207], v[64:67]
	v_mfma_f32_16x16x32_bf16 v[116:119], v[168:171], v[184:187], v[116:119]
	v_mfma_f32_16x16x32_bf16 v[112:115], v[176:179], v[184:187], v[112:115]
	v_mfma_f32_16x16x32_bf16 v[100:103], v[168:171], v[192:195], v[100:103]
	v_mfma_f32_16x16x32_bf16 v[96:99], v[176:179], v[192:195], v[96:99]
	v_mfma_f32_16x16x32_bf16 v[84:87], v[168:171], v[200:203], v[84:87]
	v_mfma_f32_16x16x32_bf16 v[76:79], v[176:179], v[200:203], v[76:79]
	v_mfma_f32_16x16x32_bf16 v[68:71], v[168:171], v[208:211], v[68:71]
	v_mfma_f32_16x16x32_bf16 v[64:67], v[176:179], v[208:211], v[64:67]
	s_setprio 0
	s_barrier
	s_add_u32 s98, s18, 0x80
	s_addc_u32 s99, s19, 0
	s_add_u32 s100, s20, 0x80
	s_addc_u32 s101, s21, 0
	s_add_i32 s14, s4, s27
	s_mov_b32 m0, s14
	ds_read_b128 v[180:183], v159 offset:16384
	ds_read_b128 v[184:187], v159 offset:17408
	ds_read_b128 v[188:191], v159 offset:18432
	ds_read_b128 v[192:195], v159 offset:19456
	ds_read_b128 v[196:199], v159 offset:20480
	ds_read_b128 v[200:203], v159 offset:21504
	ds_read_b128 v[204:207], v159 offset:22528
	ds_read_b128 v[208:211], v159 offset:23552
	global_load_lds_dwordx4 v132, s[18:19]
	s_add_i32 m0, s14, 0x2000
	s_add_u32 s14, s18, 0xb0000
	s_addc_u32 s15, s19, 0
	s_add_i32 s52, s40, s27
	global_load_lds_dwordx4 v128, s[18:19]
	s_mov_b32 m0, s52
	s_nop 0
	global_load_lds_dwordx4 v132, s[14:15]
	s_add_i32 m0, s52, 0x2000
	s_nop 0
	global_load_lds_dwordx4 v128, s[14:15]
	s_mov_b32 m0, s29
	s_nop 0
	global_load_lds_dwordx4 v134, s[20:21]
	s_mov_b32 m0, s30
	s_nop 0
	global_load_lds_dwordx4 v130, s[20:21]
	s_waitcnt vmcnt(8)
	s_waitcnt lgkmcnt(0)
	s_barrier
	s_setprio 1
	s_waitcnt lgkmcnt(0)
	v_mfma_f32_16x16x32_bf16 v[60:63], v[142:145], v[180:183], v[60:63]
	v_mfma_f32_16x16x32_bf16 v[56:59], v[150:153], v[180:183], v[56:59]
	v_mfma_f32_16x16x32_bf16 v[44:47], v[142:145], v[188:191], v[44:47]
	v_mfma_f32_16x16x32_bf16 v[40:43], v[150:153], v[188:191], v[40:43]
	v_mfma_f32_16x16x32_bf16 v[36:39], v[142:145], v[196:199], v[36:39]
	v_mfma_f32_16x16x32_bf16 v[24:27], v[150:153], v[196:199], v[24:27]
	v_mfma_f32_16x16x32_bf16 v[16:19], v[142:145], v[204:207], v[16:19]
	v_mfma_f32_16x16x32_bf16 v[8:11], v[150:153], v[204:207], v[8:11]
	v_mfma_f32_16x16x32_bf16 v[60:63], v[146:149], v[184:187], v[60:63]
	v_mfma_f32_16x16x32_bf16 v[56:59], v[160:163], v[184:187], v[56:59]
	v_mfma_f32_16x16x32_bf16 v[44:47], v[146:149], v[192:195], v[44:47]
	v_mfma_f32_16x16x32_bf16 v[40:43], v[160:163], v[192:195], v[40:43]
	v_mfma_f32_16x16x32_bf16 v[36:39], v[146:149], v[200:203], v[36:39]
	v_mfma_f32_16x16x32_bf16 v[24:27], v[160:163], v[200:203], v[24:27]
	v_mfma_f32_16x16x32_bf16 v[16:19], v[146:149], v[208:211], v[16:19]
	v_mfma_f32_16x16x32_bf16 v[8:11], v[160:163], v[208:211], v[8:11]
	s_setprio 0
	s_setprio 1
	v_mfma_f32_16x16x32_bf16 v[52:55], v[164:167], v[180:183], v[52:55]
	v_mfma_f32_16x16x32_bf16 v[48:51], v[172:175], v[180:183], v[48:51]
	v_mfma_f32_16x16x32_bf16 v[32:35], v[164:167], v[188:191], v[32:35]
	v_mfma_f32_16x16x32_bf16 v[28:31], v[172:175], v[188:191], v[28:31]
	v_mfma_f32_16x16x32_bf16 v[20:23], v[164:167], v[196:199], v[20:23]
	v_mfma_f32_16x16x32_bf16 v[12:15], v[172:175], v[196:199], v[12:15]
	v_mfma_f32_16x16x32_bf16 v[4:7], v[164:167], v[204:207], v[4:7]
	v_mfma_f32_16x16x32_bf16 v[0:3], v[172:175], v[204:207], v[0:3]
	v_mfma_f32_16x16x32_bf16 v[52:55], v[168:171], v[184:187], v[52:55]
	v_mfma_f32_16x16x32_bf16 v[48:51], v[176:179], v[184:187], v[48:51]
	v_mfma_f32_16x16x32_bf16 v[32:35], v[168:171], v[192:195], v[32:35]
	v_mfma_f32_16x16x32_bf16 v[28:31], v[176:179], v[192:195], v[28:31]
	v_mfma_f32_16x16x32_bf16 v[20:23], v[168:171], v[200:203], v[20:23]
	v_mfma_f32_16x16x32_bf16 v[12:15], v[176:179], v[200:203], v[12:15]
	v_mfma_f32_16x16x32_bf16 v[4:7], v[168:171], v[208:211], v[4:7]
	v_mfma_f32_16x16x32_bf16 v[0:3], v[176:179], v[208:211], v[0:3]
	s_setprio 0
	s_barrier
	s_add_i32 s52, 0, 0x18000
	s_add_i32 s53, 0, 0x1c000
	v_add_u32_e32 v160, s52, v155
	v_add_u32_e32 v176, s53, v155
	ds_read_b128 v[142:145], v160
	ds_read_b128 v[146:149], v160 offset:1024
	ds_read_b128 v[150:153], v160 offset:2048
	ds_read_b128 v[160:163], v160 offset:3072
	ds_read_b128 v[164:167], v176
	ds_read_b128 v[168:171], v176 offset:1024
	ds_read_b128 v[172:175], v176 offset:2048
	ds_read_b128 v[176:179], v176 offset:3072
	s_add_u32 s14, s20, 0xb0000
	s_addc_u32 s15, s21, 0
	s_mov_b32 m0, s31
	ds_read_b128 v[180:183], v159 offset:32768
	ds_read_b128 v[184:187], v159 offset:33792
	ds_read_b128 v[188:191], v159 offset:34816
	ds_read_b128 v[192:195], v159 offset:35840
	ds_read_b128 v[196:199], v159 offset:36864
	ds_read_b128 v[200:203], v159 offset:37888
	ds_read_b128 v[204:207], v159 offset:38912
	ds_read_b128 v[208:211], v159 offset:39936
	global_load_lds_dwordx4 v134, s[14:15]
	s_mov_b32 m0, s34
	s_nop 0
	global_load_lds_dwordx4 v130, s[14:15]
	s_waitcnt vmcnt(8)
	s_waitcnt lgkmcnt(0)
	s_barrier
	s_setprio 1
	s_waitcnt lgkmcnt(0)
	v_mfma_f32_16x16x32_bf16 v[124:127], v[142:145], v[180:183], v[124:127]
	v_mfma_f32_16x16x32_bf16 v[120:123], v[150:153], v[180:183], v[120:123]
	v_mfma_f32_16x16x32_bf16 v[108:111], v[142:145], v[188:191], v[108:111]
	v_mfma_f32_16x16x32_bf16 v[104:107], v[150:153], v[188:191], v[104:107]
	v_mfma_f32_16x16x32_bf16 v[92:95], v[142:145], v[196:199], v[92:95]
	v_mfma_f32_16x16x32_bf16 v[88:91], v[150:153], v[196:199], v[88:91]
	v_mfma_f32_16x16x32_bf16 v[80:83], v[142:145], v[204:207], v[80:83]
	v_mfma_f32_16x16x32_bf16 v[72:75], v[150:153], v[204:207], v[72:75]
	v_mfma_f32_16x16x32_bf16 v[124:127], v[146:149], v[184:187], v[124:127]
	v_mfma_f32_16x16x32_bf16 v[120:123], v[160:163], v[184:187], v[120:123]
	v_mfma_f32_16x16x32_bf16 v[108:111], v[146:149], v[192:195], v[108:111]
	v_mfma_f32_16x16x32_bf16 v[104:107], v[160:163], v[192:195], v[104:107]
	v_mfma_f32_16x16x32_bf16 v[92:95], v[146:149], v[200:203], v[92:95]
	v_mfma_f32_16x16x32_bf16 v[88:91], v[160:163], v[200:203], v[88:91]
	v_mfma_f32_16x16x32_bf16 v[80:83], v[146:149], v[208:211], v[80:83]
	v_mfma_f32_16x16x32_bf16 v[72:75], v[160:163], v[208:211], v[72:75]
	s_setprio 0
	s_setprio 1
	v_mfma_f32_16x16x32_bf16 v[116:119], v[164:167], v[180:183], v[116:119]
	v_mfma_f32_16x16x32_bf16 v[112:115], v[172:175], v[180:183], v[112:115]
	v_mfma_f32_16x16x32_bf16 v[100:103], v[164:167], v[188:191], v[100:103]
	v_mfma_f32_16x16x32_bf16 v[96:99], v[172:175], v[188:191], v[96:99]
	v_mfma_f32_16x16x32_bf16 v[84:87], v[164:167], v[196:199], v[84:87]
	v_mfma_f32_16x16x32_bf16 v[76:79], v[172:175], v[196:199], v[76:79]
	v_mfma_f32_16x16x32_bf16 v[68:71], v[164:167], v[204:207], v[68:71]
	v_mfma_f32_16x16x32_bf16 v[64:67], v[172:175], v[204:207], v[64:67]
	v_mfma_f32_16x16x32_bf16 v[116:119], v[168:171], v[184:187], v[116:119]
	v_mfma_f32_16x16x32_bf16 v[112:115], v[176:179], v[184:187], v[112:115]
	v_mfma_f32_16x16x32_bf16 v[100:103], v[168:171], v[192:195], v[100:103]
	v_mfma_f32_16x16x32_bf16 v[96:99], v[176:179], v[192:195], v[96:99]
	v_mfma_f32_16x16x32_bf16 v[84:87], v[168:171], v[200:203], v[84:87]
	v_mfma_f32_16x16x32_bf16 v[76:79], v[176:179], v[200:203], v[76:79]
	v_mfma_f32_16x16x32_bf16 v[68:71], v[168:171], v[208:211], v[68:71]
	v_mfma_f32_16x16x32_bf16 v[64:67], v[176:179], v[208:211], v[64:67]
	s_setprio 0
	s_barrier
	s_add_i32 s14, s52, s27
	s_mov_b32 m0, s14
	ds_read_b128 v[180:183], v159 offset:49152
	ds_read_b128 v[184:187], v159 offset:50176
	ds_read_b128 v[188:191], v159 offset:51200
	ds_read_b128 v[192:195], v159 offset:52224
	ds_read_b128 v[196:199], v159 offset:53248
	ds_read_b128 v[200:203], v159 offset:54272
	ds_read_b128 v[204:207], v159 offset:55296
	ds_read_b128 v[208:211], v159 offset:56320
	global_load_lds_dwordx4 v132, s[98:99]
	s_add_i32 m0, s14, 0x2000
	s_add_u32 s14, s18, 0xb0080
	s_addc_u32 s15, s19, 0
	s_add_i32 s18, s53, s27
	global_load_lds_dwordx4 v128, s[98:99]
	s_mov_b32 m0, s18
	s_nop 0
	global_load_lds_dwordx4 v132, s[14:15]
	s_add_i32 m0, s18, 0x2000
	s_nop 0
	global_load_lds_dwordx4 v128, s[14:15]
	s_mov_b32 m0, s38
	s_nop 0
	global_load_lds_dwordx4 v134, s[100:101]
	s_mov_b32 m0, s39
	s_nop 0
	global_load_lds_dwordx4 v130, s[100:101]
	s_waitcnt vmcnt(8)
	s_waitcnt lgkmcnt(0)
	s_barrier
	s_setprio 1
	s_waitcnt lgkmcnt(0)
	v_mfma_f32_16x16x32_bf16 v[60:63], v[142:145], v[180:183], v[60:63]
	v_mfma_f32_16x16x32_bf16 v[56:59], v[150:153], v[180:183], v[56:59]
	v_mfma_f32_16x16x32_bf16 v[44:47], v[142:145], v[188:191], v[44:47]
	v_mfma_f32_16x16x32_bf16 v[40:43], v[150:153], v[188:191], v[40:43]
	v_mfma_f32_16x16x32_bf16 v[36:39], v[142:145], v[196:199], v[36:39]
	v_mfma_f32_16x16x32_bf16 v[24:27], v[150:153], v[196:199], v[24:27]
	v_mfma_f32_16x16x32_bf16 v[16:19], v[142:145], v[204:207], v[16:19]
	v_mfma_f32_16x16x32_bf16 v[8:11], v[150:153], v[204:207], v[8:11]
	v_mfma_f32_16x16x32_bf16 v[60:63], v[146:149], v[184:187], v[60:63]
	v_mfma_f32_16x16x32_bf16 v[56:59], v[160:163], v[184:187], v[56:59]
	v_mfma_f32_16x16x32_bf16 v[44:47], v[146:149], v[192:195], v[44:47]
	v_mfma_f32_16x16x32_bf16 v[40:43], v[160:163], v[192:195], v[40:43]
	v_mfma_f32_16x16x32_bf16 v[36:39], v[146:149], v[200:203], v[36:39]
	v_mfma_f32_16x16x32_bf16 v[24:27], v[160:163], v[200:203], v[24:27]
	v_mfma_f32_16x16x32_bf16 v[16:19], v[146:149], v[208:211], v[16:19]
	v_mfma_f32_16x16x32_bf16 v[8:11], v[160:163], v[208:211], v[8:11]
	s_setprio 0
	s_setprio 1
	v_mfma_f32_16x16x32_bf16 v[52:55], v[164:167], v[180:183], v[52:55]
	v_mfma_f32_16x16x32_bf16 v[48:51], v[172:175], v[180:183], v[48:51]
	v_mfma_f32_16x16x32_bf16 v[32:35], v[164:167], v[188:191], v[32:35]
	v_mfma_f32_16x16x32_bf16 v[28:31], v[172:175], v[188:191], v[28:31]
	v_mfma_f32_16x16x32_bf16 v[20:23], v[164:167], v[196:199], v[20:23]
	v_mfma_f32_16x16x32_bf16 v[12:15], v[172:175], v[196:199], v[12:15]
	v_mfma_f32_16x16x32_bf16 v[4:7], v[164:167], v[204:207], v[4:7]
	v_mfma_f32_16x16x32_bf16 v[0:3], v[172:175], v[204:207], v[0:3]
	v_mfma_f32_16x16x32_bf16 v[52:55], v[168:171], v[184:187], v[52:55]
	v_mfma_f32_16x16x32_bf16 v[48:51], v[176:179], v[184:187], v[48:51]
	v_mfma_f32_16x16x32_bf16 v[32:35], v[168:171], v[192:195], v[32:35]
	v_mfma_f32_16x16x32_bf16 v[28:31], v[176:179], v[192:195], v[28:31]
	v_mfma_f32_16x16x32_bf16 v[20:23], v[168:171], v[200:203], v[20:23]
	v_mfma_f32_16x16x32_bf16 v[12:15], v[176:179], v[200:203], v[12:15]
	v_mfma_f32_16x16x32_bf16 v[4:7], v[168:171], v[208:211], v[4:7]
	v_mfma_f32_16x16x32_bf16 v[0:3], v[176:179], v[208:211], v[0:3]
	s_setprio 0
	s_barrier
	s_add_i32 s51, s51, 2
	s_add_u32 s45, s45, 0x100
	s_addc_u32 s50, s50, 0
	s_cmp_gt_u32 s51, 41
	s_mov_b64 s[14:15], s[16:17]
	s_cbranch_scc0 .LBB0_1361
	s_and_b64 vcc, exec, s[10:11]
	s_cbranch_vccz .LBB0_1364
	s_barrier

	.amdhsa_kernel _Z8yoco_fwd4Args
		.amdhsa_group_segment_fixed_size 0
		.amdhsa_private_segment_fixed_size 0
		.amdhsa_kernarg_size 496
		.amdhsa_user_sgpr_count 2
		.amdhsa_user_sgpr_dispatch_ptr 0
		.amdhsa_user_sgpr_queue_ptr 0
		.amdhsa_user_sgpr_kernarg_segment_ptr 1
		.amdhsa_user_sgpr_dispatch_id 0
		.amdhsa_user_sgpr_kernarg_preload_length 0
		.amdhsa_user_sgpr_kernarg_preload_offset 0
		.amdhsa_user_sgpr_private_segment_size 0
		.amdhsa_uses_dynamic_stack 0
		.amdhsa_enable_private_segment 0
		.amdhsa_system_sgpr_workgroup_id_x 1
		.amdhsa_system_sgpr_workgroup_id_y 0
		.amdhsa_system_sgpr_workgroup_id_z 0
		.amdhsa_system_sgpr_workgroup_info 0
		.amdhsa_system_vgpr_workitem_id 2
		.amdhsa_next_free_vgpr 251
		.amdhsa_next_free_sgpr 102
		.amdhsa_accum_offset 252
		.amdhsa_reserve_vcc 1
		.amdhsa_float_round_mode_32 0
		.amdhsa_float_round_mode_16_64 0
		.amdhsa_float_denorm_mode_32 3
		.amdhsa_float_denorm_mode_16_64 3
		.amdhsa_dx10_clamp 1
		.amdhsa_ieee_mode 1
		.amdhsa_fp16_overflow 0
		.amdhsa_tg_split 0
		.amdhsa_exception_fp_ieee_invalid_op 0
		.amdhsa_exception_fp_denorm_src 0
		.amdhsa_exception_fp_ieee_div_zero 0
		.amdhsa_exception_fp_ieee_overflow 0
		.amdhsa_exception_fp_ieee_underflow 0
		.amdhsa_exception_fp_ieee_inexact 0
		.amdhsa_exception_int_div_zero 0
	.end_amdhsa_kernel

amdhsa.kernels:
  - .agpr_count:     0
    .args:
      - .offset:         0
        .size:           240
        .value_kind:     by_value
      - .offset:         240
        .size:           4
        .value_kind:     hidden_block_count_x
      - .offset:         244
        .size:           4
        .value_kind:     hidden_block_count_y
      - .offset:         248
        .size:           4
        .value_kind:     hidden_block_count_z
      - .offset:         252
        .size:           2
        .value_kind:     hidden_group_size_x
      - .offset:         254
        .size:           2
        .value_kind:     hidden_group_size_y
      - .offset:         256
        .size:           2
        .value_kind:     hidden_group_size_z
      - .offset:         258
        .size:           2
        .value_kind:     hidden_remainder_x
      - .offset:         260
        .size:           2
        .value_kind:     hidden_remainder_y
      - .offset:         262
        .size:           2
        .value_kind:     hidden_remainder_z
      - .offset:         280
        .size:           8
        .value_kind:     hidden_global_offset_x
      - .offset:         288
        .size:           8
        .value_kind:     hidden_global_offset_y
      - .offset:         296
        .size:           8
        .value_kind:     hidden_global_offset_z
      - .offset:         304
        .size:           2
        .value_kind:     hidden_grid_dims
      - .offset:         328
        .size:           8
        .value_kind:     hidden_multigrid_sync_arg
      - .offset:         360
        .size:           4
        .value_kind:     hidden_dynamic_lds_size
    .group_segment_fixed_size: 0
    .kernarg_segment_align: 8
    .kernarg_segment_size: 496
    .language:       OpenCL C
    .language_version:
      - 2
      - 0
    .max_flat_workgroup_size: 512
    .name:           _Z8yoco_fwd4Args
    .private_segment_fixed_size: 0
    .sgpr_count:     108
    .sgpr_spill_count: 7
    .symbol:         _Z8yoco_fwd4Args.kd
    .uniform_work_group_size: 1
    .uses_dynamic_stack: false
    .vgpr_count:     251
    .vgpr_spill_count: 0
    .wavefront_size: 64
